# V image in LDS stores key-row bits 2/3 swapped so P needs no permlane32_swap before P.V (8 swaps per P tile dropped)
# baseline (speedup 1.0000x reference)
; #define SLOAD(i, k0) do { sv0[i] = *reinterpret_cast<const bf16x8*>(&Vh[(size_t)((k0) + sr) * ldv + sc]); sv1[i] = *reinterpret_cast<const bf16x8*>(&Vh[(size_t)((k0) + 32 + sr) * ldv + sc]); \
;     _Pragma("unroll") for (int _q = 0; _q < NKP; ++_q) sk[i][_q] = *reinterpret_cast<const bf16x8*>(&Kh[(size_t)(k0) * ldk + koff[_q]]); } while (0)
; #define SWRITE(b, i) do { *(bf16x8*)(V_lds + (b) * SHM_V + vst0) = sv0[i]; *(bf16x8*)(V_lds + (b) * SHM_V + vst1) = sv1[i]; \
;     _Pragma("unroll") for (int _q = 0; _q < NKP; ++_q) *(bf16x8*)(K_lds + (b) * SHM_K + klds[_q]) = sk[i][_q]; } while (0)
; #define SWRITE(b) do { *(bf16x8*)(V_lds + (b) * SHM_V + vst0) = sv0; *(bf16x8*)(V_lds + (b) * SHM_V + vst1) = sv1; \
;     _Pragma("unroll") for (int _q = 0; _q < NKP; ++_q) *(bf16x8*)(K_lds + (b) * SHM_K + klds[_q]) = sk[_q]; } while (0)
; __device__ __forceinline__ int v_st(int k, int c) { const int kk = (k & ~0xC) | ((k & 4) << 1) | ((k & 8) >> 1); return ((kk >> 3) * 4 + (c >> 5)) * 512 + ((kk & 7) * 32 + (c & 31)) * 2; }
; __device__ __forceinline__ int v_rd_base(int lane) { return ((lane & 3) << 3) | (((lane >> 2) & 3) << 6) | (((lane >> 4) & 1) << 5) | (((lane >> 5) & 1) << 8); }
; template <int DQK, int SDEPTH, int QL, bool NOMAX, int ldq, int ldk, int ldv, int ldo> ...
;     ...
;     const bf16_t* Qw = Qb + (size_t)(wid * QBLK + r32) * ldq + hi * 8;
; #pragma unroll
;     for (int d0 = 0; d0 < NQR; ++d0) qr[d0] = *reinterpret_cast<const bf16x8*>(Qw + d0 * 16);
; #pragma unroll
;     for (int d0 = 0; d0 < QL; ++d0) *(bf16x8*)(qpark + d0 * 1024) = *reinterpret_cast<const bf16x8*>(Qw + (NQR + d0) * 16);
;     const int sr = tid >> 4, sc = (tid & 15) * 8, vst0 = v_st(sr, sc), vst1 = v_st(32 + sr, sc);
;     int koff[NKP], klds[NKP];
; #pragma unroll
;     for (int i = 0; i < NKP; ++i) { const int row = tid >> 3, c8 = (tid & 7) + 8 * i; koff[i] = row * ldk + c8 * 8; klds[i] = row * RS + c8 * 16; }
;     const int vb0 = (int)(uintptr_t)V_lds + v_rd_base(lane);
;     bf16x8 sv0[SDEPTH], sv1[SDEPTH], sk[SDEPTH][NKP];
;     ...
;     f32x16 pA0, pA1, pB0, pB1; float mnA, mnB, alA, alB; bf16x8 pa0, pa1, pa2, pa3; const int NT = seq / KVBLK;
;     if (ATT_PRIO && wid >= 4) __builtin_amdgcn_s_setprio(1);
;     constexpr int SE = 0, SO = SDEPTH - 1;
;     SLOAD(SE, 0); asm volatile("s_waitcnt vmcnt(0)" ::: "memory"); SWRITE(0, SE); __syncthreads();
.LBB0_1467:
	v_add_u32_e32 v0, s48, v190
	v_ashrrev_i32_e32 v28, 4, v0
	v_lshlrev_b32_e32 v34, 3, v190
	v_ashrrev_i32_e32 v35, 3, v0
	v_and_b32_e32 v36, 7, v190
	v_ashrrev_i32_e32 v29, 31, v28
	v_and_b32_e32 v2, 0x78, v34
	v_add_u32_e32 v30, 32, v28
	v_lshlrev_b32_e32 v0, 9, v35
	v_or_b32_e32 v37, 8, v36
	v_lshlrev_b64 v[16:17], 10, v[28:29]
	v_lshl_or_b32 v8, v36, 3, v0
	v_lshl_or_b32 v10, v37, 3, v0
	v_lshl_add_u64 v[0:1], s[26:27], 0, v[16:17]
	v_lshlrev_b32_e32 v2, 1, v2
	v_mov_b32_e32 v3, v33
	v_ashrrev_i32_e32 v31, 31, v30
	v_lshl_add_u64 v[22:23], v[0:1], 0, v[2:3]
	v_lshlrev_b64 v[0:1], 10, v[30:31]
	v_ashrrev_i32_e32 v9, 31, v8
	v_lshl_add_u64 v[0:1], s[26:27], 0, v[0:1]
	v_lshlrev_b64 v[18:19], 1, v[8:9]
	v_ashrrev_i32_e32 v11, 31, v10
	v_lshl_add_u64 v[4:5], v[0:1], 0, v[2:3]
	v_lshl_add_u64 v[26:27], s[24:25], 0, v[18:19]
	v_lshlrev_b64 v[20:21], 1, v[10:11]
	global_load_dwordx4 v[0:3], v[22:23], off
	s_nop 0
	global_load_dwordx4 v[4:7], v[4:5], off
	v_lshl_add_u64 v[24:25], s[24:25], 0, v[20:21]
	global_load_dwordx4 v[8:11], v[26:27], off
	global_load_dwordx4 v[12:15], v[24:25], off
	s_movk_i32 s6, 0x110
	v_mad_u32_u24 v31, v192, s6, 0
	v_add_u32_e32 v196, v31, v32
	v_and_b32_e32 v31, 0xfffff0, v28
	v_and_or_b32 v31, v28, 8, v31
	v_and_b32_e32 v32, 0xfffff0, v30
	v_bfe_u32 v34, v34, 5, 2
	v_mov_b32_e32 v38, v28
	v_and_b32_e32 v28, 3, v28
	v_lshrrev_b32_e32 v31, 1, v31
	v_and_or_b32 v30, v30, 8, v32
	v_lshlrev_b32_e32 v29, 4, v190
	v_and_or_b32 v28, v38, 4, v28
	v_or_b32_e32 v31, v31, v34
	v_lshrrev_b32_e32 v30, 1, v30
	v_and_b32_e32 v29, 48, v29
	v_lshlrev_b32_e32 v28, 6, v28
	v_lshlrev_b32_e32 v31, 9, v31
	v_or_b32_e32 v30, v30, v34
	v_mul_lo_u32 v35, v35, s6
	v_lshlrev_b32_e32 v30, 9, v30
	v_or3_b32 v31, v31, v28, v29
	v_lshl_add_u32 v36, v36, 4, v35
	v_lshl_add_u32 v35, v37, 4, v35
	v_or3_b32 v28, v30, v28, v29
	v_add_u32_e32 v199, 0, v31
	v_add_u32_e32 v197, 0, v36
	v_add_u32_e32 v198, 0, v35
	s_waitcnt vmcnt(0)
	v_add_u32_e32 v200, 0, v28
	s_mov_b32 s7, 0x10000
	v_add_co_u32_e32 v42, vcc, s7, v22
	s_mov_b32 s6, 0x18000
	s_nop 0
	v_addc_co_u32_e32 v43, vcc, 0, v23, vcc
	v_add_co_u32_e32 v46, vcc, s6, v22
	v_and_b32_e32 v32, 63, v190
	s_nop 0
	v_addc_co_u32_e32 v47, vcc, 0, v23, vcc
	v_add_co_u32_e32 v50, vcc, s7, v26
	v_lshlrev_b32_e32 v55, 4, v32
	s_nop 0
	v_addc_co_u32_e32 v51, vcc, 0, v27, vcc
	v_add_co_u32_e32 v52, vcc, s7, v24
	v_lshlrev_b32_e32 v54, 3, v32
	s_nop 0
	v_addc_co_u32_e32 v53, vcc, 0, v25, vcc
	v_lshlrev_b32_e32 v56, 1, v32
	v_and_b32_e32 v58, 32, v56
	v_and_b32_e32 v59, 0x100, v54
	s_mov_b32 s7, 0x28000
	s_cmp_lg_u32 0, -1
	s_cselect_b32 s6, 0, 0
	s_waitcnt vmcnt(3)
	ds_write_b128 v199, v[0:3]
	s_waitcnt vmcnt(2)
	ds_write_b128 v200, v[4:7]
	s_waitcnt vmcnt(1)
	ds_write_b128 v197, v[8:11] offset:32768
	s_waitcnt vmcnt(0)
	ds_write_b128 v198, v[12:15] offset:32768
	s_waitcnt lgkmcnt(0)
	s_barrier
; #define SLOAD(i, k0) do { sv0[i] = *reinterpret_cast<const bf16x8*>(&Vh[(size_t)((k0) + sr) * ldv + sc]); sv1[i] = *reinterpret_cast<const bf16x8*>(&Vh[(size_t)((k0) + 32 + sr) * ldv + sc]); \
;     _Pragma("unroll") for (int _q = 0; _q < NKP; ++_q) sk[i][_q] = *reinterpret_cast<const bf16x8*>(&Kh[(size_t)(k0) * ldk + koff[_q]]); } while (0)
; #define SWRITE(b, i) do { *(bf16x8*)(V_lds + (b) * SHM_V + vst0) = sv0[i]; *(bf16x8*)(V_lds + (b) * SHM_V + vst1) = sv1[i]; \
;     _Pragma("unroll") for (int _q = 0; _q < NKP; ++_q) *(bf16x8*)(K_lds + (b) * SHM_K + klds[_q]) = sk[i][_q]; } while (0)
; #define SWAIT() do { if constexpr (SDEPTH == 2) { if constexpr (NKP == 1) asm volatile("s_waitcnt vmcnt(3)" ::: "memory"); else if constexpr (NKP == 2) asm volatile("s_waitcnt vmcnt(4)" ::: "memory"); else asm volatile("s_waitcnt vmcnt(5)" ::: "memory"); } \
;     else asm volatile("s_waitcnt vmcnt(0)" ::: "memory"); } while (0)
; #define SLOAD(k0) do { sv0 = *reinterpret_cast<const bf16x8*>(&Vh[(size_t)((k0) + sr) * ldv + sc]); sv1 = *reinterpret_cast<const bf16x8*>(&Vh[(size_t)((k0) + 32 + sr) * ldv + sc]); \
;     _Pragma("unroll") for (int _q = 0; _q < NKP; ++_q) sk[_q] = *reinterpret_cast<const bf16x8*>(&Kh[(size_t)(k0) * ldk + koff[_q]]); } while (0)
; #define SWRITE(b) do { *(bf16x8*)(V_lds + (b) * SHM_V + vst0) = sv0; *(bf16x8*)(V_lds + (b) * SHM_V + vst1) = sv1; \
;     _Pragma("unroll") for (int _q = 0; _q < NKP; ++_q) *(bf16x8*)(K_lds + (b) * SHM_K + klds[_q]) = sk[_q]; } while (0)
; template <int DQK, int SDEPTH, int QL, bool NOMAX, int ldq, int ldk, int ldv, int ldo> ...
;     ...
;     SLOAD(SE, 0); asm volatile("s_waitcnt vmcnt(0)" ::: "memory"); SWRITE(0, SE); __syncthreads();
;     qkt<DQK, QL>(pA0, pA1, K_lds, qr, qpark, r32, hi); if constexpr (NOMAX) { partialSM_nm(pA0); alA = 1.f; } else partialSM(pA0, pA1, m_reg, mnA, alA, C, thr_raw);
;     SLOAD(SO, KVBLK); if constexpr (SDEPTH == 2) { if (2 < NT) SLOAD(SE, 2 * KVBLK); }
;     SWAIT(); SWRITE(1, SO); __syncthreads();
	ds_read_b128 v[0:3], v196 offset:32768
	ds_read_b128 v[28:31], v196 offset:32800
	s_waitcnt lgkmcnt(1)
	v_mfma_f32_32x32x16_bf16 v[0:15], v[0:3], v[142:145], 0
	ds_read_b128 v[34:37], v196 offset:41472
	ds_read_b128 v[38:41], v196 offset:41504
	s_add_i32 s15, s53, -3
	s_lshl_b64 s[8:9], s[20:21], 10
	v_mov_b32_e32 v193, 0
	s_mov_b32 s14, 1
	v_mov_b32_e32 v61, v193
	v_mov_b32_e32 v62, v193
	s_waitcnt lgkmcnt(1)
	v_mfma_f32_32x32x16_bf16 v[66:81], v[34:37], v[142:145], 0
	v_mov_b32_e32 v63, v193
	v_mov_b32_e32 v64, v193
	v_mov_b32_e32 v65, v193
	v_mfma_f32_32x32x16_bf16 v[0:15], v[28:31], v[138:141], v[0:15]
	ds_read_b128 v[28:31], v196 offset:32832
	ds_read_b128 v[34:37], v196 offset:32864
	s_waitcnt lgkmcnt(2)
	v_mfma_f32_32x32x16_bf16 v[66:81], v[38:41], v[138:141], v[66:81]
	s_waitcnt lgkmcnt(1)
	v_mfma_f32_32x32x16_bf16 v[0:15], v[28:31], v[134:137], v[0:15]
	ds_read_b128 v[28:31], v196 offset:41536
	ds_read_b128 v[38:41], v196 offset:41568
	s_waitcnt lgkmcnt(1)
	v_mfma_f32_32x32x16_bf16 v[66:81], v[28:31], v[134:137], v[66:81]
	ds_read_b128 v[28:31], v196 offset:32896
	v_mfma_f32_32x32x16_bf16 v[0:15], v[34:37], v[130:133], v[0:15]
	s_waitcnt lgkmcnt(1)
	v_mfma_f32_32x32x16_bf16 v[66:81], v[38:41], v[130:133], v[66:81]
	ds_read_b128 v[34:37], v196 offset:41600
	ds_read_b128 v[38:41], v196 offset:32928
	s_waitcnt lgkmcnt(2)
	v_mfma_f32_32x32x16_bf16 v[0:15], v[28:31], v[126:129], v[0:15]
	ds_read_b128 v[28:31], v196 offset:41632
	global_load_dwordx4 v[42:45], v[42:43], off
	s_nop 0
	global_load_dwordx4 v[46:49], v[46:47], off
	s_waitcnt lgkmcnt(2)
	v_mfma_f32_32x32x16_bf16 v[66:81], v[34:37], v[126:129], v[66:81]
	global_load_dwordx4 v[34:37], v[50:51], off
	s_nop 0
	global_load_dwordx4 v[50:53], v[52:53], off
	s_waitcnt lgkmcnt(1)
	v_mfma_f32_32x32x16_bf16 v[0:15], v[38:41], v[122:125], v[0:15]
	ds_read_b128 v[38:41], v196 offset:32960
	s_waitcnt lgkmcnt(1)
	v_mfma_f32_32x32x16_bf16 v[66:81], v[28:31], v[122:125], v[66:81]
	v_and_b32_e32 v28, 0xc0, v55
	v_and_or_b32 v60, v54, 24, v28
	v_or3_b32 v60, v60, v58, v59
	v_add_co_u32_e32 v58, vcc, s66, v22
	ds_read_b128 v[28:31], v196 offset:41664
	ds_read_b128 v[54:57], v196 offset:32992
	v_addc_co_u32_e32 v59, vcc, 0, v23, vcc
	v_add_co_u32_e32 v22, vcc, s7, v22
	s_waitcnt lgkmcnt(2)
	v_mfma_f32_32x32x16_bf16 v[0:15], v[38:41], v[118:121], v[0:15]
	v_addc_co_u32_e32 v23, vcc, 0, v23, vcc
	v_add_co_u32_e32 v26, vcc, s66, v26
	ds_read_b128 v[38:41], v196 offset:41696
	s_nop 0
	v_addc_co_u32_e32 v27, vcc, 0, v27, vcc
	v_add_co_u32_e32 v24, vcc, s66, v24
	s_waitcnt lgkmcnt(2)
	v_mfma_f32_32x32x16_bf16 v[66:81], v[28:31], v[118:121], v[66:81]
	v_addc_co_u32_e32 v25, vcc, 0, v25, vcc
	global_load_dwordx4 v[146:149], v[58:59], off
	global_load_dwordx4 v[150:153], v[22:23], off
	global_load_dwordx4 v[154:157], v[26:27], off
	global_load_dwordx4 v[158:161], v[24:25], off
	v_add_u32_e32 v195, s6, v60
	s_addk_i32 s6, 0x4000
	v_add_u32_e32 v194, s6, v60
	s_lshl_b64 s[6:7], s[22:23], 8
	s_waitcnt lgkmcnt(1)
	v_mfma_f32_32x32x16_bf16 v[0:15], v[54:57], v[114:117], v[0:15]
	s_waitcnt vmcnt(4)
	s_waitcnt vmcnt(7)
	ds_write_b128 v199, v[42:45] offset:16384
	s_waitcnt vmcnt(6)
	ds_write_b128 v200, v[46:49] offset:16384
	s_waitcnt vmcnt(5)
	ds_write_b128 v197, v[34:37] offset:50176
	s_waitcnt vmcnt(4)
	ds_write_b128 v198, v[50:53] offset:50176
	s_waitcnt lgkmcnt(4)
	v_mfma_f32_32x32x16_bf16 v[66:81], v[38:41], v[114:117], v[66:81]
	s_nop 1
	v_exp_f32_e32 v206, v0
	v_exp_f32_e32 v209, v1
	v_exp_f32_e32 v204, v2
	v_exp_f32_e32 v207, v3
	v_exp_f32_e32 v203, v4
	v_exp_f32_e32 v205, v5
	v_exp_f32_e32 v208, v6
	v_exp_f32_e32 v216, v7
	v_exp_f32_e32 v189, v8
	v_exp_f32_e32 v202, v9
	v_exp_f32_e32 v187, v10
	v_exp_f32_e32 v201, v11
	v_exp_f32_e32 v184, v12
	v_exp_f32_e32 v188, v13
	v_exp_f32_e32 v185, v14
	v_exp_f32_e32 v186, v15
	v_lshl_add_u64 v[0:1], s[8:9], 0, v[16:17]
	v_and_b32_e32 v2, 15, v190
	s_add_u32 s8, s0, s8
	v_lshl_or_b32 v0, v2, 4, v0
	s_addc_u32 s9, s1, s9
	v_lshl_add_u64 v[178:179], s[0:1], 0, v[0:1]
	v_lshl_add_u64 v[180:181], s[8:9], 0, v[18:19]
	v_lshl_add_u64 v[182:183], s[8:9], 0, v[20:21]
	s_nop 0
	v_readfirstlane_b32 s98, v178
	v_readfirstlane_b32 s99, v179
	v_readfirstlane_b32 s100, v180
	v_readfirstlane_b32 s101, v181
	s_nop 1
	v_subrev_u32_e32 v240, s98, v178
	v_subrev_u32_e32 v242, s100, v180
	v_add_u32_e32 v241, 0x8000, v240
	s_add_u32 s98, s98, s6
	s_addc_u32 s99, s99, s7
	s_add_u32 s100, s100, s6
	s_addc_u32 s101, s101, s7
	s_add_u32 s98, s98, 0x3ca4c000
	s_addc_u32 s99, s99, 0
	s_add_u32 s100, s100, 0x398cc000
	s_addc_u32 s101, s101, 0
	v_mov_b32_e32 v50, 0
	v_mov_b32_e32 v51, v193
	v_mov_b32_e32 v52, v193
	v_mov_b32_e32 v53, v193
	v_mov_b32_e32 v54, v193
	v_mov_b32_e32 v55, v193
	v_mov_b32_e32 v56, v193
	v_mov_b32_e32 v57, v193
	v_mov_b32_e32 v58, v193
	v_mov_b32_e32 v59, v193
	v_mov_b32_e32 v60, v193
	v_mov_b32_e32 v34, 0
	v_mov_b32_e32 v35, v193
	v_mov_b32_e32 v36, v193
	v_mov_b32_e32 v37, v193
	v_mov_b32_e32 v38, v193
	v_mov_b32_e32 v39, v193
	v_mov_b32_e32 v40, v193
	v_mov_b32_e32 v41, v193
	v_mov_b32_e32 v42, v193
	v_mov_b32_e32 v43, v193
	v_mov_b32_e32 v44, v193
	v_mov_b32_e32 v45, v193
	v_mov_b32_e32 v46, v193
	v_mov_b32_e32 v47, v193
	v_mov_b32_e32 v48, v193
	v_mov_b32_e32 v49, v193
	v_mov_b32_e32 v16, 0
	v_mov_b32_e32 v17, v193
	v_mov_b32_e32 v18, v193
	v_mov_b32_e32 v19, v193
	v_mov_b32_e32 v20, v193
	v_mov_b32_e32 v21, v193
	v_mov_b32_e32 v22, v193
	v_mov_b32_e32 v23, v193
	v_mov_b32_e32 v24, v193
	v_mov_b32_e32 v25, v193
	v_mov_b32_e32 v26, v193
	v_mov_b32_e32 v27, v193
	v_mov_b32_e32 v28, v193
	v_mov_b32_e32 v29, v193
	v_mov_b32_e32 v30, v193
	v_mov_b32_e32 v31, v193
	v_mov_b32_e32 v0, 0
	v_mov_b32_e32 v1, v193
	v_mov_b32_e32 v2, v193
	v_mov_b32_e32 v3, v193
	v_mov_b32_e32 v4, v193
	v_mov_b32_e32 v5, v193
	v_mov_b32_e32 v6, v193
	v_mov_b32_e32 v7, v193
	v_mov_b32_e32 v8, v193
	v_mov_b32_e32 v9, v193
	v_mov_b32_e32 v10, v193
	v_mov_b32_e32 v11, v193
	v_mov_b32_e32 v12, v193
	v_mov_b32_e32 v13, v193
	v_mov_b32_e32 v14, v193
	v_mov_b32_e32 v15, v193
	s_waitcnt lgkmcnt(0)
	s_barrier
	s_branch .LBB0_1469

; #define SBAR() __builtin_amdgcn_sched_barrier(0)
; #define SLOAD(i, k0) do { sv0[i] = *reinterpret_cast<const bf16x8*>(&Vh[(size_t)((k0) + sr) * ldv + sc]); sv1[i] = *reinterpret_cast<const bf16x8*>(&Vh[(size_t)((k0) + 32 + sr) * ldv + sc]); \
;     _Pragma("unroll") for (int _q = 0; _q < NKP; ++_q) sk[i][_q] = *reinterpret_cast<const bf16x8*>(&Kh[(size_t)(k0) * ldk + koff[_q]]); } while (0)
; #define PVD0(...) do { if constexpr (PV_PIPE != 0) pv_d0_pipe(__VA_ARGS__); else pv_d0(__VA_ARGS__); } while (0)
; #define SLOAD(k0) do { sv0 = *reinterpret_cast<const bf16x8*>(&Vh[(size_t)((k0) + sr) * ldv + sc]); sv1 = *reinterpret_cast<const bf16x8*>(&Vh[(size_t)((k0) + 32 + sr) * ldv + sc]); \
;     _Pragma("unroll") for (int _q = 0; _q < NKP; ++_q) sk[_q] = *reinterpret_cast<const bf16x8*>(&Kh[(size_t)(k0) * ldk + koff[_q]]); } while (0)
; template <int DQK, int SDEPTH, int QL, bool NOMAX, int ldq, int ldk, int ldv, int ldo> ...
;     ...
;         SBAR(); qkt<DQK, QL>(pB0, pB1, K_lds + SHM_K, qr, qpark, r32, hi);
;         finishSM(pA0, pA1, alA, l_reg, pa0, pa1, pa2, pa3); SBAR();
;         SLOAD(SO, (j + SDEPTH) * KVBLK); SBAR();
;         PVD0(o, vb0, pa0, pa1, pa2, pa3); if constexpr (NOMAX) { partialSM_nm(pB0); alB = 1.f; } else partialSM(pB0, pB1, m_reg, mnB, alB, C, thr_raw);
.LBB0_1469:
	ds_read_b128 v[98:101], v196 offset:58880
	ds_read_b128 v[82:85], v196 offset:50176
	ds_read_b128 v[102:105], v196 offset:50208
	ds_read_b128 v[162:165], v196 offset:58912
	v_exp_f32_e32 v106, v70
	v_exp_f32_e32 v107, v71
	s_waitcnt lgkmcnt(2)
	v_mfma_f32_32x32x16_bf16 v[82:97], v[82:85], v[142:145], 0
	v_exp_f32_e32 v108, v72
	v_exp_f32_e32 v109, v73
	v_exp_f32_e32 v110, v74
	v_exp_f32_e32 v111, v75
	v_exp_f32_e32 v112, v76
	v_exp_f32_e32 v113, v77
	v_exp_f32_e32 v210, v78
	s_waitcnt lgkmcnt(1)
	v_mfma_f32_32x32x16_bf16 v[82:97], v[102:105], v[138:141], v[82:97]
	ds_read_b128 v[102:105], v196 offset:50240
	ds_read_b128 v[166:169], v196 offset:58944
	v_exp_f32_e32 v211, v79
	v_exp_f32_e32 v212, v80
	v_exp_f32_e32 v81, v81
	s_waitcnt lgkmcnt(1)
	v_mfma_f32_32x32x16_bf16 v[82:97], v[102:105], v[134:137], v[82:97]
	ds_read_b128 v[102:105], v196 offset:50272
	ds_read_b128 v[170:173], v196 offset:58976
	s_waitcnt lgkmcnt(1)
	v_mfma_f32_32x32x16_bf16 v[82:97], v[102:105], v[130:133], v[82:97]
	ds_read_b128 v[102:105], v196 offset:50304
	ds_read_b128 v[174:177], v196 offset:59008
	s_waitcnt lgkmcnt(1)
	v_mfma_f32_32x32x16_bf16 v[82:97], v[102:105], v[126:129], v[82:97]
	ds_read_b128 v[102:105], v196 offset:50336
	ds_read_b128 v[220:223], v196 offset:59040
	s_waitcnt lgkmcnt(1)
	v_mfma_f32_32x32x16_bf16 v[82:97], v[102:105], v[122:125], v[82:97]
	ds_read_b128 v[102:105], v196 offset:50368
	ds_read_b128 v[224:227], v196 offset:59072
	s_waitcnt lgkmcnt(1)
	v_mfma_f32_32x32x16_bf16 v[82:97], v[102:105], v[118:121], v[82:97]
	ds_read_b128 v[102:105], v196 offset:50400
	ds_read_b128 v[228:231], v196 offset:59104
	s_waitcnt lgkmcnt(1)
	v_mfma_f32_32x32x16_bf16 v[82:97], v[102:105], v[114:117], v[82:97]
	v_exp_f32_e32 v102, v66
	v_add_f32_e32 v66, 0, v206
	v_add_f32_e32 v66, v209, v66
	v_add_f32_e32 v66, v204, v66
	v_add_f32_e32 v66, v207, v66
	v_add_f32_e32 v66, v203, v66
	v_add_f32_e32 v66, v205, v66
	v_add_f32_e32 v66, v208, v66
	v_add_f32_e32 v66, v216, v66
	v_add_f32_e32 v66, v189, v66
	v_add_f32_e32 v66, v202, v66
	v_add_f32_e32 v66, v187, v66
	v_add_f32_e32 v66, v201, v66
	v_add_f32_e32 v66, v184, v66
	v_exp_f32_e32 v103, v67
	v_add_f32_e32 v66, v188, v66
	v_exp_f32_e32 v104, v68
	v_add_f32_e32 v66, v185, v66
	v_exp_f32_e32 v105, v69
	v_add_f32_e32 v66, v186, v66
	v_add_f32_e32 v66, v102, v66
	v_add_f32_e32 v66, v103, v66
	v_add_f32_e32 v66, v104, v66
	v_add_f32_e32 v66, v105, v66
	v_add_f32_e32 v66, v106, v66
	v_add_f32_e32 v66, v107, v66
	v_add_f32_e32 v66, v108, v66
	v_add_f32_e32 v66, v109, v66
	v_add_f32_e32 v66, v110, v66
	v_add_f32_e32 v66, v111, v66
	v_add_f32_e32 v66, v112, v66
	v_add_f32_e32 v66, v113, v66
	v_add_f32_e32 v66, v210, v66
	v_add_f32_e32 v66, v211, v66
	v_add_f32_e32 v66, v212, v66
	v_add_f32_e32 v217, v81, v66
	v_cvt_pk_bf16_f32 v66, v206, v209
	v_cvt_pk_bf16_f32 v67, v204, v207
	v_cvt_pk_bf16_f32 v68, v203, v205
	v_cvt_pk_bf16_f32 v69, v208, v216
	v_cvt_pk_bf16_f32 v70, v189, v202
	v_cvt_pk_bf16_f32 v71, v187, v201
	v_cvt_pk_bf16_f32 v72, v184, v188
	v_cvt_pk_bf16_f32 v73, v185, v186
	v_cvt_pk_bf16_f32 v74, v102, v103
	v_cvt_pk_bf16_f32 v75, v104, v105
	v_cvt_pk_bf16_f32 v76, v106, v107
	v_cvt_pk_bf16_f32 v77, v108, v109
	v_cvt_pk_bf16_f32 v78, v110, v111
	v_cvt_pk_bf16_f32 v79, v112, v113
	v_cvt_pk_bf16_f32 v80, v210, v211
	v_cvt_pk_bf16_f32 v81, v212, v81
	v_mfma_f32_32x32x16_bf16 v[98:113], v[98:101], v[142:145], 0
	v_mfma_f32_32x32x16_bf16 v[98:113], v[162:165], v[138:141], v[98:113]
	v_mfma_f32_32x32x16_bf16 v[98:113], v[166:169], v[134:137], v[98:113]
	global_load_dwordx4 v[162:165], v240, s[98:99] offset:256
	global_load_dwordx4 v[166:169], v241, s[98:99] offset:256
	v_mfma_f32_32x32x16_bf16 v[98:113], v[170:173], v[130:133], v[98:113]
	global_load_dwordx4 v[170:173], v242, s[100:101] offset:256
	v_mfma_f32_32x32x16_bf16 v[98:113], v[174:177], v[126:129], v[98:113]
	global_load_dwordx4 v[174:177], v242, s[100:101] offset:384
	s_add_u32 s98, s98, 0x10000
	s_addc_u32 s99, s99, 0
	s_add_u32 s100, s100, 0x10000
	s_addc_u32 s101, s101, 0
	v_mfma_f32_32x32x16_bf16 v[98:113], v[220:223], v[122:125], v[98:113]
	v_mfma_f32_32x32x16_bf16 v[98:113], v[224:227], v[118:121], v[98:113]
	s_waitcnt lgkmcnt(0)
	v_mfma_f32_32x32x16_bf16 v[98:113], v[228:231], v[114:117], v[98:113]
	ds_read_b64_tr_b16 v[202:203], v195 offset:0
	ds_read_b64_tr_b16 v[204:205], v195 offset:0x800
	ds_read_b64_tr_b16 v[206:207], v195 offset:0x1000
	ds_read_b64_tr_b16 v[208:209], v195 offset:0x1800
	ds_read_b64_tr_b16 v[220:221], v195 offset:0x2000
	ds_read_b64_tr_b16 v[222:223], v195 offset:0x2800
	ds_read_b64_tr_b16 v[224:225], v195 offset:0x3000
	ds_read_b64_tr_b16 v[226:227], v195 offset:0x3800
	s_waitcnt lgkmcnt(6)
	s_nop 0
	v_mfma_f32_32x32x16_bf16 v[50:65], v[66:69], v[202:205], v[50:65]
	ds_read_b64_tr_b16 v[202:203], v195 offset:0x200
	ds_read_b64_tr_b16 v[204:205], v195 offset:0xa00
	s_waitcnt lgkmcnt(6)
	v_mfma_f32_32x32x16_bf16 v[50:65], v[70:73], v[206:209], v[50:65]
	ds_read_b64_tr_b16 v[206:207], v195 offset:0x1200
	ds_read_b64_tr_b16 v[208:209], v195 offset:0x1a00
	s_waitcnt lgkmcnt(6)
	v_mfma_f32_32x32x16_bf16 v[50:65], v[74:77], v[220:223], v[50:65]
	ds_read_b64_tr_b16 v[220:221], v195 offset:0x2200
	ds_read_b64_tr_b16 v[222:223], v195 offset:0x2a00
	s_waitcnt lgkmcnt(6)
	v_mfma_f32_32x32x16_bf16 v[50:65], v[78:81], v[224:227], v[50:65]
	ds_read_b64_tr_b16 v[224:225], v195 offset:0x3200
	ds_read_b64_tr_b16 v[226:227], v195 offset:0x3a00
	s_waitcnt lgkmcnt(6)
	v_mfma_f32_32x32x16_bf16 v[34:49], v[66:69], v[202:205], v[34:49]
	ds_read_b64_tr_b16 v[202:203], v195 offset:0x400
	ds_read_b64_tr_b16 v[204:205], v195 offset:0xc00
	s_waitcnt lgkmcnt(6)
; #define SBAR() __builtin_amdgcn_sched_barrier(0)
; #define SLOAD(i, k0) do { sv0[i] = *reinterpret_cast<const bf16x8*>(&Vh[(size_t)((k0) + sr) * ldv + sc]); sv1[i] = *reinterpret_cast<const bf16x8*>(&Vh[(size_t)((k0) + 32 + sr) * ldv + sc]); \
;     _Pragma("unroll") for (int _q = 0; _q < NKP; ++_q) sk[i][_q] = *reinterpret_cast<const bf16x8*>(&Kh[(size_t)(k0) * ldk + koff[_q]]); } while (0)
; #define SWRITE(b, i) do { *(bf16x8*)(V_lds + (b) * SHM_V + vst0) = sv0[i]; *(bf16x8*)(V_lds + (b) * SHM_V + vst1) = sv1[i]; \
;     _Pragma("unroll") for (int _q = 0; _q < NKP; ++_q) *(bf16x8*)(K_lds + (b) * SHM_K + klds[_q]) = sk[i][_q]; } while (0)
; #define SWAIT() do { if constexpr (SDEPTH == 2) { if constexpr (NKP == 1) asm volatile("s_waitcnt vmcnt(3)" ::: "memory"); else if constexpr (NKP == 2) asm volatile("s_waitcnt vmcnt(4)" ::: "memory"); else asm volatile("s_waitcnt vmcnt(5)" ::: "memory"); } \
;     else asm volatile("s_waitcnt vmcnt(0)" ::: "memory"); } while (0)
; #define PVD0(...) do { if constexpr (PV_PIPE != 0) pv_d0_pipe(__VA_ARGS__); else pv_d0(__VA_ARGS__); } while (0)
; #define RESC(a) do { if constexpr (!NOMAX) if (__any((a) < 1.f)) { if (hi == 0) al_l[r32] = (a); asm volatile("s_waitcnt lgkmcnt(0)" ::: "memory"); \
;     _Pragma("unroll") for (int d = 0; d < 4; ++d) _Pragma("unroll") for (int r = 0; r < 16; ++r) o[d][r] *= al_l[crow(r, hi)]; } } while (0)
; #define SLOAD(k0) do { sv0 = *reinterpret_cast<const bf16x8*>(&Vh[(size_t)((k0) + sr) * ldv + sc]); sv1 = *reinterpret_cast<const bf16x8*>(&Vh[(size_t)((k0) + 32 + sr) * ldv + sc]); \
;     _Pragma("unroll") for (int _q = 0; _q < NKP; ++_q) sk[_q] = *reinterpret_cast<const bf16x8*>(&Kh[(size_t)(k0) * ldk + koff[_q]]); } while (0)
; template <int DQK, int SDEPTH, int QL, bool NOMAX, int ldq, int ldk, int ldv, int ldo> ...
;     ...
;         PVD0(o, vb0, pa0, pa1, pa2, pa3); if constexpr (NOMAX) { partialSM_nm(pB0); alB = 1.f; } else partialSM(pB0, pB1, m_reg, mnB, alB, C, thr_raw);
;         __syncthreads(); SWAIT(); SWRITE(0, SE);
;         RESC(alB); __syncthreads();
;         SBAR(); qkt<DQK, QL>(pA0, pA1, K_lds, qr, qpark, r32, hi);
;         finishSM(pB0, pB1, alB, l_reg, pa0, pa1, pa2, pa3); SBAR();
;         if (SDEPTH == 1 || j + 3 < NT) SLOAD(SE, (j + 1 + SDEPTH) * KVBLK); SBAR();
	v_mfma_f32_32x32x16_bf16 v[34:49], v[70:73], v[206:209], v[34:49]
	ds_read_b64_tr_b16 v[206:207], v195 offset:0x1400
	ds_read_b64_tr_b16 v[208:209], v195 offset:0x1c00
	s_waitcnt lgkmcnt(6)
	v_mfma_f32_32x32x16_bf16 v[34:49], v[74:77], v[220:223], v[34:49]
	ds_read_b64_tr_b16 v[220:221], v195 offset:0x2400
	ds_read_b64_tr_b16 v[222:223], v195 offset:0x2c00
	s_waitcnt lgkmcnt(6)
	v_mfma_f32_32x32x16_bf16 v[34:49], v[78:81], v[224:227], v[34:49]
	ds_read_b64_tr_b16 v[224:225], v195 offset:0x3400
	ds_read_b64_tr_b16 v[226:227], v195 offset:0x3c00
	s_waitcnt lgkmcnt(6)
	v_mfma_f32_32x32x16_bf16 v[16:31], v[66:69], v[202:205], v[16:31]
	ds_read_b64_tr_b16 v[202:203], v195 offset:0x600
	ds_read_b64_tr_b16 v[204:205], v195 offset:0xe00
	s_waitcnt lgkmcnt(6)
	v_mfma_f32_32x32x16_bf16 v[16:31], v[70:73], v[206:209], v[16:31]
	ds_read_b64_tr_b16 v[206:207], v195 offset:0x1600
	ds_read_b64_tr_b16 v[208:209], v195 offset:0x1e00
	s_waitcnt lgkmcnt(6)
	v_mfma_f32_32x32x16_bf16 v[16:31], v[74:77], v[220:223], v[16:31]
	ds_read_b64_tr_b16 v[220:221], v195 offset:0x2600
	ds_read_b64_tr_b16 v[222:223], v195 offset:0x2e00
	s_waitcnt lgkmcnt(6)
	v_mfma_f32_32x32x16_bf16 v[16:31], v[78:81], v[224:227], v[16:31]
	ds_read_b64_tr_b16 v[224:225], v195 offset:0x3600
	ds_read_b64_tr_b16 v[226:227], v195 offset:0x3e00
	s_waitcnt lgkmcnt(0)
	v_mfma_f32_32x32x16_bf16 v[0:15], v[66:69], v[202:205], v[0:15]
	s_barrier
	s_waitcnt vmcnt(4)
	s_waitcnt vmcnt(7)
	ds_write_b128 v199, v[146:149]
	s_waitcnt vmcnt(6)
	ds_write_b128 v200, v[150:153]
	s_waitcnt vmcnt(5)
	ds_write_b128 v197, v[154:157] offset:32768
	s_waitcnt vmcnt(4)
	ds_write_b128 v198, v[158:161] offset:32768
	v_exp_f32_e32 v210, v82
	v_mfma_f32_32x32x16_bf16 v[0:15], v[70:73], v[206:209], v[0:15]
	v_exp_f32_e32 v211, v83
	v_exp_f32_e32 v212, v84
	v_exp_f32_e32 v213, v85
	v_exp_f32_e32 v214, v86
	v_exp_f32_e32 v215, v87
	v_exp_f32_e32 v216, v88
	v_exp_f32_e32 v219, v89
	v_mfma_f32_32x32x16_bf16 v[0:15], v[74:77], v[220:223], v[0:15]
	v_exp_f32_e32 v228, v90
	v_exp_f32_e32 v229, v91
	v_exp_f32_e32 v230, v92
	v_exp_f32_e32 v220, v93
	v_exp_f32_e32 v221, v94
	v_exp_f32_e32 v222, v95
	v_exp_f32_e32 v223, v96
	v_mfma_f32_32x32x16_bf16 v[0:15], v[78:81], v[224:227], v[0:15]
	v_exp_f32_e32 v231, v97
	s_waitcnt lgkmcnt(0)
	s_barrier
	ds_read_b128 v[66:69], v196 offset:41472
	ds_read_b128 v[70:73], v196 offset:32768
	ds_read_b128 v[202:205], v196 offset:32800
	ds_read_b128 v[206:209], v196 offset:41504
	v_exp_f32_e32 v224, v105
	v_exp_f32_e32 v225, v106
	s_waitcnt lgkmcnt(2)
	v_mfma_f32_32x32x16_bf16 v[82:97], v[70:73], v[142:145], 0
	v_exp_f32_e32 v226, v107
	v_exp_f32_e32 v227, v108
	v_exp_f32_e32 v232, v109
	v_exp_f32_e32 v233, v110
	v_exp_f32_e32 v236, v111
	v_exp_f32_e32 v237, v112
	v_exp_f32_e32 v113, v113
	v_mfma_f32_32x32x16_bf16 v[66:81], v[66:69], v[142:145], 0
	s_waitcnt lgkmcnt(1)
	v_mfma_f32_32x32x16_bf16 v[82:97], v[202:205], v[138:141], v[82:97]
	s_waitcnt lgkmcnt(0)
	v_mfma_f32_32x32x16_bf16 v[66:81], v[206:209], v[138:141], v[66:81]
	ds_read_b128 v[202:205], v196 offset:32832
	ds_read_b128 v[206:209], v196 offset:41536
	s_waitcnt lgkmcnt(1)
	v_mfma_f32_32x32x16_bf16 v[82:97], v[202:205], v[134:137], v[82:97]
	s_waitcnt lgkmcnt(0)
	v_mfma_f32_32x32x16_bf16 v[66:81], v[206:209], v[134:137], v[66:81]
	ds_read_b128 v[202:205], v196 offset:32864
	ds_read_b128 v[206:209], v196 offset:41568
	s_waitcnt lgkmcnt(1)
	v_mfma_f32_32x32x16_bf16 v[82:97], v[202:205], v[130:133], v[82:97]
	s_waitcnt lgkmcnt(0)
	v_mfma_f32_32x32x16_bf16 v[66:81], v[206:209], v[130:133], v[66:81]
	ds_read_b128 v[202:205], v196 offset:32896
	ds_read_b128 v[206:209], v196 offset:41600
	s_waitcnt lgkmcnt(1)
	v_mfma_f32_32x32x16_bf16 v[82:97], v[202:205], v[126:129], v[82:97]
	s_waitcnt lgkmcnt(0)
	v_mfma_f32_32x32x16_bf16 v[66:81], v[206:209], v[126:129], v[66:81]
	ds_read_b128 v[202:205], v196 offset:32928
	ds_read_b128 v[206:209], v196 offset:41632
	s_waitcnt lgkmcnt(1)
	v_mfma_f32_32x32x16_bf16 v[82:97], v[202:205], v[122:125], v[82:97]
	s_waitcnt lgkmcnt(0)
	v_mfma_f32_32x32x16_bf16 v[66:81], v[206:209], v[122:125], v[66:81]
	ds_read_b128 v[202:205], v196 offset:32960
	ds_read_b128 v[206:209], v196 offset:41664
	s_waitcnt lgkmcnt(1)
	v_mfma_f32_32x32x16_bf16 v[82:97], v[202:205], v[118:121], v[82:97]
	s_waitcnt lgkmcnt(0)
	v_mfma_f32_32x32x16_bf16 v[66:81], v[206:209], v[118:121], v[66:81]
	ds_read_b128 v[202:205], v196 offset:32992
	ds_read_b128 v[206:209], v196 offset:41696
	s_waitcnt lgkmcnt(1)
	v_mfma_f32_32x32x16_bf16 v[82:97], v[202:205], v[114:117], v[82:97]
	v_exp_f32_e32 v203, v98
	v_add_f32_e32 v98, 0, v210
	v_add_f32_e32 v98, v211, v98
	v_add_f32_e32 v98, v212, v98
	v_add_f32_e32 v98, v213, v98
	v_add_f32_e32 v98, v214, v98
	v_add_f32_e32 v98, v215, v98
	v_add_f32_e32 v98, v216, v98
	v_add_f32_e32 v98, v219, v98
	v_add_f32_e32 v98, v228, v98
	v_add_f32_e32 v98, v229, v98
	v_add_f32_e32 v98, v230, v98
	v_add_f32_e32 v98, v220, v98
	v_add_f32_e32 v98, v221, v98
	v_exp_f32_e32 v204, v99
	v_add_f32_e32 v98, v222, v98
	v_exp_f32_e32 v205, v100
	v_add_f32_e32 v98, v223, v98
	s_waitcnt lgkmcnt(0)
	v_mfma_f32_32x32x16_bf16 v[66:81], v[206:209], v[114:117], v[66:81]
	v_exp_f32_e32 v206, v101
	v_add_f32_e32 v98, v231, v98
	v_exp_f32_e32 v207, v102
	v_add_f32_e32 v98, v98, v203
	v_exp_f32_e32 v208, v103
	v_add_f32_e32 v98, v204, v98
	v_exp_f32_e32 v209, v104
	v_add_f32_e32 v98, v205, v98
	v_add_f32_e32 v98, v206, v98
	v_add_f32_e32 v98, v207, v98
	v_add_f32_e32 v98, v208, v98
	v_add_f32_e32 v98, v209, v98
	v_add_f32_e32 v98, v224, v98
	v_add_f32_e32 v98, v225, v98
	v_add_f32_e32 v98, v226, v98
	v_add_f32_e32 v98, v227, v98
	v_add_f32_e32 v98, v232, v98
	v_add_f32_e32 v98, v233, v98
	v_add_f32_e32 v98, v236, v98
	v_add_f32_e32 v98, v237, v98
	v_add_f32_e32 v201, v113, v98
	v_cvt_pk_bf16_f32 v98, v210, v211
	v_cvt_pk_bf16_f32 v99, v212, v213
	v_cvt_pk_bf16_f32 v100, v214, v215
	v_cvt_pk_bf16_f32 v101, v216, v219
	v_cvt_pk_bf16_f32 v102, v228, v229
	v_cvt_pk_bf16_f32 v103, v230, v220
	v_cvt_pk_bf16_f32 v104, v221, v222
	v_cvt_pk_bf16_f32 v105, v223, v231
	v_cvt_pk_bf16_f32 v106, v203, v204
	v_cvt_pk_bf16_f32 v107, v205, v206
	v_cvt_pk_bf16_f32 v108, v207, v208
	v_cvt_pk_bf16_f32 v109, v209, v224
	v_cvt_pk_bf16_f32 v110, v225, v226
	v_cvt_pk_bf16_f32 v111, v227, v232
	v_cvt_pk_bf16_f32 v112, v233, v236
	v_cvt_pk_bf16_f32 v113, v237, v113
	s_cmp_ge_u32 s14, s15
	s_cselect_b64 s[8:9], -1, 0
	s_and_b64 vcc, exec, s[8:9]
	s_cbranch_vccnz .LBB0_1468
	global_load_dwordx4 v[146:149], v240, s[98:99] offset:256
	global_load_dwordx4 v[150:153], v241, s[98:99] offset:256
	global_load_dwordx4 v[154:157], v242, s[100:101] offset:256
	global_load_dwordx4 v[158:161], v242, s[100:101] offset:384
	s_add_u32 s98, s98, 0x10000
	s_addc_u32 s99, s99, 0
	s_add_u32 s100, s100, 0x10000
	s_addc_u32 s101, s101, 0
	s_branch .LBB0_1468
; #define SBAR() __builtin_amdgcn_sched_barrier(0)
; #define PVD0(...) do { if constexpr (PV_PIPE != 0) pv_d0_pipe(__VA_ARGS__); else pv_d0(__VA_ARGS__); } while (0)
; template <int DQK, int SDEPTH, int QL, bool NOMAX, int ldq, int ldk, int ldv, int ldo> ...
;     ...
;     SBAR(); qkt<DQK, QL>(pB0, pB1, K_lds + SHM_K, qr, qpark, r32, hi);
;     finishSM(pA0, pA1, alA, l_reg, pa0, pa1, pa2, pa3); SBAR();
;     PVD0(o, vb0, pa0, pa1, pa2, pa3); if constexpr (NOMAX) { partialSM_nm(pB0); alB = 1.f; } else partialSM(pB0, pB1, m_reg, mnB, alB, C, thr_raw);
.LBB0_1471:
	v_mov_b32_e32 v238, v193
	s_nop 1
	v_permlane32_swap_b32_e32 v193, v238
	v_add_f32_e32 v193, v193, v238
	ds_read_b128 v[82:85], v196 offset:58880
	ds_read_b128 v[86:89], v196 offset:50176
	ds_read_b128 v[146:149], v196 offset:50208
	v_exp_f32_e32 v67, v67
	v_exp_f32_e32 v69, v69
	s_waitcnt lgkmcnt(1)
	v_mfma_f32_32x32x16_bf16 v[98:113], v[86:89], v[142:145], 0
	v_mfma_f32_32x32x16_bf16 v[82:97], v[82:85], v[142:145], 0
	ds_read_b128 v[142:145], v196 offset:58912
	s_waitcnt lgkmcnt(1)
	v_mfma_f32_32x32x16_bf16 v[98:113], v[146:149], v[138:141], v[98:113]
	s_waitcnt lgkmcnt(0)
	v_mfma_f32_32x32x16_bf16 v[82:97], v[142:145], v[138:141], v[82:97]
	ds_read_b128 v[138:141], v196 offset:50240
	ds_read_b128 v[142:145], v196 offset:58944
	s_waitcnt lgkmcnt(1)
	v_mfma_f32_32x32x16_bf16 v[98:113], v[138:141], v[134:137], v[98:113]
	s_waitcnt lgkmcnt(0)
	v_mfma_f32_32x32x16_bf16 v[82:97], v[142:145], v[134:137], v[82:97]
	ds_read_b128 v[134:137], v196 offset:50272
	ds_read_b128 v[138:141], v196 offset:58976
	s_waitcnt lgkmcnt(1)
	v_mfma_f32_32x32x16_bf16 v[98:113], v[134:137], v[130:133], v[98:113]
	s_waitcnt lgkmcnt(0)
	v_mfma_f32_32x32x16_bf16 v[82:97], v[138:141], v[130:133], v[82:97]
	ds_read_b128 v[130:133], v196 offset:50304
	ds_read_b128 v[134:137], v196 offset:59008
	s_waitcnt lgkmcnt(1)
	v_mfma_f32_32x32x16_bf16 v[98:113], v[130:133], v[126:129], v[98:113]
	s_waitcnt lgkmcnt(0)
	v_mfma_f32_32x32x16_bf16 v[82:97], v[134:137], v[126:129], v[82:97]
	ds_read_b128 v[126:129], v196 offset:50336
	ds_read_b128 v[130:133], v196 offset:59040
	s_waitcnt lgkmcnt(1)
	v_mfma_f32_32x32x16_bf16 v[98:113], v[126:129], v[122:125], v[98:113]
	s_waitcnt lgkmcnt(0)
	v_mfma_f32_32x32x16_bf16 v[82:97], v[130:133], v[122:125], v[82:97]
	ds_read_b128 v[122:125], v196 offset:50368
	ds_read_b128 v[126:129], v196 offset:59072
	s_waitcnt lgkmcnt(1)
	v_mfma_f32_32x32x16_bf16 v[98:113], v[122:125], v[118:121], v[98:113]
	s_waitcnt lgkmcnt(0)
	v_mfma_f32_32x32x16_bf16 v[82:97], v[126:129], v[118:121], v[82:97]
	ds_read_b128 v[118:121], v196 offset:50400
	ds_read_b128 v[122:125], v196 offset:59104
	v_exp_f32_e32 v126, v80
	v_exp_f32_e32 v127, v81
	s_waitcnt lgkmcnt(1)
	v_mfma_f32_32x32x16_bf16 v[98:113], v[118:121], v[114:117], v[98:113]
	v_exp_f32_e32 v118, v72
	v_exp_f32_e32 v119, v73
	v_exp_f32_e32 v120, v74
	v_exp_f32_e32 v121, v75
	s_waitcnt lgkmcnt(0)
	v_mfma_f32_32x32x16_bf16 v[82:97], v[122:125], v[114:117], v[82:97]
	v_exp_f32_e32 v114, v66
	v_add_f32_e32 v66, 0, v206
	v_add_f32_e32 v66, v209, v66
	v_add_f32_e32 v66, v204, v66
	v_add_f32_e32 v66, v207, v66
	v_add_f32_e32 v66, v203, v66
	v_add_f32_e32 v66, v205, v66
	v_add_f32_e32 v66, v208, v66
	v_add_f32_e32 v66, v216, v66
	v_add_f32_e32 v66, v189, v66
	v_add_f32_e32 v66, v202, v66
	v_add_f32_e32 v66, v187, v66
	v_add_f32_e32 v66, v201, v66
	v_add_f32_e32 v66, v184, v66
	v_add_f32_e32 v66, v188, v66
	v_exp_f32_e32 v115, v68
	v_add_f32_e32 v66, v185, v66
	v_add_f32_e32 v66, v186, v66
	v_exp_f32_e32 v116, v70
	v_add_f32_e32 v66, v114, v66
	v_exp_f32_e32 v117, v71
	v_add_f32_e32 v66, v67, v66
	v_add_f32_e32 v66, v115, v66
	v_add_f32_e32 v66, v69, v66
	v_add_f32_e32 v66, v116, v66
	v_add_f32_e32 v66, v117, v66
	v_exp_f32_e32 v122, v76
	v_add_f32_e32 v66, v118, v66
	v_exp_f32_e32 v123, v77
	v_add_f32_e32 v66, v119, v66
	v_exp_f32_e32 v124, v78
	v_add_f32_e32 v66, v120, v66
	v_exp_f32_e32 v125, v79
	v_add_f32_e32 v66, v121, v66
	v_add_f32_e32 v66, v122, v66
	v_add_f32_e32 v66, v123, v66
	v_add_f32_e32 v66, v124, v66
	v_add_f32_e32 v66, v125, v66
	v_add_f32_e32 v66, v126, v66
	v_add_f32_e32 v66, v127, v66
	v_mov_b32_e32 v68, v66
	s_nop 1
	v_permlane32_swap_b32_e32 v66, v68
	v_cvt_pk_bf16_f32 v70, v206, v209
	v_cvt_pk_bf16_f32 v71, v204, v207
	v_cvt_pk_bf16_f32 v72, v203, v205
	v_cvt_pk_bf16_f32 v73, v208, v216
	v_cvt_pk_bf16_f32 v74, v189, v202
	v_cvt_pk_bf16_f32 v75, v187, v201
	v_cvt_pk_bf16_f32 v76, v184, v188
	v_cvt_pk_bf16_f32 v77, v185, v186
	v_cvt_pk_bf16_f32 v78, v114, v67
	v_cvt_pk_bf16_f32 v79, v115, v69
	v_cvt_pk_bf16_f32 v80, v116, v117
	v_cvt_pk_bf16_f32 v81, v118, v119
	v_cvt_pk_bf16_f32 v114, v120, v121
	v_cvt_pk_bf16_f32 v115, v122, v123
	v_cvt_pk_bf16_f32 v116, v124, v125
	v_cvt_pk_bf16_f32 v117, v126, v127
	ds_read_b64_tr_b16 v[118:119], v195 offset:0
	ds_read_b64_tr_b16 v[120:121], v195 offset:0x800
	ds_read_b64_tr_b16 v[122:123], v195 offset:0x1000
	ds_read_b64_tr_b16 v[124:125], v195 offset:0x1800
	ds_read_b64_tr_b16 v[126:127], v195 offset:0x2000
	ds_read_b64_tr_b16 v[128:129], v195 offset:0x2800
	ds_read_b64_tr_b16 v[130:131], v195 offset:0x3000
	ds_read_b64_tr_b16 v[132:133], v195 offset:0x3800
	s_waitcnt lgkmcnt(0)
	s_nop 0
	v_mfma_f32_32x32x16_bf16 v[50:65], v[70:73], v[118:121], v[50:65]
	ds_read_b64_tr_b16 v[118:119], v195 offset:0x200
	ds_read_b64_tr_b16 v[120:121], v195 offset:0xa00
	v_mfma_f32_32x32x16_bf16 v[50:65], v[74:77], v[122:125], v[50:65]
	ds_read_b64_tr_b16 v[122:123], v195 offset:0x1200
	ds_read_b64_tr_b16 v[124:125], v195 offset:0x1a00
	v_mfma_f32_32x32x16_bf16 v[50:65], v[78:81], v[126:129], v[50:65]
	ds_read_b64_tr_b16 v[126:127], v195 offset:0x2200
	ds_read_b64_tr_b16 v[128:129], v195 offset:0x2a00
	v_mfma_f32_32x32x16_bf16 v[50:65], v[114:117], v[130:133], v[50:65]
	ds_read_b64_tr_b16 v[130:131], v195 offset:0x3200
	ds_read_b64_tr_b16 v[132:133], v195 offset:0x3a00
	s_waitcnt lgkmcnt(0)
; #define SBAR() __builtin_amdgcn_sched_barrier(0)
; #define PVD0(...) do { if constexpr (PV_PIPE != 0) pv_d0_pipe(__VA_ARGS__); else pv_d0(__VA_ARGS__); } while (0)
; #define RESC(a) do { if constexpr (!NOMAX) if (__any((a) < 1.f)) { if (hi == 0) al_l[r32] = (a); asm volatile("s_waitcnt lgkmcnt(0)" ::: "memory"); \
;     _Pragma("unroll") for (int d = 0; d < 4; ++d) _Pragma("unroll") for (int r = 0; r < 16; ++r) o[d][r] *= al_l[crow(r, hi)]; } } while (0)
; #define RESC(a) do { if (__any((a) < 1.f)) { if (hi == 0) al_l[r32] = (a); asm volatile("s_waitcnt lgkmcnt(0)" ::: "memory"); \
;     _Pragma("unroll") for (int d = 0; d < 4; ++d) _Pragma("unroll") for (int r = 0; r < 16; ++r) o[d][r] *= al_l[crow(r, hi)]; } } while (0)
; template <int DQK, int SDEPTH, int QL, bool NOMAX, int ldq, int ldk, int ldv, int ldo> ...
;     ...
;     PVD0(o, vb0, pa0, pa1, pa2, pa3); if constexpr (NOMAX) { partialSM_nm(pB0); alB = 1.f; } else partialSM(pB0, pB1, m_reg, mnB, alB, C, thr_raw);
;     __syncthreads(); RESC(alB);
;     finishSM(pB0, pB1, alB, l_reg, pa0, pa1, pa2, pa3); SBAR();
	v_mfma_f32_32x32x16_bf16 v[34:49], v[70:73], v[118:121], v[34:49]
	ds_read_b64_tr_b16 v[118:119], v195 offset:0x400
	ds_read_b64_tr_b16 v[120:121], v195 offset:0xc00
	v_mfma_f32_32x32x16_bf16 v[34:49], v[74:77], v[122:125], v[34:49]
	ds_read_b64_tr_b16 v[122:123], v195 offset:0x1400
	ds_read_b64_tr_b16 v[124:125], v195 offset:0x1c00
	v_mfma_f32_32x32x16_bf16 v[34:49], v[78:81], v[126:129], v[34:49]
	ds_read_b64_tr_b16 v[126:127], v195 offset:0x2400
	ds_read_b64_tr_b16 v[128:129], v195 offset:0x2c00
	v_mfma_f32_32x32x16_bf16 v[34:49], v[114:117], v[130:133], v[34:49]
	ds_read_b64_tr_b16 v[130:131], v195 offset:0x3400
	ds_read_b64_tr_b16 v[132:133], v195 offset:0x3c00
	s_waitcnt lgkmcnt(0)
	v_mfma_f32_32x32x16_bf16 v[16:31], v[70:73], v[118:121], v[16:31]
	ds_read_b64_tr_b16 v[118:119], v195 offset:0x600
	ds_read_b64_tr_b16 v[120:121], v195 offset:0xe00
	v_mfma_f32_32x32x16_bf16 v[16:31], v[74:77], v[122:125], v[16:31]
	ds_read_b64_tr_b16 v[122:123], v195 offset:0x1600
	ds_read_b64_tr_b16 v[124:125], v195 offset:0x1e00
	v_mfma_f32_32x32x16_bf16 v[16:31], v[78:81], v[126:129], v[16:31]
	ds_read_b64_tr_b16 v[126:127], v195 offset:0x2600
	ds_read_b64_tr_b16 v[128:129], v195 offset:0x2e00
	v_mfma_f32_32x32x16_bf16 v[16:31], v[114:117], v[130:133], v[16:31]
	ds_read_b64_tr_b16 v[130:131], v195 offset:0x3600
	ds_read_b64_tr_b16 v[132:133], v195 offset:0x3e00
	s_waitcnt lgkmcnt(0)
	v_mfma_f32_32x32x16_bf16 v[0:15], v[70:73], v[118:121], v[0:15]
	v_exp_f32_e32 v70, v98
	v_exp_f32_e32 v71, v99
	v_exp_f32_e32 v72, v100
	v_exp_f32_e32 v73, v101
	v_add_f32_e32 v67, 0, v70
	v_add_f32_e32 v67, v71, v67
	v_add_f32_e32 v67, v72, v67
	v_mfma_f32_32x32x16_bf16 v[0:15], v[74:77], v[122:125], v[0:15]
	v_exp_f32_e32 v74, v102
	v_exp_f32_e32 v75, v103
	v_exp_f32_e32 v76, v104
	v_exp_f32_e32 v77, v105
	v_add_f32_e32 v67, v73, v67
	v_add_f32_e32 v67, v74, v67
	v_add_f32_e32 v67, v75, v67
	v_mfma_f32_32x32x16_bf16 v[0:15], v[78:81], v[126:129], v[0:15]
	v_exp_f32_e32 v78, v106
	v_exp_f32_e32 v79, v107
	v_exp_f32_e32 v80, v108
	v_add_f32_e32 v67, v76, v67
	v_exp_f32_e32 v81, v109
	v_add_f32_e32 v67, v77, v67
	v_exp_f32_e32 v98, v110
	v_add_f32_e32 v67, v78, v67
	v_exp_f32_e32 v99, v111
	v_add_f32_e32 v67, v79, v67
	v_exp_f32_e32 v100, v112
	v_add_f32_e32 v67, v80, v67
	v_exp_f32_e32 v101, v113
	v_add_f32_e32 v67, v81, v67
	v_exp_f32_e32 v82, v82
	v_add_f32_e32 v67, v98, v67
	v_exp_f32_e32 v83, v83
	v_add_f32_e32 v67, v99, v67
	v_exp_f32_e32 v84, v84
	v_add_f32_e32 v67, v100, v67
	v_exp_f32_e32 v85, v85
	v_add_f32_e32 v67, v101, v67
	v_exp_f32_e32 v86, v86
	v_add_f32_e32 v67, v82, v67
	v_exp_f32_e32 v87, v87
	v_add_f32_e32 v67, v83, v67
	v_exp_f32_e32 v88, v88
	v_add_f32_e32 v67, v84, v67
	v_exp_f32_e32 v89, v89
	v_add_f32_e32 v67, v85, v67
	v_exp_f32_e32 v90, v90
	v_add_f32_e32 v67, v86, v67
	v_exp_f32_e32 v91, v91
	v_add_f32_e32 v67, v87, v67
	v_exp_f32_e32 v92, v92
	v_add_f32_e32 v67, v88, v67
	v_exp_f32_e32 v93, v93
	v_add_f32_e32 v67, v89, v67
	v_exp_f32_e32 v94, v94
	v_add_f32_e32 v67, v90, v67
	v_exp_f32_e32 v95, v95
	v_add_f32_e32 v67, v91, v67
	v_mfma_f32_32x32x16_bf16 v[0:15], v[114:117], v[130:133], v[0:15]
	v_exp_f32_e32 v96, v96
	v_add_f32_e32 v67, v92, v67
	v_exp_f32_e32 v97, v97
	v_add_f32_e32 v67, v93, v67
	v_add_f32_e32 v67, v94, v67
	v_add_f32_e32 v67, v95, v67
	v_add_f32_e32 v67, v96, v67
	v_add_f32_e32 v67, v97, v67
	v_mov_b32_e32 v69, v67
	s_barrier
; template <int M> __device__ __forceinline__ float swz_xor(float v) { return __int_as_float(__builtin_amdgcn_ds_swizzle(__float_as_int(v), (M << 10) | 0x1f)); }
; #define SBAR() __builtin_amdgcn_sched_barrier(0)
; __device__ __forceinline__ int crow(int r, int hi) { return (r & 3) + 8 * (r >> 2) + 4 * hi; }
; __device__ __forceinline__ unsigned cvtpk(float lo, float hi) { unsigned r; asm volatile("v_cvt_pk_bf16_f32 %0, %1, %2" : "=v"(r) : "v"(lo), "v"(hi)); return r; }
; #define PVD0(...) do { if constexpr (PV_PIPE != 0) pv_d0_pipe(__VA_ARGS__); else pv_d0(__VA_ARGS__); } while (0)
; template <int DQK, int SDEPTH, int QL, bool NOMAX, int ldq, int ldk, int ldv, int ldo> ...
;     ...
;     finishSM(pB0, pB1, alB, l_reg, pa0, pa1, pa2, pa3); SBAR();
;     PVD0(o, vb0 + SHM_V, pa0, pa1, pa2, pa3);
;     if (ATT_PRIO) __builtin_amdgcn_s_setprio(0);
;     if (hi == 0) li_l[r32] = l_reg; asm volatile("s_waitcnt lgkmcnt(0)" ::: "memory");
;     float rli[16];
; #pragma unroll
;     for (int r = 0; r < 16; ++r) rli[r] = __builtin_amdgcn_rcpf(li_l[crow(r, hi)]);
;     bf16_t* Ow = Ob + (size_t)(wid * QBLK) * ldo + (r32 & ~1);
;     const bool odd = (r32 & 1) != 0;
; #pragma unroll
;     for (int r = 0; r < 16; r += 2) { const int orow = crow(r, hi) + (odd ? 1 : 0);
; #pragma unroll
;         for (int d0 = 0; d0 < 4; ++d0) { const float a = o[d0][r] * rli[r], b = o[d0][r + 1] * rli[r + 1];
;             const float recv = swz_xor<1>(odd ? a : b);
;             const unsigned w = odd ? cvtpk(recv, b) : cvtpk(a, recv);
;             *(unsigned*)(Ow + (size_t)orow * ldo + d0 * 32) = w; } }
	s_nop 0
	v_permlane32_swap_b32_e32 v67, v69
	v_cvt_pk_bf16_f32 v70, v70, v71
	v_cvt_pk_bf16_f32 v71, v72, v73
	v_cvt_pk_bf16_f32 v72, v74, v75
	v_cvt_pk_bf16_f32 v73, v76, v77
	v_cvt_pk_bf16_f32 v74, v78, v79
	v_cvt_pk_bf16_f32 v75, v80, v81
	v_cvt_pk_bf16_f32 v76, v98, v99
	v_cvt_pk_bf16_f32 v77, v100, v101
	v_cvt_pk_bf16_f32 v78, v82, v83
	v_cvt_pk_bf16_f32 v79, v84, v85
	v_cvt_pk_bf16_f32 v80, v86, v87
	v_cvt_pk_bf16_f32 v81, v88, v89
	v_cvt_pk_bf16_f32 v82, v90, v91
	v_cvt_pk_bf16_f32 v83, v92, v93
	v_cvt_pk_bf16_f32 v84, v94, v95
	v_cvt_pk_bf16_f32 v85, v96, v97
	ds_read_b64_tr_b16 v[86:87], v194 offset:0
	ds_read_b64_tr_b16 v[88:89], v194 offset:0x800
	ds_read_b64_tr_b16 v[90:91], v194 offset:0x1000
	ds_read_b64_tr_b16 v[92:93], v194 offset:0x1800
	ds_read_b64_tr_b16 v[94:95], v194 offset:0x2000
	ds_read_b64_tr_b16 v[96:97], v194 offset:0x2800
	ds_read_b64_tr_b16 v[98:99], v194 offset:0x3000
	ds_read_b64_tr_b16 v[100:101], v194 offset:0x3800
	s_waitcnt lgkmcnt(0)
	s_nop 0
	v_mfma_f32_32x32x16_bf16 v[50:65], v[70:73], v[86:89], v[50:65]
	ds_read_b64_tr_b16 v[86:87], v194 offset:0x200
	ds_read_b64_tr_b16 v[88:89], v194 offset:0xa00
	v_mfma_f32_32x32x16_bf16 v[50:65], v[74:77], v[90:93], v[50:65]
	ds_read_b64_tr_b16 v[90:91], v194 offset:0x1200
	ds_read_b64_tr_b16 v[92:93], v194 offset:0x1a00
	v_mfma_f32_32x32x16_bf16 v[50:65], v[78:81], v[94:97], v[50:65]
	ds_read_b64_tr_b16 v[94:95], v194 offset:0x2200
	ds_read_b64_tr_b16 v[96:97], v194 offset:0x2a00
	v_mfma_f32_32x32x16_bf16 v[50:65], v[82:85], v[98:101], v[50:65]
	ds_read_b64_tr_b16 v[98:99], v194 offset:0x3200
	ds_read_b64_tr_b16 v[100:101], v194 offset:0x3a00
	s_waitcnt lgkmcnt(0)
	v_mfma_f32_32x32x16_bf16 v[34:49], v[70:73], v[86:89], v[34:49]
	ds_read_b64_tr_b16 v[86:87], v194 offset:0x400
	ds_read_b64_tr_b16 v[88:89], v194 offset:0xc00
	v_mfma_f32_32x32x16_bf16 v[34:49], v[74:77], v[90:93], v[34:49]
	ds_read_b64_tr_b16 v[90:91], v194 offset:0x1400
	ds_read_b64_tr_b16 v[92:93], v194 offset:0x1c00
	v_mfma_f32_32x32x16_bf16 v[34:49], v[78:81], v[94:97], v[34:49]
	ds_read_b64_tr_b16 v[94:95], v194 offset:0x2400
	ds_read_b64_tr_b16 v[96:97], v194 offset:0x2c00
	v_mfma_f32_32x32x16_bf16 v[34:49], v[82:85], v[98:101], v[34:49]
	ds_read_b64_tr_b16 v[98:99], v194 offset:0x3400
	ds_read_b64_tr_b16 v[100:101], v194 offset:0x3c00
	s_waitcnt lgkmcnt(0)
	v_mfma_f32_32x32x16_bf16 v[16:31], v[70:73], v[86:89], v[16:31]
	ds_read_b64_tr_b16 v[86:87], v194 offset:0x600
	ds_read_b64_tr_b16 v[88:89], v194 offset:0xe00
	v_mfma_f32_32x32x16_bf16 v[16:31], v[74:77], v[90:93], v[16:31]
	ds_read_b64_tr_b16 v[90:91], v194 offset:0x1600
	ds_read_b64_tr_b16 v[92:93], v194 offset:0x1e00
	v_mfma_f32_32x32x16_bf16 v[16:31], v[78:81], v[94:97], v[16:31]
	ds_read_b64_tr_b16 v[94:95], v194 offset:0x2600
	ds_read_b64_tr_b16 v[96:97], v194 offset:0x2e00
	v_mfma_f32_32x32x16_bf16 v[16:31], v[82:85], v[98:101], v[16:31]
	ds_read_b64_tr_b16 v[98:99], v194 offset:0x3600
	ds_read_b64_tr_b16 v[100:101], v194 offset:0x3e00
	s_waitcnt lgkmcnt(0)
	v_mfma_f32_32x32x16_bf16 v[0:15], v[70:73], v[86:89], v[0:15]
	v_mfma_f32_32x32x16_bf16 v[0:15], v[74:77], v[90:93], v[0:15]
	v_mfma_f32_32x32x16_bf16 v[0:15], v[78:81], v[94:97], v[0:15]
	v_mfma_f32_32x32x16_bf16 v[0:15], v[82:85], v[98:101], v[0:15]
	s_setprio 0
	v_cmp_gt_u32_e32 vcc, 32, v32
	s_and_saveexec_b64 s[6:7], vcc
	v_pk_add_f32 v[66:67], v[66:67], v[68:69]
	v_lshl_add_u32 v32, v192, 2, s49
	v_add_f32_e32 v66, v193, v66
	v_add_f32_e32 v66, v66, v67
	ds_write_b32 v32, v66
	s_or_b64 exec, exec, s[6:7]
	s_waitcnt lgkmcnt(0)
	v_lshl_add_u32 v32, v191, 4, s49
	ds_read_b128 v[78:81], v32
	ds_read_b128 v[74:77], v32 offset:32
	v_and_b32_e32 v82, 1, v190
	ds_read_b128 v[70:73], v32 offset:64
	ds_read_b128 v[66:69], v32 offset:96
	v_cmp_eq_u32_e64 s[8:9], 0, v82
	s_waitcnt lgkmcnt(3)
	v_rcp_f32_e32 v78, v78
	v_rcp_f32_e32 v79, v79
	v_cmp_eq_u32_e64 s[6:7], 1, v82
	v_mul_f32_e32 v32, v50, v78
	v_mul_f32_e32 v51, v51, v79
	v_cndmask_b32_e64 v50, v32, v51, s[8:9]
	ds_swizzle_b32 v50, v50 offset:swizzle(SWAP,1)
	s_and_saveexec_b64 s[14:15], s[6:7]
	s_xor_b64 s[14:15], exec, s[14:15]
	s_cbranch_execz .LBB0_1475
	s_waitcnt lgkmcnt(0)
	v_cvt_pk_bf16_f32 v83, v50, v51

; __device__ __forceinline__ int fresh_lane() { int l; asm volatile("v_mbcnt_lo_u32_b32 %0, -1, 0\n\tv_mbcnt_hi_u32_b32 %0, -1, %0" : "=v"(l)); return l; }
; __device__ __forceinline__ int v_rd_base(int lane) { return ((lane & 3) << 3) | (((lane >> 2) & 3) << 6) | (((lane >> 4) & 1) << 5) | (((lane >> 5) & 1) << 8); }
; __device__ __forceinline__ int v_st(int k, int c) { const int kk = (k & ~0xC) | ((k & 4) << 1) | ((k & 8) >> 1); return ((kk >> 3) * 4 + (c >> 5)) * 512 + ((kk & 7) * 32 + (c & 31)) * 2; }
; template <int DQK, int SDEPTH, int QL, bool NOMAX, int ldq, int ldk, int ldv, int ldo> ...
;     ...
;     const int tid_l = tid_in * 64 + fresh_lane();
;     const int tid = tid_l, wid = tid_in  , lane = tid & 63, r32 = lane & 31, hi = lane >> 5;
;     char* V_lds = lds; char* K_lds = lds + 2 * SHM_V;
;     float* ws = (float*)(lds + 2 * SHM_V + 2 * SHM_K) + wid * 64; float* li_l = ws; float* al_l = ws + 32;
;     constexpr int NQR = DQK / 16 - QL;
;     char* qpark = lds + 2 * SHM_V + 2 * SHM_K + 2048 + wid * (QL * 1024) + lane * 16;
;     float m_reg = -1e30f, l_reg = 0; f32x16 o[4] = {}; bf16x8 qr[NQR];
;     const bf16_t* Qw = Qb + (size_t)(wid * QBLK + r32) * ldq + hi * 8;
; #pragma unroll
;     for (int d0 = 0; d0 < NQR; ++d0) qr[d0] = *reinterpret_cast<const bf16x8*>(Qw + d0 * 16);
; #pragma unroll
;     for (int d0 = 0; d0 < QL; ++d0) *(bf16x8*)(qpark + d0 * 1024) = *reinterpret_cast<const bf16x8*>(Qw + (NQR + d0) * 16);
;     const int sr = tid >> 4, sc = (tid & 15) * 8, vst0 = v_st(sr, sc), vst1 = v_st(32 + sr, sc);
;     int koff[NKP], klds[NKP];
; #pragma unroll
;     for (int i = 0; i < NKP; ++i) { const int row = tid >> 3, c8 = (tid & 7) + 8 * i; koff[i] = row * ldk + c8 * 8; klds[i] = row * RS + c8 * 16; }
;     const int vb0 = (int)(uintptr_t)V_lds + v_rd_base(lane);
;     bf16x8 sv0[SDEPTH], sv1[SDEPTH], sk[SDEPTH][NKP];
;     ...
;     f32x16 pA0, pA1, pB0, pB1; float mnA, mnB, alA, alB; bf16x8 pa0, pa1, pa2, pa3; const int NT = seq / KVBLK;
;     if (ATT_PRIO && wid >= 4) __builtin_amdgcn_s_setprio(1);
;     constexpr int SE = 0, SO = SDEPTH - 1;
;     SLOAD(SE, 0); asm volatile("s_waitcnt vmcnt(0)" ::: "memory"); SWRITE(0, SE); __syncthreads();
;     qkt<DQK, QL>(pA0, pA1, K_lds, qr, qpark, r32, hi); if constexpr (NOMAX) { partialSM_nm(pA0); alA = 1.f; } else partialSM(pA0, pA1, m_reg, mnA, alA, C, thr_raw);
.LBB0_2011:
	v_add_u32_e32 v0, s39, v232
	v_ashrrev_i32_e32 v28, 4, v0
	v_lshlrev_b32_e32 v34, 3, v232
	v_ashrrev_i32_e32 v35, 3, v0
	v_and_b32_e32 v36, 7, v232
	s_movk_i32 s4, 0x600
	v_ashrrev_i32_e32 v29, 31, v28
	v_and_b32_e32 v2, 0x78, v34
	v_add_u32_e32 v30, 32, v28
	v_mul_lo_u32 v0, v35, s4
	v_or_b32_e32 v37, 8, v36
	v_or_b32_e32 v46, 16, v36
	v_lshlrev_b64 v[16:17], 11, v[28:29]
	v_lshl_or_b32 v8, v36, 3, v0
	v_lshl_or_b32 v10, v37, 3, v0
	v_lshl_or_b32 v22, v46, 3, v0
	v_lshl_add_u64 v[0:1], s[26:27], 0, v[16:17]
	v_lshlrev_b32_e32 v2, 1, v2
	v_mov_b32_e32 v3, v33
	v_ashrrev_i32_e32 v31, 31, v30
	v_lshl_add_u64 v[38:39], v[0:1], 0, v[2:3]
	v_lshlrev_b64 v[0:1], 11, v[30:31]
	v_ashrrev_i32_e32 v9, 31, v8
	v_lshl_add_u64 v[0:1], s[26:27], 0, v[0:1]
	v_lshlrev_b64 v[18:19], 1, v[8:9]
	v_ashrrev_i32_e32 v11, 31, v10
	v_lshl_add_u64 v[4:5], v[0:1], 0, v[2:3]
	v_lshl_add_u64 v[40:41], s[24:25], 0, v[18:19]
	v_lshlrev_b64 v[20:21], 1, v[10:11]
	global_load_dwordx4 v[0:3], v[38:39], off
	s_nop 0
	global_load_dwordx4 v[4:7], v[4:5], off
	v_lshl_add_u64 v[42:43], s[24:25], 0, v[20:21]
	global_load_dwordx4 v[8:11], v[40:41], off
	global_load_dwordx4 v[12:15], v[42:43], off
	v_ashrrev_i32_e32 v23, 31, v22
	v_lshlrev_b64 v[22:23], 1, v[22:23]
	v_lshl_add_u64 v[44:45], s[24:25], 0, v[22:23]
	global_load_dwordx4 v[24:27], v[44:45], off
	v_bfe_u32 v31, v34, 5, 2
	v_and_b32_e32 v34, 0xfffff0, v28
	v_and_or_b32 v34, v28, 8, v34
	v_and_b32_e32 v47, 0xfffff0, v30
	v_mov_b32_e32 v48, v28
	v_and_b32_e32 v28, 3, v28
	v_lshrrev_b32_e32 v34, 1, v34
	v_and_or_b32 v30, v30, 8, v47
	v_lshlrev_b32_e32 v29, 4, v232
	v_and_or_b32 v28, v48, 4, v28
	v_or_b32_e32 v34, v34, v31
	v_lshrrev_b32_e32 v30, 1, v30
	s_movk_i32 s4, 0x190
	v_and_b32_e32 v29, 48, v29
	v_lshlrev_b32_e32 v28, 6, v28
	v_lshlrev_b32_e32 v34, 9, v34
	v_or_b32_e32 v30, v30, v31
	v_mad_u32_u24 v58, v240, s4, 0
	v_mul_lo_u32 v35, v35, s4
	v_lshlrev_b32_e32 v30, 9, v30
	v_or3_b32 v31, v34, v28, v29
	v_add_u32_e32 v245, v58, v32
	v_lshl_add_u32 v36, v36, 4, v35
	v_lshl_add_u32 v37, v37, 4, v35
	v_lshl_add_u32 v35, v46, 4, v35
	v_or3_b32 v28, v30, v28, v29
	v_add_u32_e32 v249, 0, v31
	v_add_u32_e32 v246, 0, v36
	v_add_u32_e32 v247, 0, v37
	v_add_u32_e32 v248, 0, v35
	s_waitcnt vmcnt(0)
	v_add_u32_e32 v250, 0, v28
	v_add_co_u32_e32 v46, vcc, s66, v38
	s_mov_b32 s4, 0x30000
	s_nop 0
	v_addc_co_u32_e32 v47, vcc, 0, v39, vcc
	v_add_co_u32_e32 v38, vcc, s4, v38
	v_and_b32_e32 v241, 63, v232
	s_nop 0
	v_addc_co_u32_e32 v39, vcc, 0, v39, vcc
	v_add_co_u32_e32 v48, vcc, s4, v40
	v_lshlrev_b32_e32 v59, 4, v241
	s_nop 0
	v_addc_co_u32_e32 v49, vcc, 0, v41, vcc
	v_add_co_u32_e32 v50, vcc, s4, v42
	v_lshlrev_b32_e32 v60, 3, v241
	s_waitcnt vmcnt(4)
	ds_write_b128 v249, v[0:3]
	s_waitcnt vmcnt(3)
	ds_write_b128 v250, v[4:7]
	s_waitcnt vmcnt(2)
	ds_write_b128 v246, v[8:11] offset:32768
	s_waitcnt vmcnt(1)
	ds_write_b128 v247, v[12:15] offset:32768
	s_waitcnt vmcnt(0)
	ds_write_b128 v248, v[24:27] offset:32768
	s_waitcnt lgkmcnt(0)
	s_barrier
	ds_read_b128 v[0:3], v245 offset:32768
	ds_read_b128 v[24:27], v245 offset:32800
	s_waitcnt lgkmcnt(1)
	v_mfma_f32_32x32x16_bf16 v[0:15], v[0:3], v[158:161], 0
	ds_read_b128 v[28:31], v245 offset:45568
	ds_read_b128 v[34:37], v245 offset:45600
	v_addc_co_u32_e32 v51, vcc, 0, v43, vcc
	v_add_co_u32_e32 v52, vcc, s4, v44
	v_lshlrev_b32_e32 v61, 1, v241
	s_nop 0
	v_addc_co_u32_e32 v53, vcc, 0, v45, vcc
	s_waitcnt lgkmcnt(1)
	v_mfma_f32_32x32x16_bf16 v[66:81], v[28:31], v[158:161], 0
	s_cmp_lg_u32 0, -1
	s_cselect_b32 s6, 0, 0
	s_add_i32 s7, s6, 0x4000
	s_add_u32 s4, s54, s55
	s_addc_u32 s5, s52, s53
	v_lshl_add_u64 v[216:217], s[4:5], 0, v[18:19]
	v_lshl_add_u64 v[218:219], s[4:5], 0, v[20:21]
	v_mfma_f32_32x32x16_bf16 v[0:15], v[24:27], v[154:157], v[0:15]
	ds_read_b128 v[24:27], v245 offset:32832
	ds_read_b128 v[28:31], v245 offset:32864
	v_lshl_add_u64 v[220:221], s[4:5], 0, v[22:23]
	s_lshl_b64 s[4:5], s[22:23], 11
	v_add_u32_e32 v58, 0xe400, v58
	v_mov_b32_e32 v243, 0
	v_add_u32_e32 v32, v58, v32
	v_mov_b32_e32 v58, v243
	s_waitcnt lgkmcnt(2)
	v_mfma_f32_32x32x16_bf16 v[66:81], v[34:37], v[154:157], v[66:81]
	v_mov_b32_e32 v62, v243
	v_mov_b32_e32 v63, v243
	v_mov_b32_e32 v64, v243
	v_mov_b32_e32 v65, v243
	v_mov_b32_e32 v18, v243
	v_mov_b32_e32 v19, v243
	v_mov_b32_e32 v20, v243
	s_waitcnt lgkmcnt(1)
	v_mfma_f32_32x32x16_bf16 v[0:15], v[24:27], v[150:153], v[0:15]
	ds_read_b128 v[24:27], v245 offset:45632
	ds_read_b128 v[34:37], v245 offset:45664
	v_mov_b32_e32 v21, v243
	v_mov_b32_e32 v22, v243
	v_mov_b32_e32 v23, v243
	s_mov_b64 s[14:15], 0x40000
	s_waitcnt lgkmcnt(1)
	v_mfma_f32_32x32x16_bf16 v[66:81], v[24:27], v[150:153], v[66:81]
	v_mfma_f32_32x32x16_bf16 v[0:15], v[28:31], v[146:149], v[0:15]
	ds_read_b128 v[24:27], v245 offset:32896
	ds_read_b128 v[28:31], v245 offset:32928
	s_waitcnt lgkmcnt(2)
	v_mfma_f32_32x32x16_bf16 v[66:81], v[34:37], v[146:149], v[66:81]
	s_waitcnt lgkmcnt(1)
	v_mfma_f32_32x32x16_bf16 v[0:15], v[24:27], v[142:145], v[0:15]
	ds_read_b128 v[24:27], v245 offset:45696
	ds_read_b128 v[34:37], v245 offset:45728
	s_waitcnt lgkmcnt(1)
	v_mfma_f32_32x32x16_bf16 v[66:81], v[24:27], v[142:145], v[66:81]
	v_mfma_f32_32x32x16_bf16 v[0:15], v[28:31], v[138:141], v[0:15]
	ds_read_b128 v[24:27], v245 offset:32960
	ds_read_b128 v[28:31], v245 offset:32992
	s_waitcnt lgkmcnt(2)
	v_mfma_f32_32x32x16_bf16 v[66:81], v[34:37], v[138:141], v[66:81]
	s_waitcnt lgkmcnt(1)
	v_mfma_f32_32x32x16_bf16 v[0:15], v[24:27], v[134:137], v[0:15]
	ds_read_b128 v[24:27], v245 offset:45760
	ds_read_b128 v[34:37], v245 offset:45792
	s_waitcnt lgkmcnt(1)
; __device__ __forceinline__ int v_st(int k, int c) { const int kk = (k & ~0xC) | ((k & 4) << 1) | ((k & 8) >> 1); return ((kk >> 3) * 4 + (c >> 5)) * 512 + ((kk & 7) * 32 + (c & 31)) * 2; }
; __device__ __forceinline__ int v_rd_base(int lane) { return ((lane & 3) << 3) | (((lane >> 2) & 3) << 6) | (((lane >> 4) & 1) << 5) | (((lane >> 5) & 1) << 8); }
; #define SLOAD(i, k0) do { sv0[i] = *reinterpret_cast<const bf16x8*>(&Vh[(size_t)((k0) + sr) * ldv + sc]); sv1[i] = *reinterpret_cast<const bf16x8*>(&Vh[(size_t)((k0) + 32 + sr) * ldv + sc]); \
;     _Pragma("unroll") for (int _q = 0; _q < NKP; ++_q) sk[i][_q] = *reinterpret_cast<const bf16x8*>(&Kh[(size_t)(k0) * ldk + koff[_q]]); } while (0)
; #define SWRITE(b, i) do { *(bf16x8*)(V_lds + (b) * SHM_V + vst0) = sv0[i]; *(bf16x8*)(V_lds + (b) * SHM_V + vst1) = sv1[i]; \
;     _Pragma("unroll") for (int _q = 0; _q < NKP; ++_q) *(bf16x8*)(K_lds + (b) * SHM_K + klds[_q]) = sk[i][_q]; } while (0)
; #define SWRITE(b) do { *(bf16x8*)(V_lds + (b) * SHM_V + vst0) = sv0; *(bf16x8*)(V_lds + (b) * SHM_V + vst1) = sv1; \
;     _Pragma("unroll") for (int _q = 0; _q < NKP; ++_q) *(bf16x8*)(K_lds + (b) * SHM_K + klds[_q]) = sk[_q]; } while (0)
; template <int DQK, int SDEPTH, int QL, bool NOMAX, int ldq, int ldk, int ldv, int ldo> ...
;     ...
;     const int sr = tid >> 4, sc = (tid & 15) * 8, vst0 = v_st(sr, sc), vst1 = v_st(32 + sr, sc);
;     int koff[NKP], klds[NKP];
; #pragma unroll
;     for (int i = 0; i < NKP; ++i) { const int row = tid >> 3, c8 = (tid & 7) + 8 * i; koff[i] = row * ldk + c8 * 8; klds[i] = row * RS + c8 * 16; }
;     const int vb0 = (int)(uintptr_t)V_lds + v_rd_base(lane);
;     bf16x8 sv0[SDEPTH], sv1[SDEPTH], sk[SDEPTH][NKP];
;     ...
;     f32x16 pA0, pA1, pB0, pB1; float mnA, mnB, alA, alB; bf16x8 pa0, pa1, pa2, pa3; const int NT = seq / KVBLK;
;     if (ATT_PRIO && wid >= 4) __builtin_amdgcn_s_setprio(1);
;     constexpr int SE = 0, SO = SDEPTH - 1;
;     SLOAD(SE, 0); asm volatile("s_waitcnt vmcnt(0)" ::: "memory"); SWRITE(0, SE); __syncthreads();
;     qkt<DQK, QL>(pA0, pA1, K_lds, qr, qpark, r32, hi); if constexpr (NOMAX) { partialSM_nm(pA0); alA = 1.f; } else partialSM(pA0, pA1, m_reg, mnA, alA, C, thr_raw);
;     SLOAD(SO, KVBLK); if constexpr (SDEPTH == 2) { if (2 < NT) SLOAD(SE, 2 * KVBLK); }
;     SWAIT(); SWRITE(1, SO); __syncthreads();
	v_mfma_f32_32x32x16_bf16 v[66:81], v[24:27], v[134:137], v[66:81]
	ds_read_b128 v[24:27], v245 offset:33024
	v_mfma_f32_32x32x16_bf16 v[0:15], v[28:31], v[130:133], v[0:15]
	s_waitcnt lgkmcnt(1)
	v_mfma_f32_32x32x16_bf16 v[66:81], v[34:37], v[130:133], v[66:81]
	ds_read_b128 v[28:31], v245 offset:45824
	ds_read_b128 v[34:37], v245 offset:33056
	s_waitcnt lgkmcnt(2)
	v_mfma_f32_32x32x16_bf16 v[0:15], v[24:27], v[126:129], v[0:15]
	ds_read_b128 v[24:27], v245 offset:45856
	s_waitcnt lgkmcnt(2)
	v_mfma_f32_32x32x16_bf16 v[66:81], v[28:31], v[126:129], v[66:81]
	global_load_dwordx4 v[28:31], v[46:47], off
	s_nop 0
	global_load_dwordx4 v[38:41], v[38:39], off
	s_nop 0
	global_load_dwordx4 v[42:45], v[48:49], off
	s_nop 0
	global_load_dwordx4 v[46:49], v[50:51], off
	s_waitcnt lgkmcnt(1)
	v_mfma_f32_32x32x16_bf16 v[0:15], v[34:37], v[122:125], v[0:15]
	global_load_dwordx4 v[34:37], v[52:53], off
	ds_read_b128 v[50:53], v245 offset:33088
	s_waitcnt lgkmcnt(1)
	v_mfma_f32_32x32x16_bf16 v[66:81], v[24:27], v[122:125], v[66:81]
	ds_read_b128 v[24:27], v245 offset:45888
	ds_read_b128 v[54:57], v245 offset:33120
	s_waitcnt lgkmcnt(2)
	v_mfma_f32_32x32x16_bf16 v[0:15], v[50:53], v[118:121], v[0:15]
	v_and_b32_e32 v50, 0xc0, v59
	v_and_b32_e32 v59, 32, v61
	v_and_b32_e32 v61, 0x100, v60
	v_and_or_b32 v60, v60, 24, v50
	ds_read_b128 v[50:53], v245 offset:45920
	s_waitcnt vmcnt(0)
	s_waitcnt vmcnt(4)
	ds_write_b128 v249, v[28:31] offset:16384
	s_waitcnt lgkmcnt(3)
	v_mfma_f32_32x32x16_bf16 v[66:81], v[24:27], v[118:121], v[66:81]
	v_or3_b32 v24, v60, v59, v61
	v_add_u32_e32 v244, s6, v24
	v_add_u32_e32 v242, s7, v24
	s_lshl_b64 s[6:7], s[20:21], 8
	s_add_u32 s4, s6, s4
	s_addc_u32 s5, s7, s5
	v_lshl_add_u64 v[222:223], s[4:5], 0, v[16:17]
	s_waitcnt lgkmcnt(2)
	v_mfma_f32_32x32x16_bf16 v[0:15], v[54:57], v[114:117], v[0:15]
	s_waitcnt vmcnt(3)
	ds_write_b128 v250, v[38:41] offset:16384
	s_waitcnt vmcnt(2)
	ds_write_b128 v246, v[42:45] offset:58368
	s_waitcnt vmcnt(1)
	ds_write_b128 v247, v[46:49] offset:58368
	s_waitcnt vmcnt(0)
	ds_write_b128 v248, v[34:37] offset:58368
	s_mov_b32 s4, 2
	v_mov_b32_e32 v54, v243
	v_mov_b32_e32 v55, v243
	v_mov_b32_e32 v56, v243
	v_mov_b32_e32 v57, v243
	v_mov_b32_e32 v59, v243
	s_waitcnt lgkmcnt(5)
	v_mfma_f32_32x32x16_bf16 v[66:81], v[50:53], v[114:117], v[66:81]
	v_exp_f32_e32 v190, v0
	v_exp_f32_e32 v209, v1
	v_exp_f32_e32 v191, v2
	v_exp_f32_e32 v208, v3
	v_exp_f32_e32 v192, v4
	v_exp_f32_e32 v207, v5
	v_exp_f32_e32 v193, v6
	v_exp_f32_e32 v206, v7
	v_exp_f32_e32 v198, v8
	v_exp_f32_e32 v205, v9
	v_exp_f32_e32 v199, v10
	v_exp_f32_e32 v204, v11
	v_exp_f32_e32 v200, v12
	v_exp_f32_e32 v202, v13
	v_exp_f32_e32 v201, v14
	v_exp_f32_e32 v203, v15
	v_and_b32_e32 v0, 15, v232
	v_lshl_or_b32 v222, v0, 4, v222
	v_mov_b32_e32 v50, 0
	v_mov_b32_e32 v51, v243
	v_mov_b32_e32 v52, v243
	v_mov_b32_e32 v53, v243
	v_mov_b32_e32 v60, v243
	v_mov_b32_e32 v61, v243
	v_mov_b32_e32 v34, 0
	v_mov_b32_e32 v35, v243
	v_mov_b32_e32 v36, v243
	v_mov_b32_e32 v37, v243
	v_mov_b32_e32 v38, v243
	v_mov_b32_e32 v39, v243
	v_mov_b32_e32 v40, v243
	v_mov_b32_e32 v41, v243
	v_mov_b32_e32 v42, v243
	v_mov_b32_e32 v43, v243
	v_mov_b32_e32 v44, v243
	v_mov_b32_e32 v45, v243
	v_mov_b32_e32 v46, v243
	v_mov_b32_e32 v47, v243
	v_mov_b32_e32 v48, v243
	v_mov_b32_e32 v49, v243
	v_mov_b32_e32 v16, 0
	v_mov_b32_e32 v17, v243
	v_mov_b32_e32 v24, v243
	v_mov_b32_e32 v25, v243
	v_mov_b32_e32 v26, v243
	v_mov_b32_e32 v27, v243
	v_mov_b32_e32 v28, v243
	v_mov_b32_e32 v29, v243
	v_mov_b32_e32 v30, v243
	v_mov_b32_e32 v31, v243
	v_mov_b32_e32 v0, 0
	v_mov_b32_e32 v1, v243
	v_mov_b32_e32 v2, v243
	v_mov_b32_e32 v3, v243
	v_mov_b32_e32 v4, v243
	v_mov_b32_e32 v5, v243
	v_mov_b32_e32 v6, v243
	v_mov_b32_e32 v7, v243
	v_mov_b32_e32 v8, v243
	v_mov_b32_e32 v9, v243
	v_mov_b32_e32 v10, v243
	v_mov_b32_e32 v11, v243
	v_mov_b32_e32 v12, v243
	v_mov_b32_e32 v13, v243
	v_mov_b32_e32 v14, v243
	v_mov_b32_e32 v15, v243
	s_mov_b64 s[6:7], 0x60000
	v_readfirstlane_b32 s98, v222
	v_readfirstlane_b32 s99, v223
	v_readfirstlane_b32 s100, v216
	v_readfirstlane_b32 s101, v217
	s_nop 1
	v_subrev_u32_e32 v219, s98, v222
	v_subrev_u32_e32 v216, s100, v216
	v_add_u32_e32 v217, 0x10000, v219
	s_add_u32 s98, s98, s0
	s_addc_u32 s99, s99, s1
	s_add_u32 s100, s100, s0
	s_addc_u32 s101, s101, s1
	s_add_u32 s98, s98, 0x3ca5c000
	s_addc_u32 s99, s99, 0
	s_add_u32 s100, s100, 0x398fc000
	s_addc_u32 s101, s101, 0
	s_waitcnt lgkmcnt(0)
	s_barrier
; #define SBAR() __builtin_amdgcn_sched_barrier(0)
; #define SLOAD(i, k0) do { sv0[i] = *reinterpret_cast<const bf16x8*>(&Vh[(size_t)((k0) + sr) * ldv + sc]); sv1[i] = *reinterpret_cast<const bf16x8*>(&Vh[(size_t)((k0) + 32 + sr) * ldv + sc]); \
;     _Pragma("unroll") for (int _q = 0; _q < NKP; ++_q) sk[i][_q] = *reinterpret_cast<const bf16x8*>(&Kh[(size_t)(k0) * ldk + koff[_q]]); } while (0)
; #define PVD0(...) do { if constexpr (PV_PIPE != 0) pv_d0_pipe(__VA_ARGS__); else pv_d0(__VA_ARGS__); } while (0)
; #define SLOAD(k0) do { sv0 = *reinterpret_cast<const bf16x8*>(&Vh[(size_t)((k0) + sr) * ldv + sc]); sv1 = *reinterpret_cast<const bf16x8*>(&Vh[(size_t)((k0) + 32 + sr) * ldv + sc]); \
;     _Pragma("unroll") for (int _q = 0; _q < NKP; ++_q) sk[_q] = *reinterpret_cast<const bf16x8*>(&Kh[(size_t)(k0) * ldk + koff[_q]]); } while (0)
; __device__ __forceinline__ void finishSM(f32x16& p0, f32x16& p1, float alpha, float& l_reg, bf16x8& pa0, bf16x8& pa1, bf16x8& pa2, bf16x8& pa3) {
; #pragma unroll
;     for (int r = 0; r < 16; ++r) p1[r] = __builtin_amdgcn_exp2f(p1[r]);
;     float ps = 0;
; #pragma unroll
;     for (int r = 0; r < 16; ++r) ps += p0[r];
; #pragma unroll
;     for (int r = 0; r < 16; ++r) ps += p1[r];
;     { auto rr = __builtin_amdgcn_permlane32_swap(__float_as_uint(ps), __float_as_uint(ps), false, false);
;       ps = __uint_as_float(rr[0]) + __uint_as_float(rr[1]); }
;     l_reg = l_reg * alpha + ps;
;     ...
;     PK4(p0, 0, pa0); PK4(p0, 8, pa1); PK4(p1, 0, pa2); PK4(p1, 8, pa3);
;     ...
; }
; template <int DQK, int SDEPTH, int QL, bool NOMAX, int ldq, int ldk, int ldv, int ldo> ...
;     ...
;         SBAR(); qkt<DQK, QL>(pB0, pB1, K_lds + SHM_K, qr, qpark, r32, hi);
;         finishSM(pA0, pA1, alA, l_reg, pa0, pa1, pa2, pa3); SBAR();
;         SLOAD(SO, (j + SDEPTH) * KVBLK); SBAR();
;         PVD0(o, vb0, pa0, pa1, pa2, pa3); if constexpr (NOMAX) { partialSM_nm(pB0); alB = 1.f; } else partialSM(pB0, pB1, m_reg, mnB, alB, C, thr_raw);
.LBB0_2012:
	ds_read_b128 v[82:85], v245 offset:58368
	ds_read_b128 v[106:109], v245 offset:58400
	ds_read_b128 v[102:105], v32 offset:12800
	ds_read_b128 v[98:101], v32 offset:12832
	v_exp_f32_e32 v66, v66
	v_exp_f32_e32 v67, v67
	s_waitcnt lgkmcnt(3)
	v_mfma_f32_32x32x16_bf16 v[82:97], v[82:85], v[158:161], 0
	v_exp_f32_e32 v68, v68
	v_exp_f32_e32 v69, v69
	v_exp_f32_e32 v70, v70
	v_exp_f32_e32 v71, v71
	v_exp_f32_e32 v72, v72
	v_exp_f32_e32 v73, v73
	v_exp_f32_e32 v74, v74
	s_waitcnt lgkmcnt(2)
	v_mfma_f32_32x32x16_bf16 v[82:97], v[106:109], v[154:157], v[82:97]
	ds_read_b128 v[110:113], v245 offset:58432
	ds_read_b128 v[106:109], v32 offset:12864
	v_exp_f32_e32 v75, v75
	v_exp_f32_e32 v76, v76
	v_exp_f32_e32 v77, v77
	v_exp_f32_e32 v78, v78
	v_exp_f32_e32 v79, v79
	v_exp_f32_e32 v80, v80
	s_waitcnt lgkmcnt(1)
	v_mfma_f32_32x32x16_bf16 v[82:97], v[110:113], v[150:153], v[82:97]
	ds_read_b128 v[162:165], v245 offset:58464
	ds_read_b128 v[110:113], v32 offset:12896
	v_exp_f32_e32 v81, v81
	s_waitcnt lgkmcnt(1)
	v_mfma_f32_32x32x16_bf16 v[82:97], v[162:165], v[146:149], v[82:97]
	ds_read_b128 v[166:169], v245 offset:58496
	ds_read_b128 v[162:165], v32 offset:12928
	s_waitcnt lgkmcnt(1)
	v_mfma_f32_32x32x16_bf16 v[82:97], v[166:169], v[142:145], v[82:97]
	ds_read_b128 v[170:173], v245 offset:58528
	ds_read_b128 v[166:169], v32 offset:12960
	s_waitcnt lgkmcnt(1)
	v_mfma_f32_32x32x16_bf16 v[82:97], v[170:173], v[138:141], v[82:97]
	ds_read_b128 v[174:177], v245 offset:58560
	ds_read_b128 v[170:173], v32 offset:12992
	s_waitcnt lgkmcnt(1)
	v_mfma_f32_32x32x16_bf16 v[82:97], v[174:177], v[134:137], v[82:97]
	ds_read_b128 v[178:181], v245 offset:58592
	ds_read_b128 v[174:177], v32 offset:13024
	s_waitcnt lgkmcnt(1)
	v_mfma_f32_32x32x16_bf16 v[82:97], v[178:181], v[130:133], v[82:97]
	ds_read_b128 v[182:185], v245 offset:58624
	ds_read_b128 v[178:181], v32 offset:13056
	s_waitcnt lgkmcnt(1)
	v_mfma_f32_32x32x16_bf16 v[82:97], v[182:185], v[126:129], v[82:97]
	ds_read_b128 v[186:189], v245 offset:58656
	ds_read_b128 v[182:185], v32 offset:13088
	s_waitcnt lgkmcnt(1)
	v_mfma_f32_32x32x16_bf16 v[82:97], v[186:189], v[122:125], v[82:97]
	ds_read_b128 v[194:197], v245 offset:58688
	ds_read_b128 v[186:189], v32 offset:13120
	s_waitcnt lgkmcnt(1)
	v_mfma_f32_32x32x16_bf16 v[82:97], v[194:197], v[118:121], v[82:97]
	ds_read_b128 v[224:227], v245 offset:58720
	ds_read_b128 v[194:197], v32 offset:13152
	s_waitcnt lgkmcnt(1)
	v_mfma_f32_32x32x16_bf16 v[82:97], v[224:227], v[114:117], v[82:97]
	v_add_f32_e32 v224, 0, v190
	v_add_f32_e32 v224, v209, v224
	v_add_f32_e32 v224, v191, v224
	v_add_f32_e32 v224, v208, v224
	v_add_f32_e32 v224, v192, v224
	v_add_f32_e32 v224, v207, v224
	v_add_f32_e32 v224, v193, v224
	v_add_f32_e32 v224, v206, v224
	v_add_f32_e32 v224, v198, v224
	v_add_f32_e32 v224, v205, v224
	v_add_f32_e32 v224, v199, v224
	v_add_f32_e32 v224, v204, v224
	v_add_f32_e32 v224, v200, v224
	v_add_f32_e32 v224, v202, v224
	v_add_f32_e32 v224, v201, v224
	v_add_f32_e32 v224, v203, v224
	v_add_f32_e32 v224, v66, v224
	v_add_f32_e32 v224, v67, v224
	v_add_f32_e32 v224, v68, v224
	v_add_f32_e32 v224, v69, v224
	v_add_f32_e32 v224, v70, v224
	v_add_f32_e32 v224, v71, v224
	v_add_f32_e32 v224, v72, v224
	v_add_f32_e32 v224, v73, v224
	v_add_f32_e32 v224, v74, v224
	v_add_f32_e32 v224, v75, v224
	v_add_f32_e32 v224, v76, v224
	v_add_f32_e32 v224, v77, v224
	v_add_f32_e32 v224, v78, v224
	v_add_f32_e32 v224, v79, v224
	v_add_f32_e32 v224, v80, v224
	v_add_f32_e32 v251, v81, v224
	v_cvt_pk_bf16_f32 v190, v190, v209
	v_cvt_pk_bf16_f32 v191, v191, v208
	v_cvt_pk_bf16_f32 v192, v192, v207
	v_cvt_pk_bf16_f32 v193, v193, v206
	v_cvt_pk_bf16_f32 v198, v198, v205
	v_cvt_pk_bf16_f32 v199, v199, v204
	v_cvt_pk_bf16_f32 v200, v200, v202
	v_cvt_pk_bf16_f32 v201, v201, v203
	v_cvt_pk_bf16_f32 v202, v66, v67
	v_cvt_pk_bf16_f32 v203, v68, v69
	v_cvt_pk_bf16_f32 v204, v70, v71
	v_cvt_pk_bf16_f32 v205, v72, v73
	v_cvt_pk_bf16_f32 v206, v74, v75
	v_cvt_pk_bf16_f32 v207, v76, v77
	v_cvt_pk_bf16_f32 v208, v78, v79
	v_cvt_pk_bf16_f32 v209, v80, v81
	v_mfma_f32_32x32x16_bf16 v[66:81], v[102:105], v[158:161], 0
	v_mfma_f32_32x32x16_bf16 v[66:81], v[98:101], v[154:157], v[66:81]
	v_mfma_f32_32x32x16_bf16 v[66:81], v[106:109], v[150:153], v[66:81]
	global_load_dwordx4 v[98:101], v219, s[98:99] offset:256
	global_load_dwordx4 v[102:105], v217, s[98:99] offset:256
	v_mfma_f32_32x32x16_bf16 v[66:81], v[110:113], v[146:149], v[66:81]
	global_load_dwordx4 v[106:109], v216, s[100:101] offset:256
	global_load_dwordx4 v[110:113], v216, s[100:101] offset:384
	v_mfma_f32_32x32x16_bf16 v[66:81], v[162:165], v[142:145], v[66:81]
	global_load_dwordx4 v[162:165], v216, s[100:101] offset:512
	s_add_u32 s98, s98, 0x20000
	s_addc_u32 s99, s99, 0
	s_add_u32 s100, s100, 0x30000
	s_addc_u32 s101, s101, 0
	v_mfma_f32_32x32x16_bf16 v[66:81], v[166:169], v[138:141], v[66:81]
	v_mfma_f32_32x32x16_bf16 v[66:81], v[170:173], v[134:137], v[66:81]
	v_mfma_f32_32x32x16_bf16 v[66:81], v[174:177], v[130:133], v[66:81]
	v_mfma_f32_32x32x16_bf16 v[66:81], v[178:181], v[126:129], v[66:81]
	v_mfma_f32_32x32x16_bf16 v[66:81], v[182:185], v[122:125], v[66:81]
	v_mfma_f32_32x32x16_bf16 v[66:81], v[186:189], v[118:121], v[66:81]
	s_waitcnt lgkmcnt(0)
	v_mfma_f32_32x32x16_bf16 v[66:81], v[194:197], v[114:117], v[66:81]
	ds_read_b64_tr_b16 v[166:167], v244 offset:0
	ds_read_b64_tr_b16 v[168:169], v244 offset:0x800
	ds_read_b64_tr_b16 v[170:171], v244 offset:0x1000
	ds_read_b64_tr_b16 v[172:173], v244 offset:0x1800
	ds_read_b64_tr_b16 v[174:175], v244 offset:0x2000
	ds_read_b64_tr_b16 v[176:177], v244 offset:0x2800
	ds_read_b64_tr_b16 v[178:179], v244 offset:0x3000
	ds_read_b64_tr_b16 v[180:181], v244 offset:0x3800
	s_waitcnt lgkmcnt(6)
; #define SBAR() __builtin_amdgcn_sched_barrier(0)
; #define SLOAD(i, k0) do { sv0[i] = *reinterpret_cast<const bf16x8*>(&Vh[(size_t)((k0) + sr) * ldv + sc]); sv1[i] = *reinterpret_cast<const bf16x8*>(&Vh[(size_t)((k0) + 32 + sr) * ldv + sc]); \
;     _Pragma("unroll") for (int _q = 0; _q < NKP; ++_q) sk[i][_q] = *reinterpret_cast<const bf16x8*>(&Kh[(size_t)(k0) * ldk + koff[_q]]); } while (0)
; #define SWRITE(b, i) do { *(bf16x8*)(V_lds + (b) * SHM_V + vst0) = sv0[i]; *(bf16x8*)(V_lds + (b) * SHM_V + vst1) = sv1[i]; \
;     _Pragma("unroll") for (int _q = 0; _q < NKP; ++_q) *(bf16x8*)(K_lds + (b) * SHM_K + klds[_q]) = sk[i][_q]; } while (0)
; template <int D0> __device__ __forceinline__ void pv_one(f32x16& od, int vb, bf16x8 pa0, bf16x8 pa1, bf16x8 pa2, bf16x8 pa3) {
;     const s16x4 l0 = tr_read<v_rd_off(D0, 0, 0)>(vb), h0 = tr_read<v_rd_off(D0, 0, 1)>(vb), l1 = tr_read<v_rd_off(D0, 1, 0)>(vb), h1 = tr_read<v_rd_off(D0, 1, 1)>(vb);
;     const s16x4 l2 = tr_read<v_rd_off(D0, 2, 0)>(vb), h2 = tr_read<v_rd_off(D0, 2, 1)>(vb), l3 = tr_read<v_rd_off(D0, 3, 0)>(vb), h3 = tr_read<v_rd_off(D0, 3, 1)>(vb);
;     asm volatile("s_waitcnt lgkmcnt(0)" ::: "memory"); SBAR();
;     ...
;     od = __builtin_amdgcn_mfma_f32_32x32x16_bf16(pa0, PK(l0, h0), od, 0, 0, 0);
;     od = __builtin_amdgcn_mfma_f32_32x32x16_bf16(pa1, PK(l1, h1), od, 0, 0, 0);
;     od = __builtin_amdgcn_mfma_f32_32x32x16_bf16(pa2, PK(l2, h2), od, 0, 0, 0);
;     od = __builtin_amdgcn_mfma_f32_32x32x16_bf16(pa3, PK(l3, h3), od, 0, 0, 0);
;     ...
; }
; __device__ __forceinline__ void pv_d0(f32x16* o, int vb, bf16x8 pa0, bf16x8 pa1, bf16x8 pa2, bf16x8 pa3) {
;     pv_one<0>(o[0], vb, pa0, pa1, pa2, pa3); pv_one<1>(o[1], vb, pa0, pa1, pa2, pa3); pv_one<2>(o[2], vb, pa0, pa1, pa2, pa3); pv_one<3>(o[3], vb, pa0, pa1, pa2, pa3);
; template <int DQK, int SDEPTH, int QL, bool NOMAX, int ldq, int ldk, int ldv, int ldo> ...
;     ...
;         PVD0(o, vb0, pa0, pa1, pa2, pa3); if constexpr (NOMAX) { partialSM_nm(pB0); alB = 1.f; } else partialSM(pB0, pB1, m_reg, mnB, alB, C, thr_raw);
;         __syncthreads(); SWAIT(); SWRITE(0, SE);
;         RESC(alB); __syncthreads();
;         SBAR(); qkt<DQK, QL>(pA0, pA1, K_lds, qr, qpark, r32, hi);
;         finishSM(pB0, pB1, alB, l_reg, pa0, pa1, pa2, pa3); SBAR();
;         if (SDEPTH == 1 || j + 3 < NT) SLOAD(SE, (j + 1 + SDEPTH) * KVBLK); SBAR();
	s_nop 0
	v_mfma_f32_32x32x16_bf16 v[50:65], v[190:193], v[166:169], v[50:65]
	ds_read_b64_tr_b16 v[166:167], v244 offset:0x200
	ds_read_b64_tr_b16 v[168:169], v244 offset:0xa00
	s_waitcnt lgkmcnt(6)
	v_mfma_f32_32x32x16_bf16 v[50:65], v[198:201], v[170:173], v[50:65]
	ds_read_b64_tr_b16 v[170:171], v244 offset:0x1200
	ds_read_b64_tr_b16 v[172:173], v244 offset:0x1a00
	s_waitcnt lgkmcnt(6)
	v_mfma_f32_32x32x16_bf16 v[50:65], v[202:205], v[174:177], v[50:65]
	ds_read_b64_tr_b16 v[174:175], v244 offset:0x2200
	ds_read_b64_tr_b16 v[176:177], v244 offset:0x2a00
	s_waitcnt lgkmcnt(6)
	v_mfma_f32_32x32x16_bf16 v[50:65], v[206:209], v[178:181], v[50:65]
	ds_read_b64_tr_b16 v[178:179], v244 offset:0x3200
	ds_read_b64_tr_b16 v[180:181], v244 offset:0x3a00
	s_waitcnt lgkmcnt(6)
	v_mfma_f32_32x32x16_bf16 v[34:49], v[190:193], v[166:169], v[34:49]
	ds_read_b64_tr_b16 v[166:167], v244 offset:0x400
	ds_read_b64_tr_b16 v[168:169], v244 offset:0xc00
	s_waitcnt lgkmcnt(6)
	v_mfma_f32_32x32x16_bf16 v[34:49], v[198:201], v[170:173], v[34:49]
	ds_read_b64_tr_b16 v[170:171], v244 offset:0x1400
	ds_read_b64_tr_b16 v[172:173], v244 offset:0x1c00
	s_waitcnt lgkmcnt(6)
	v_mfma_f32_32x32x16_bf16 v[34:49], v[202:205], v[174:177], v[34:49]
	ds_read_b64_tr_b16 v[174:175], v244 offset:0x2400
	ds_read_b64_tr_b16 v[176:177], v244 offset:0x2c00
	s_waitcnt lgkmcnt(6)
	v_mfma_f32_32x32x16_bf16 v[34:49], v[206:209], v[178:181], v[34:49]
	ds_read_b64_tr_b16 v[178:179], v244 offset:0x3400
	ds_read_b64_tr_b16 v[180:181], v244 offset:0x3c00
	s_waitcnt lgkmcnt(6)
	v_mfma_f32_32x32x16_bf16 v[16:31], v[190:193], v[166:169], v[16:31]
	ds_read_b64_tr_b16 v[166:167], v244 offset:0x600
	ds_read_b64_tr_b16 v[168:169], v244 offset:0xe00
	s_waitcnt lgkmcnt(6)
	v_mfma_f32_32x32x16_bf16 v[16:31], v[198:201], v[170:173], v[16:31]
	ds_read_b64_tr_b16 v[170:171], v244 offset:0x1600
	ds_read_b64_tr_b16 v[172:173], v244 offset:0x1e00
	s_waitcnt lgkmcnt(6)
	v_mfma_f32_32x32x16_bf16 v[16:31], v[202:205], v[174:177], v[16:31]
	ds_read_b64_tr_b16 v[174:175], v244 offset:0x2600
	ds_read_b64_tr_b16 v[176:177], v244 offset:0x2e00
	s_waitcnt lgkmcnt(6)
	v_mfma_f32_32x32x16_bf16 v[16:31], v[206:209], v[178:181], v[16:31]
	ds_read_b64_tr_b16 v[178:179], v244 offset:0x3600
	ds_read_b64_tr_b16 v[180:181], v244 offset:0x3e00
	s_waitcnt lgkmcnt(0)
	v_mfma_f32_32x32x16_bf16 v[0:15], v[190:193], v[166:169], v[0:15]
	s_barrier
	s_waitcnt vmcnt(0)
	s_waitcnt vmcnt(4)
	ds_write_b128 v249, v[98:101]
	s_waitcnt vmcnt(3)
	ds_write_b128 v250, v[102:105]
	s_waitcnt vmcnt(2)
	ds_write_b128 v246, v[106:109] offset:32768
	s_waitcnt vmcnt(1)
	ds_write_b128 v247, v[110:113] offset:32768
	s_waitcnt vmcnt(0)
	ds_write_b128 v248, v[162:165] offset:32768
	v_exp_f32_e32 v253, v82
	v_mfma_f32_32x32x16_bf16 v[0:15], v[198:201], v[170:173], v[0:15]
	v_exp_f32_e32 v198, v86
	v_exp_f32_e32 v199, v87
	v_exp_f32_e32 v200, v94
	v_exp_f32_e32 v201, v95
	v_exp_f32_e32 v237, v83
	v_exp_f32_e32 v238, v84
	v_exp_f32_e32 v236, v85
	v_mfma_f32_32x32x16_bf16 v[0:15], v[202:205], v[174:177], v[0:15]
	v_exp_f32_e32 v204, v93
	v_exp_f32_e32 v202, v96
	v_exp_f32_e32 v203, v97
	v_exp_f32_e32 v214, v88
	v_exp_f32_e32 v215, v89
	v_exp_f32_e32 v210, v90
	v_exp_f32_e32 v211, v91
	v_mfma_f32_32x32x16_bf16 v[0:15], v[206:209], v[178:181], v[0:15]
	v_exp_f32_e32 v212, v92
	s_waitcnt lgkmcnt(0)
	s_barrier
	ds_read_b128 v[98:101], v245 offset:45568
	ds_read_b128 v[82:85], v245 offset:32768
	ds_read_b128 v[106:109], v245 offset:32800
	ds_read_b128 v[102:105], v245 offset:45600
	v_exp_f32_e32 v66, v66
	v_exp_f32_e32 v67, v67
	s_waitcnt lgkmcnt(2)
	v_mfma_f32_32x32x16_bf16 v[82:97], v[82:85], v[158:161], 0
	v_exp_f32_e32 v68, v68
	v_exp_f32_e32 v69, v69
	v_exp_f32_e32 v70, v70
	v_exp_f32_e32 v71, v71
	v_exp_f32_e32 v72, v72
	v_exp_f32_e32 v73, v73
	v_exp_f32_e32 v74, v74
	s_waitcnt lgkmcnt(1)
	v_mfma_f32_32x32x16_bf16 v[82:97], v[106:109], v[154:157], v[82:97]
	ds_read_b128 v[110:113], v245 offset:32832
	ds_read_b128 v[106:109], v245 offset:45632
	v_exp_f32_e32 v75, v75
	v_exp_f32_e32 v76, v76
	v_exp_f32_e32 v77, v77
	v_exp_f32_e32 v78, v78
	v_exp_f32_e32 v79, v79
	v_exp_f32_e32 v80, v80
	s_waitcnt lgkmcnt(1)
	v_mfma_f32_32x32x16_bf16 v[82:97], v[110:113], v[150:153], v[82:97]
	ds_read_b128 v[162:165], v245 offset:32864
	ds_read_b128 v[110:113], v245 offset:45664
	v_exp_f32_e32 v81, v81
	s_waitcnt lgkmcnt(1)
	v_mfma_f32_32x32x16_bf16 v[82:97], v[162:165], v[146:149], v[82:97]
	ds_read_b128 v[166:169], v245 offset:32896
	ds_read_b128 v[162:165], v245 offset:45696
	s_waitcnt lgkmcnt(1)
	v_mfma_f32_32x32x16_bf16 v[82:97], v[166:169], v[142:145], v[82:97]
	ds_read_b128 v[170:173], v245 offset:32928
	ds_read_b128 v[166:169], v245 offset:45728
	s_waitcnt lgkmcnt(1)
	v_mfma_f32_32x32x16_bf16 v[82:97], v[170:173], v[138:141], v[82:97]
	ds_read_b128 v[174:177], v245 offset:32960
	ds_read_b128 v[170:173], v245 offset:45760
	s_waitcnt lgkmcnt(1)
	v_mfma_f32_32x32x16_bf16 v[82:97], v[174:177], v[134:137], v[82:97]
	ds_read_b128 v[178:181], v245 offset:32992
	ds_read_b128 v[174:177], v245 offset:45792
	s_waitcnt lgkmcnt(1)
	v_mfma_f32_32x32x16_bf16 v[82:97], v[178:181], v[130:133], v[82:97]
	ds_read_b128 v[178:181], v245 offset:33024
	ds_read_b128 v[186:189], v245 offset:45824
	s_waitcnt lgkmcnt(1)
	v_mfma_f32_32x32x16_bf16 v[82:97], v[178:181], v[126:129], v[82:97]
	ds_read_b128 v[178:181], v245 offset:33056
	ds_read_b128 v[182:185], v245 offset:45856
	s_waitcnt lgkmcnt(1)
	v_mfma_f32_32x32x16_bf16 v[82:97], v[178:181], v[122:125], v[82:97]
	ds_read_b128 v[190:193], v245 offset:33088
	ds_read_b128 v[178:181], v245 offset:45888
	s_waitcnt lgkmcnt(1)
; #define SBAR() __builtin_amdgcn_sched_barrier(0)
; #define SLOAD(i, k0) do { sv0[i] = *reinterpret_cast<const bf16x8*>(&Vh[(size_t)((k0) + sr) * ldv + sc]); sv1[i] = *reinterpret_cast<const bf16x8*>(&Vh[(size_t)((k0) + 32 + sr) * ldv + sc]); \
;     _Pragma("unroll") for (int _q = 0; _q < NKP; ++_q) sk[i][_q] = *reinterpret_cast<const bf16x8*>(&Kh[(size_t)(k0) * ldk + koff[_q]]); } while (0)
; #define PVD0(...) do { if constexpr (PV_PIPE != 0) pv_d0_pipe(__VA_ARGS__); else pv_d0(__VA_ARGS__); } while (0)
; #define SLOAD(k0) do { sv0 = *reinterpret_cast<const bf16x8*>(&Vh[(size_t)((k0) + sr) * ldv + sc]); sv1 = *reinterpret_cast<const bf16x8*>(&Vh[(size_t)((k0) + 32 + sr) * ldv + sc]); \
;     _Pragma("unroll") for (int _q = 0; _q < NKP; ++_q) sk[_q] = *reinterpret_cast<const bf16x8*>(&Kh[(size_t)(k0) * ldk + koff[_q]]); } while (0)
; __device__ __forceinline__ void finishSM(f32x16& p0, f32x16& p1, float alpha, float& l_reg, bf16x8& pa0, bf16x8& pa1, bf16x8& pa2, bf16x8& pa3) {
; #pragma unroll
;     for (int r = 0; r < 16; ++r) p1[r] = __builtin_amdgcn_exp2f(p1[r]);
;     float ps = 0;
; #pragma unroll
;     for (int r = 0; r < 16; ++r) ps += p0[r];
; #pragma unroll
;     for (int r = 0; r < 16; ++r) ps += p1[r];
;     { auto rr = __builtin_amdgcn_permlane32_swap(__float_as_uint(ps), __float_as_uint(ps), false, false);
;       ps = __uint_as_float(rr[0]) + __uint_as_float(rr[1]); }
;     l_reg = l_reg * alpha + ps;
;     ...
;     PK4(p0, 0, pa0); PK4(p0, 8, pa1); PK4(p1, 0, pa2); PK4(p1, 8, pa3);
;     ...
; }
; template <int DQK, int SDEPTH, int QL, bool NOMAX, int ldq, int ldk, int ldv, int ldo> ...
;     ...
;         SBAR(); qkt<DQK, QL>(pA0, pA1, K_lds, qr, qpark, r32, hi);
;         finishSM(pB0, pB1, alB, l_reg, pa0, pa1, pa2, pa3); SBAR();
;         if (SDEPTH == 1 || j + 3 < NT) SLOAD(SE, (j + 1 + SDEPTH) * KVBLK); SBAR();
;         PVD0(o, vb0 + SHM_V, pa0, pa1, pa2, pa3); if constexpr (NOMAX) { partialSM_nm(pA0); alA = 1.f; } else partialSM(pA0, pA1, m_reg, mnA, alA, C, thr_raw);
	v_mfma_f32_32x32x16_bf16 v[82:97], v[190:193], v[118:121], v[82:97]
	ds_read_b128 v[194:197], v245 offset:33120
	ds_read_b128 v[190:193], v245 offset:45920
	s_waitcnt lgkmcnt(1)
	v_mfma_f32_32x32x16_bf16 v[82:97], v[194:197], v[114:117], v[82:97]
	v_add_f32_e32 v194, 0, v253
	v_add_f32_e32 v194, v237, v194
	v_add_f32_e32 v194, v238, v194
	v_add_f32_e32 v194, v236, v194
	v_add_f32_e32 v194, v198, v194
	v_add_f32_e32 v194, v199, v194
	v_add_f32_e32 v194, v214, v194
	v_add_f32_e32 v194, v215, v194
	v_add_f32_e32 v194, v210, v194
	v_add_f32_e32 v194, v211, v194
	v_add_f32_e32 v194, v212, v194
	v_add_f32_e32 v194, v204, v194
	v_add_f32_e32 v194, v200, v194
	v_add_f32_e32 v194, v201, v194
	v_add_f32_e32 v194, v202, v194
	v_add_f32_e32 v194, v203, v194
	v_add_f32_e32 v194, v194, v66
	v_add_f32_e32 v194, v67, v194
	v_add_f32_e32 v194, v68, v194
	v_add_f32_e32 v194, v69, v194
	v_add_f32_e32 v194, v70, v194
	v_add_f32_e32 v194, v71, v194
	v_add_f32_e32 v194, v72, v194
	v_add_f32_e32 v194, v73, v194
	v_add_f32_e32 v194, v74, v194
	v_add_f32_e32 v194, v75, v194
	v_add_f32_e32 v194, v76, v194
	v_add_f32_e32 v194, v77, v194
	v_add_f32_e32 v194, v78, v194
	v_add_f32_e32 v194, v79, v194
	v_add_f32_e32 v194, v80, v194
	v_add_f32_e32 v252, v81, v194
	v_cvt_pk_bf16_f32 v194, v253, v237
	v_cvt_pk_bf16_f32 v195, v238, v236
	v_cvt_pk_bf16_f32 v196, v198, v199
	v_cvt_pk_bf16_f32 v197, v214, v215
	v_cvt_pk_bf16_f32 v198, v210, v211
	v_cvt_pk_bf16_f32 v199, v212, v204
	v_cvt_pk_bf16_f32 v200, v200, v201
	v_cvt_pk_bf16_f32 v201, v202, v203
	v_cvt_pk_bf16_f32 v202, v66, v67
	v_cvt_pk_bf16_f32 v203, v68, v69
	v_cvt_pk_bf16_f32 v204, v70, v71
	v_cvt_pk_bf16_f32 v205, v72, v73
	v_cvt_pk_bf16_f32 v206, v74, v75
	v_cvt_pk_bf16_f32 v207, v76, v77
	v_cvt_pk_bf16_f32 v208, v78, v79
	v_cvt_pk_bf16_f32 v209, v80, v81
	v_mfma_f32_32x32x16_bf16 v[66:81], v[98:101], v[158:161], 0
	v_mfma_f32_32x32x16_bf16 v[66:81], v[102:105], v[154:157], v[66:81]
	global_load_dwordx4 v[98:101], v219, s[98:99] offset:256
	global_load_dwordx4 v[102:105], v217, s[98:99] offset:256
	v_mfma_f32_32x32x16_bf16 v[66:81], v[106:109], v[150:153], v[66:81]
	v_mfma_f32_32x32x16_bf16 v[66:81], v[110:113], v[146:149], v[66:81]
	global_load_dwordx4 v[106:109], v216, s[100:101] offset:256
	global_load_dwordx4 v[110:113], v216, s[100:101] offset:384
	v_mfma_f32_32x32x16_bf16 v[66:81], v[162:165], v[142:145], v[66:81]
	global_load_dwordx4 v[162:165], v216, s[100:101] offset:512
	s_add_u32 s98, s98, 0x20000
	s_addc_u32 s99, s99, 0
	s_add_u32 s100, s100, 0x30000
	s_addc_u32 s101, s101, 0
	v_mfma_f32_32x32x16_bf16 v[66:81], v[166:169], v[138:141], v[66:81]
	v_mfma_f32_32x32x16_bf16 v[66:81], v[170:173], v[134:137], v[66:81]
	v_mfma_f32_32x32x16_bf16 v[66:81], v[174:177], v[130:133], v[66:81]
	v_mfma_f32_32x32x16_bf16 v[66:81], v[186:189], v[126:129], v[66:81]
	v_mfma_f32_32x32x16_bf16 v[66:81], v[182:185], v[122:125], v[66:81]
	v_mfma_f32_32x32x16_bf16 v[66:81], v[178:181], v[118:121], v[66:81]
	s_waitcnt lgkmcnt(0)
	v_mfma_f32_32x32x16_bf16 v[66:81], v[190:193], v[114:117], v[66:81]
	ds_read_b64_tr_b16 v[166:167], v242 offset:0
	ds_read_b64_tr_b16 v[168:169], v242 offset:0x800
	ds_read_b64_tr_b16 v[170:171], v242 offset:0x1000
	ds_read_b64_tr_b16 v[172:173], v242 offset:0x1800
	ds_read_b64_tr_b16 v[174:175], v242 offset:0x2000
	ds_read_b64_tr_b16 v[176:177], v242 offset:0x2800
	ds_read_b64_tr_b16 v[178:179], v242 offset:0x3000
	ds_read_b64_tr_b16 v[180:181], v242 offset:0x3800
	s_waitcnt lgkmcnt(6)
	s_nop 0
	v_mfma_f32_32x32x16_bf16 v[50:65], v[194:197], v[166:169], v[50:65]
	ds_read_b64_tr_b16 v[166:167], v242 offset:0x200
	ds_read_b64_tr_b16 v[168:169], v242 offset:0xa00
	s_waitcnt lgkmcnt(6)
	v_mfma_f32_32x32x16_bf16 v[50:65], v[198:201], v[170:173], v[50:65]
	ds_read_b64_tr_b16 v[170:171], v242 offset:0x1200
	ds_read_b64_tr_b16 v[172:173], v242 offset:0x1a00
	s_waitcnt lgkmcnt(6)
	v_mfma_f32_32x32x16_bf16 v[50:65], v[202:205], v[174:177], v[50:65]
	ds_read_b64_tr_b16 v[174:175], v242 offset:0x2200
	ds_read_b64_tr_b16 v[176:177], v242 offset:0x2a00
	s_waitcnt lgkmcnt(6)
	v_mfma_f32_32x32x16_bf16 v[50:65], v[206:209], v[178:181], v[50:65]
	ds_read_b64_tr_b16 v[178:179], v242 offset:0x3200
	ds_read_b64_tr_b16 v[180:181], v242 offset:0x3a00
	s_waitcnt lgkmcnt(6)
	v_mfma_f32_32x32x16_bf16 v[34:49], v[194:197], v[166:169], v[34:49]
	ds_read_b64_tr_b16 v[166:167], v242 offset:0x400
	ds_read_b64_tr_b16 v[168:169], v242 offset:0xc00
	s_waitcnt lgkmcnt(6)
	v_mfma_f32_32x32x16_bf16 v[34:49], v[198:201], v[170:173], v[34:49]
	ds_read_b64_tr_b16 v[170:171], v242 offset:0x1400
	ds_read_b64_tr_b16 v[172:173], v242 offset:0x1c00
	s_waitcnt lgkmcnt(6)
	v_mfma_f32_32x32x16_bf16 v[34:49], v[202:205], v[174:177], v[34:49]
	ds_read_b64_tr_b16 v[174:175], v242 offset:0x2400
	ds_read_b64_tr_b16 v[176:177], v242 offset:0x2c00
	s_waitcnt lgkmcnt(6)
	v_mfma_f32_32x32x16_bf16 v[34:49], v[206:209], v[178:181], v[34:49]
	ds_read_b64_tr_b16 v[178:179], v242 offset:0x3400
	ds_read_b64_tr_b16 v[180:181], v242 offset:0x3c00
	s_waitcnt lgkmcnt(6)
	v_mfma_f32_32x32x16_bf16 v[16:31], v[194:197], v[166:169], v[16:31]
	ds_read_b64_tr_b16 v[166:167], v242 offset:0x600
	ds_read_b64_tr_b16 v[168:169], v242 offset:0xe00
	s_waitcnt lgkmcnt(6)
	v_mfma_f32_32x32x16_bf16 v[16:31], v[198:201], v[170:173], v[16:31]
	ds_read_b64_tr_b16 v[170:171], v242 offset:0x1600
	ds_read_b64_tr_b16 v[172:173], v242 offset:0x1e00
	s_waitcnt lgkmcnt(6)
	v_mfma_f32_32x32x16_bf16 v[16:31], v[202:205], v[174:177], v[16:31]
	ds_read_b64_tr_b16 v[174:175], v242 offset:0x2600
	ds_read_b64_tr_b16 v[176:177], v242 offset:0x2e00
	s_waitcnt lgkmcnt(6)
	v_mfma_f32_32x32x16_bf16 v[16:31], v[206:209], v[178:181], v[16:31]
	ds_read_b64_tr_b16 v[178:179], v242 offset:0x3600
	ds_read_b64_tr_b16 v[180:181], v242 offset:0x3e00
	s_waitcnt lgkmcnt(0)
	v_mfma_f32_32x32x16_bf16 v[0:15], v[194:197], v[166:169], v[0:15]
	v_exp_f32_e32 v190, v82
	v_exp_f32_e32 v191, v84
	v_exp_f32_e32 v192, v86
	v_exp_f32_e32 v193, v88
	s_barrier
; #define SBAR() __builtin_amdgcn_sched_barrier(0)
; #define SWRITE(b, i) do { *(bf16x8*)(V_lds + (b) * SHM_V + vst0) = sv0[i]; *(bf16x8*)(V_lds + (b) * SHM_V + vst1) = sv1[i]; \
;     _Pragma("unroll") for (int _q = 0; _q < NKP; ++_q) *(bf16x8*)(K_lds + (b) * SHM_K + klds[_q]) = sk[i][_q]; } while (0)
; #define SWAIT() do { if constexpr (SDEPTH == 2) { if constexpr (NKP == 1) asm volatile("s_waitcnt vmcnt(3)" ::: "memory"); else if constexpr (NKP == 2) asm volatile("s_waitcnt vmcnt(4)" ::: "memory"); else asm volatile("s_waitcnt vmcnt(5)" ::: "memory"); } \
;     else asm volatile("s_waitcnt vmcnt(0)" ::: "memory"); } while (0)
; #define PVD0(...) do { if constexpr (PV_PIPE != 0) pv_d0_pipe(__VA_ARGS__); else pv_d0(__VA_ARGS__); } while (0)
; #define RESC(a) do { if constexpr (!NOMAX) if (__any((a) < 1.f)) { if (hi == 0) al_l[r32] = (a); asm volatile("s_waitcnt lgkmcnt(0)" ::: "memory"); \
;     _Pragma("unroll") for (int d = 0; d < 4; ++d) _Pragma("unroll") for (int r = 0; r < 16; ++r) o[d][r] *= al_l[crow(r, hi)]; } } while (0)
; #define SWRITE(b) do { *(bf16x8*)(V_lds + (b) * SHM_V + vst0) = sv0; *(bf16x8*)(V_lds + (b) * SHM_V + vst1) = sv1; \
;     _Pragma("unroll") for (int _q = 0; _q < NKP; ++_q) *(bf16x8*)(K_lds + (b) * SHM_K + klds[_q]) = sk[_q]; } while (0)
; #define RESC(a) do { if (__any((a) < 1.f)) { if (hi == 0) al_l[r32] = (a); asm volatile("s_waitcnt lgkmcnt(0)" ::: "memory"); \
;     _Pragma("unroll") for (int d = 0; d < 4; ++d) _Pragma("unroll") for (int r = 0; r < 16; ++r) o[d][r] *= al_l[crow(r, hi)]; } } while (0)
; template <int DQK, int SDEPTH, int QL, bool NOMAX, int ldq, int ldk, int ldv, int ldo> ...
;     ...
;         PVD0(o, vb0 + SHM_V, pa0, pa1, pa2, pa3); if constexpr (NOMAX) { partialSM_nm(pA0); alA = 1.f; } else partialSM(pA0, pA1, m_reg, mnA, alA, C, thr_raw);
;         __syncthreads(); SWAIT(); SWRITE(1, SO);
;         RESC(alA); __syncthreads();
;     }
;     SBAR(); qkt<DQK, QL>(pB0, pB1, K_lds + SHM_K, qr, qpark, r32, hi);
;     finishSM(pA0, pA1, alA, l_reg, pa0, pa1, pa2, pa3); SBAR();
;     PVD0(o, vb0, pa0, pa1, pa2, pa3); if constexpr (NOMAX) { partialSM_nm(pB0); alB = 1.f; } else partialSM(pB0, pB1, m_reg, mnB, alB, C, thr_raw);
	v_mfma_f32_32x32x16_bf16 v[0:15], v[198:201], v[170:173], v[0:15]
	v_exp_f32_e32 v198, v90
	v_exp_f32_e32 v199, v92
	v_exp_f32_e32 v200, v94
	v_exp_f32_e32 v201, v96
	s_waitcnt vmcnt(0)
	v_add_f32_e32 v82, v243, v251
	s_add_i32 s4, s4, 2
	v_mfma_f32_32x32x16_bf16 v[0:15], v[202:205], v[174:177], v[0:15]
	v_exp_f32_e32 v205, v91
	v_exp_f32_e32 v204, v93
	v_exp_f32_e32 v202, v95
	v_exp_f32_e32 v203, v97
	v_add_f32_e32 v243, v82, v252
	v_mfma_f32_32x32x16_bf16 v[0:15], v[206:209], v[178:181], v[0:15]
	v_exp_f32_e32 v209, v83
	v_exp_f32_e32 v208, v85
	v_exp_f32_e32 v207, v87
	v_exp_f32_e32 v206, v89
	s_cmp_ge_u32 s4, s51
	s_waitcnt vmcnt(4)
	ds_write_b128 v249, v[98:101] offset:16384
	s_waitcnt vmcnt(3)
	ds_write_b128 v250, v[102:105] offset:16384
	s_waitcnt vmcnt(2)
	ds_write_b128 v246, v[106:109] offset:58368
	s_waitcnt vmcnt(1)
	ds_write_b128 v247, v[110:113] offset:58368
	s_waitcnt vmcnt(0)
	ds_write_b128 v248, v[162:165] offset:58368
	s_waitcnt lgkmcnt(0)
	s_barrier
	s_cbranch_scc0 .LBB0_2012
	v_mov_b32_e32 v213, v243
	s_nop 1
	v_permlane32_swap_b32_e32 v243, v213
	v_add_f32_e32 v243, v243, v213
	ds_read_b128 v[82:85], v245 offset:58368
	ds_read_b128 v[162:165], v245 offset:58400
	v_exp_f32_e32 v67, v67
	v_exp_f32_e32 v69, v69
	s_waitcnt lgkmcnt(1)
	v_mfma_f32_32x32x16_bf16 v[98:113], v[82:85], v[158:161], 0
	ds_read_b128 v[82:85], v32 offset:12800
	ds_read_b128 v[166:169], v32 offset:12832
	s_waitcnt lgkmcnt(1)
	v_mfma_f32_32x32x16_bf16 v[82:97], v[82:85], v[158:161], 0
	v_mfma_f32_32x32x16_bf16 v[98:113], v[162:165], v[154:157], v[98:113]
	s_waitcnt lgkmcnt(0)
	v_mfma_f32_32x32x16_bf16 v[82:97], v[166:169], v[154:157], v[82:97]
	ds_read_b128 v[154:157], v245 offset:58432
	ds_read_b128 v[158:161], v32 offset:12864
	s_waitcnt lgkmcnt(1)
	v_mfma_f32_32x32x16_bf16 v[98:113], v[154:157], v[150:153], v[98:113]
	s_waitcnt lgkmcnt(0)
	v_mfma_f32_32x32x16_bf16 v[82:97], v[158:161], v[150:153], v[82:97]
	ds_read_b128 v[150:153], v245 offset:58464
	ds_read_b128 v[154:157], v32 offset:12896
	s_waitcnt lgkmcnt(1)
	v_mfma_f32_32x32x16_bf16 v[98:113], v[150:153], v[146:149], v[98:113]
	s_waitcnt lgkmcnt(0)
	v_mfma_f32_32x32x16_bf16 v[82:97], v[154:157], v[146:149], v[82:97]
	ds_read_b128 v[146:149], v245 offset:58496
	ds_read_b128 v[150:153], v32 offset:12928
	s_waitcnt lgkmcnt(1)
	v_mfma_f32_32x32x16_bf16 v[98:113], v[146:149], v[142:145], v[98:113]
	s_waitcnt lgkmcnt(0)
	v_mfma_f32_32x32x16_bf16 v[82:97], v[150:153], v[142:145], v[82:97]
	ds_read_b128 v[142:145], v245 offset:58528
	ds_read_b128 v[146:149], v32 offset:12960
	s_waitcnt lgkmcnt(1)
	v_mfma_f32_32x32x16_bf16 v[98:113], v[142:145], v[138:141], v[98:113]
	s_waitcnt lgkmcnt(0)
	v_mfma_f32_32x32x16_bf16 v[82:97], v[146:149], v[138:141], v[82:97]
	ds_read_b128 v[138:141], v245 offset:58560
	ds_read_b128 v[142:145], v32 offset:12992
	s_waitcnt lgkmcnt(1)
	v_mfma_f32_32x32x16_bf16 v[98:113], v[138:141], v[134:137], v[98:113]
	s_waitcnt lgkmcnt(0)
	v_mfma_f32_32x32x16_bf16 v[82:97], v[142:145], v[134:137], v[82:97]
	ds_read_b128 v[134:137], v245 offset:58592
	ds_read_b128 v[138:141], v32 offset:13024
	s_waitcnt lgkmcnt(1)
	v_mfma_f32_32x32x16_bf16 v[98:113], v[134:137], v[130:133], v[98:113]
	s_waitcnt lgkmcnt(0)
	v_mfma_f32_32x32x16_bf16 v[82:97], v[138:141], v[130:133], v[82:97]
	ds_read_b128 v[130:133], v245 offset:58624
	ds_read_b128 v[134:137], v32 offset:13056
	s_waitcnt lgkmcnt(1)
	v_mfma_f32_32x32x16_bf16 v[98:113], v[130:133], v[126:129], v[98:113]
	s_waitcnt lgkmcnt(0)
	v_mfma_f32_32x32x16_bf16 v[82:97], v[134:137], v[126:129], v[82:97]
	ds_read_b128 v[126:129], v245 offset:58656
	ds_read_b128 v[130:133], v32 offset:13088
	s_waitcnt lgkmcnt(1)
	v_mfma_f32_32x32x16_bf16 v[98:113], v[126:129], v[122:125], v[98:113]
	s_waitcnt lgkmcnt(0)
	v_mfma_f32_32x32x16_bf16 v[82:97], v[130:133], v[122:125], v[82:97]
	ds_read_b128 v[122:125], v245 offset:58688
	ds_read_b128 v[126:129], v32 offset:13120
	s_waitcnt lgkmcnt(1)
	v_mfma_f32_32x32x16_bf16 v[98:113], v[122:125], v[118:121], v[98:113]
	s_waitcnt lgkmcnt(0)
	v_mfma_f32_32x32x16_bf16 v[82:97], v[126:129], v[118:121], v[82:97]
	ds_read_b128 v[118:121], v245 offset:58720
	ds_read_b128 v[122:125], v32 offset:13152
	v_exp_f32_e32 v32, v66
	v_add_f32_e32 v66, 0, v190
	v_add_f32_e32 v66, v209, v66
	v_add_f32_e32 v66, v191, v66
	v_add_f32_e32 v66, v208, v66
	v_add_f32_e32 v66, v192, v66
	v_add_f32_e32 v66, v207, v66
	v_add_f32_e32 v66, v193, v66
	v_add_f32_e32 v66, v206, v66
	v_add_f32_e32 v66, v198, v66
	v_add_f32_e32 v66, v205, v66
	v_add_f32_e32 v66, v199, v66
	v_add_f32_e32 v66, v204, v66
	v_add_f32_e32 v66, v200, v66
	v_add_f32_e32 v66, v202, v66
	s_waitcnt lgkmcnt(1)
	v_mfma_f32_32x32x16_bf16 v[98:113], v[118:121], v[114:117], v[98:113]
	v_add_f32_e32 v66, v201, v66
	v_add_f32_e32 v66, v203, v66
	v_add_f32_e32 v66, v66, v32
	v_add_f32_e32 v66, v67, v66
	v_exp_f32_e32 v118, v73
	v_exp_f32_e32 v119, v74
	v_exp_f32_e32 v120, v75
	s_waitcnt lgkmcnt(0)
; #define SBAR() __builtin_amdgcn_sched_barrier(0)
; #define PVD0(...) do { if constexpr (PV_PIPE != 0) pv_d0_pipe(__VA_ARGS__); else pv_d0(__VA_ARGS__); } while (0)
; #define RESC(a) do { if constexpr (!NOMAX) if (__any((a) < 1.f)) { if (hi == 0) al_l[r32] = (a); asm volatile("s_waitcnt lgkmcnt(0)" ::: "memory"); \
;     _Pragma("unroll") for (int d = 0; d < 4; ++d) _Pragma("unroll") for (int r = 0; r < 16; ++r) o[d][r] *= al_l[crow(r, hi)]; } } while (0)
; #define RESC(a) do { if (__any((a) < 1.f)) { if (hi == 0) al_l[r32] = (a); asm volatile("s_waitcnt lgkmcnt(0)" ::: "memory"); \
;     _Pragma("unroll") for (int d = 0; d < 4; ++d) _Pragma("unroll") for (int r = 0; r < 16; ++r) o[d][r] *= al_l[crow(r, hi)]; } } while (0)
; template <int DQK, int SDEPTH, int QL, bool NOMAX, int ldq, int ldk, int ldv, int ldo> ...
;     ...
;     SBAR(); qkt<DQK, QL>(pB0, pB1, K_lds + SHM_K, qr, qpark, r32, hi);
;     finishSM(pA0, pA1, alA, l_reg, pa0, pa1, pa2, pa3); SBAR();
;     PVD0(o, vb0, pa0, pa1, pa2, pa3); if constexpr (NOMAX) { partialSM_nm(pB0); alB = 1.f; } else partialSM(pB0, pB1, m_reg, mnB, alB, C, thr_raw);
;     __syncthreads(); RESC(alB);
;     finishSM(pB0, pB1, alB, l_reg, pa0, pa1, pa2, pa3); SBAR();
	v_mfma_f32_32x32x16_bf16 v[82:97], v[122:125], v[114:117], v[82:97]
	v_exp_f32_e32 v114, v68
	v_exp_f32_e32 v115, v70
	v_exp_f32_e32 v116, v71
	v_exp_f32_e32 v117, v72
	v_add_f32_e32 v66, v114, v66
	v_add_f32_e32 v66, v69, v66
	v_add_f32_e32 v66, v115, v66
	v_add_f32_e32 v66, v116, v66
	v_exp_f32_e32 v121, v76
	v_add_f32_e32 v66, v117, v66
	v_exp_f32_e32 v122, v77
	v_add_f32_e32 v66, v118, v66
	v_exp_f32_e32 v123, v78
	v_add_f32_e32 v66, v119, v66
	v_exp_f32_e32 v124, v79
	v_add_f32_e32 v66, v120, v66
	v_exp_f32_e32 v125, v80
	v_add_f32_e32 v66, v121, v66
	v_exp_f32_e32 v126, v81
	v_add_f32_e32 v66, v122, v66
	v_add_f32_e32 v66, v123, v66
	v_add_f32_e32 v66, v124, v66
	v_add_f32_e32 v66, v125, v66
	v_add_f32_e32 v66, v126, v66
	v_mov_b32_e32 v68, v66
	s_nop 1
	v_permlane32_swap_b32_e32 v66, v68
	v_cvt_pk_bf16_f32 v70, v190, v209
	v_cvt_pk_bf16_f32 v71, v191, v208
	v_cvt_pk_bf16_f32 v72, v192, v207
	v_cvt_pk_bf16_f32 v73, v193, v206
	v_cvt_pk_bf16_f32 v74, v198, v205
	v_cvt_pk_bf16_f32 v75, v199, v204
	v_cvt_pk_bf16_f32 v76, v200, v202
	v_cvt_pk_bf16_f32 v77, v201, v203
	v_cvt_pk_bf16_f32 v78, v32, v67
	v_cvt_pk_bf16_f32 v79, v114, v69
	v_cvt_pk_bf16_f32 v80, v115, v116
	v_cvt_pk_bf16_f32 v81, v117, v118
	v_cvt_pk_bf16_f32 v114, v119, v120
	v_cvt_pk_bf16_f32 v115, v121, v122
	v_cvt_pk_bf16_f32 v116, v123, v124
	v_cvt_pk_bf16_f32 v117, v125, v126
	ds_read_b64_tr_b16 v[118:119], v244 offset:0
	ds_read_b64_tr_b16 v[120:121], v244 offset:0x800
	ds_read_b64_tr_b16 v[122:123], v244 offset:0x1000
	ds_read_b64_tr_b16 v[124:125], v244 offset:0x1800
	ds_read_b64_tr_b16 v[126:127], v244 offset:0x2000
	ds_read_b64_tr_b16 v[128:129], v244 offset:0x2800
	ds_read_b64_tr_b16 v[130:131], v244 offset:0x3000
	ds_read_b64_tr_b16 v[132:133], v244 offset:0x3800
	s_waitcnt lgkmcnt(0)
	s_nop 0
	v_mfma_f32_32x32x16_bf16 v[50:65], v[70:73], v[118:121], v[50:65]
	ds_read_b64_tr_b16 v[118:119], v244 offset:0x200
	ds_read_b64_tr_b16 v[120:121], v244 offset:0xa00
	v_mfma_f32_32x32x16_bf16 v[50:65], v[74:77], v[122:125], v[50:65]
	ds_read_b64_tr_b16 v[122:123], v244 offset:0x1200
	ds_read_b64_tr_b16 v[124:125], v244 offset:0x1a00
	v_mfma_f32_32x32x16_bf16 v[50:65], v[78:81], v[126:129], v[50:65]
	ds_read_b64_tr_b16 v[126:127], v244 offset:0x2200
	ds_read_b64_tr_b16 v[128:129], v244 offset:0x2a00
	v_mfma_f32_32x32x16_bf16 v[50:65], v[114:117], v[130:133], v[50:65]
	ds_read_b64_tr_b16 v[130:131], v244 offset:0x3200
	ds_read_b64_tr_b16 v[132:133], v244 offset:0x3a00
	s_waitcnt lgkmcnt(0)
	v_mfma_f32_32x32x16_bf16 v[34:49], v[70:73], v[118:121], v[34:49]
	ds_read_b64_tr_b16 v[118:119], v244 offset:0x400
	ds_read_b64_tr_b16 v[120:121], v244 offset:0xc00
	v_mfma_f32_32x32x16_bf16 v[34:49], v[74:77], v[122:125], v[34:49]
	ds_read_b64_tr_b16 v[122:123], v244 offset:0x1400
	ds_read_b64_tr_b16 v[124:125], v244 offset:0x1c00
	v_mfma_f32_32x32x16_bf16 v[34:49], v[78:81], v[126:129], v[34:49]
	ds_read_b64_tr_b16 v[126:127], v244 offset:0x2400
	ds_read_b64_tr_b16 v[128:129], v244 offset:0x2c00
	v_mfma_f32_32x32x16_bf16 v[34:49], v[114:117], v[130:133], v[34:49]
	ds_read_b64_tr_b16 v[130:131], v244 offset:0x3400
	ds_read_b64_tr_b16 v[132:133], v244 offset:0x3c00
	s_waitcnt lgkmcnt(0)
	v_mfma_f32_32x32x16_bf16 v[16:31], v[70:73], v[118:121], v[16:31]
	ds_read_b64_tr_b16 v[118:119], v244 offset:0x600
	ds_read_b64_tr_b16 v[120:121], v244 offset:0xe00
	v_mfma_f32_32x32x16_bf16 v[16:31], v[74:77], v[122:125], v[16:31]
	ds_read_b64_tr_b16 v[122:123], v244 offset:0x1600
	ds_read_b64_tr_b16 v[124:125], v244 offset:0x1e00
	v_mfma_f32_32x32x16_bf16 v[16:31], v[78:81], v[126:129], v[16:31]
	ds_read_b64_tr_b16 v[126:127], v244 offset:0x2600
	ds_read_b64_tr_b16 v[128:129], v244 offset:0x2e00
	v_mfma_f32_32x32x16_bf16 v[16:31], v[114:117], v[130:133], v[16:31]
	ds_read_b64_tr_b16 v[130:131], v244 offset:0x3600
	ds_read_b64_tr_b16 v[132:133], v244 offset:0x3e00
	s_waitcnt lgkmcnt(0)
	v_mfma_f32_32x32x16_bf16 v[0:15], v[70:73], v[118:121], v[0:15]
	v_exp_f32_e32 v32, v98
	v_exp_f32_e32 v70, v99
	v_exp_f32_e32 v71, v100
	v_exp_f32_e32 v72, v101
	v_exp_f32_e32 v73, v102
	v_add_f32_e32 v67, 0, v32
	v_add_f32_e32 v67, v70, v67
	v_mfma_f32_32x32x16_bf16 v[0:15], v[74:77], v[122:125], v[0:15]
	v_exp_f32_e32 v74, v103
	v_exp_f32_e32 v75, v104
	v_add_f32_e32 v67, v71, v67
	v_exp_f32_e32 v76, v105
	v_add_f32_e32 v67, v72, v67
	v_exp_f32_e32 v77, v106
	v_add_f32_e32 v67, v73, v67
	v_mfma_f32_32x32x16_bf16 v[0:15], v[78:81], v[126:129], v[0:15]
	v_exp_f32_e32 v78, v107
	v_add_f32_e32 v67, v74, v67
	v_exp_f32_e32 v79, v108
	v_add_f32_e32 v67, v75, v67
	v_exp_f32_e32 v80, v109
	v_add_f32_e32 v67, v76, v67
	v_exp_f32_e32 v81, v110
	v_add_f32_e32 v67, v77, v67
	v_exp_f32_e32 v98, v111
	v_add_f32_e32 v67, v78, v67
	v_exp_f32_e32 v99, v112
	v_add_f32_e32 v67, v79, v67
	v_exp_f32_e32 v100, v113
	v_add_f32_e32 v67, v80, v67
	v_exp_f32_e32 v82, v82
	v_add_f32_e32 v67, v81, v67
	v_exp_f32_e32 v83, v83
	v_add_f32_e32 v67, v98, v67
	v_exp_f32_e32 v84, v84
	v_add_f32_e32 v67, v99, v67
	v_exp_f32_e32 v85, v85
	v_add_f32_e32 v67, v100, v67
	v_exp_f32_e32 v86, v86
	v_add_f32_e32 v67, v82, v67
	v_exp_f32_e32 v87, v87
	v_add_f32_e32 v67, v83, v67
	v_exp_f32_e32 v88, v88
	v_add_f32_e32 v67, v84, v67
	v_exp_f32_e32 v89, v89
	v_add_f32_e32 v67, v85, v67
	v_exp_f32_e32 v90, v90
	v_add_f32_e32 v67, v86, v67
	v_exp_f32_e32 v91, v91
	v_add_f32_e32 v67, v87, v67
	v_exp_f32_e32 v92, v92
	v_add_f32_e32 v67, v88, v67
	v_exp_f32_e32 v93, v93
	v_add_f32_e32 v67, v89, v67
	v_exp_f32_e32 v94, v94
	v_add_f32_e32 v67, v90, v67
	v_exp_f32_e32 v95, v95
	v_add_f32_e32 v67, v91, v67
	v_mfma_f32_32x32x16_bf16 v[0:15], v[114:117], v[130:133], v[0:15]
	v_exp_f32_e32 v96, v96
	v_add_f32_e32 v67, v92, v67
	v_exp_f32_e32 v97, v97
	v_add_f32_e32 v67, v93, v67
	v_add_f32_e32 v67, v94, v67
	v_add_f32_e32 v67, v95, v67
	v_add_f32_e32 v67, v96, v67
	v_add_f32_e32 v67, v97, v67
	v_mov_b32_e32 v69, v67
	s_barrier
; template <int M> __device__ __forceinline__ float swz_xor(float v) { return __int_as_float(__builtin_amdgcn_ds_swizzle(__float_as_int(v), (M << 10) | 0x1f)); }
; #define SBAR() __builtin_amdgcn_sched_barrier(0)
; __device__ __forceinline__ int crow(int r, int hi) { return (r & 3) + 8 * (r >> 2) + 4 * hi; }
; __device__ __forceinline__ unsigned cvtpk(float lo, float hi) { unsigned r; asm volatile("v_cvt_pk_bf16_f32 %0, %1, %2" : "=v"(r) : "v"(lo), "v"(hi)); return r; }
; #define PVD0(...) do { if constexpr (PV_PIPE != 0) pv_d0_pipe(__VA_ARGS__); else pv_d0(__VA_ARGS__); } while (0)
; template <int DQK, int SDEPTH, int QL, bool NOMAX, int ldq, int ldk, int ldv, int ldo> ...
;     ...
;     finishSM(pB0, pB1, alB, l_reg, pa0, pa1, pa2, pa3); SBAR();
;     PVD0(o, vb0 + SHM_V, pa0, pa1, pa2, pa3);
;     if (ATT_PRIO) __builtin_amdgcn_s_setprio(0);
;     if (hi == 0) li_l[r32] = l_reg; asm volatile("s_waitcnt lgkmcnt(0)" ::: "memory");
;     float rli[16];
; #pragma unroll
;     for (int r = 0; r < 16; ++r) rli[r] = __builtin_amdgcn_rcpf(li_l[crow(r, hi)]);
;     bf16_t* Ow = Ob + (size_t)(wid * QBLK) * ldo + (r32 & ~1);
;     const bool odd = (r32 & 1) != 0;
; #pragma unroll
;     for (int r = 0; r < 16; r += 2) { const int orow = crow(r, hi) + (odd ? 1 : 0);
; #pragma unroll
;         for (int d0 = 0; d0 < 4; ++d0) { const float a = o[d0][r] * rli[r], b = o[d0][r + 1] * rli[r + 1];
;             const float recv = swz_xor<1>(odd ? a : b);
;             const unsigned w = odd ? cvtpk(recv, b) : cvtpk(a, recv);
;             *(unsigned*)(Ow + (size_t)orow * ldo + d0 * 32) = w; } }
	s_nop 0
	v_permlane32_swap_b32_e32 v67, v69
	v_cvt_pk_bf16_f32 v70, v32, v70
	v_cvt_pk_bf16_f32 v71, v71, v72
	v_cvt_pk_bf16_f32 v72, v73, v74
	v_cvt_pk_bf16_f32 v73, v75, v76
	v_cvt_pk_bf16_f32 v74, v77, v78
	v_cvt_pk_bf16_f32 v75, v79, v80
	v_cvt_pk_bf16_f32 v76, v81, v98
	v_cvt_pk_bf16_f32 v77, v99, v100
	v_cvt_pk_bf16_f32 v78, v82, v83
	v_cvt_pk_bf16_f32 v79, v84, v85
	v_cvt_pk_bf16_f32 v80, v86, v87
	v_cvt_pk_bf16_f32 v81, v88, v89
	v_cvt_pk_bf16_f32 v82, v90, v91
	v_cvt_pk_bf16_f32 v83, v92, v93
	v_cvt_pk_bf16_f32 v84, v94, v95
	v_cvt_pk_bf16_f32 v85, v96, v97
	ds_read_b64_tr_b16 v[86:87], v242 offset:0
	ds_read_b64_tr_b16 v[88:89], v242 offset:0x800
	ds_read_b64_tr_b16 v[90:91], v242 offset:0x1000
	ds_read_b64_tr_b16 v[92:93], v242 offset:0x1800
	ds_read_b64_tr_b16 v[94:95], v242 offset:0x2000
	ds_read_b64_tr_b16 v[96:97], v242 offset:0x2800
	ds_read_b64_tr_b16 v[98:99], v242 offset:0x3000
	ds_read_b64_tr_b16 v[100:101], v242 offset:0x3800
	s_waitcnt lgkmcnt(0)
	s_nop 0
	v_mfma_f32_32x32x16_bf16 v[50:65], v[70:73], v[86:89], v[50:65]
	ds_read_b64_tr_b16 v[86:87], v242 offset:0x200
	ds_read_b64_tr_b16 v[88:89], v242 offset:0xa00
	v_mfma_f32_32x32x16_bf16 v[50:65], v[74:77], v[90:93], v[50:65]
	ds_read_b64_tr_b16 v[90:91], v242 offset:0x1200
	ds_read_b64_tr_b16 v[92:93], v242 offset:0x1a00
	v_mfma_f32_32x32x16_bf16 v[50:65], v[78:81], v[94:97], v[50:65]
	ds_read_b64_tr_b16 v[94:95], v242 offset:0x2200
	ds_read_b64_tr_b16 v[96:97], v242 offset:0x2a00
	v_mfma_f32_32x32x16_bf16 v[50:65], v[82:85], v[98:101], v[50:65]
	ds_read_b64_tr_b16 v[98:99], v242 offset:0x3200
	ds_read_b64_tr_b16 v[100:101], v242 offset:0x3a00
	s_waitcnt lgkmcnt(0)
	v_mfma_f32_32x32x16_bf16 v[34:49], v[70:73], v[86:89], v[34:49]
	ds_read_b64_tr_b16 v[86:87], v242 offset:0x400
	ds_read_b64_tr_b16 v[88:89], v242 offset:0xc00
	v_mfma_f32_32x32x16_bf16 v[34:49], v[74:77], v[90:93], v[34:49]
	ds_read_b64_tr_b16 v[90:91], v242 offset:0x1400
	ds_read_b64_tr_b16 v[92:93], v242 offset:0x1c00
	v_mfma_f32_32x32x16_bf16 v[34:49], v[78:81], v[94:97], v[34:49]
	ds_read_b64_tr_b16 v[94:95], v242 offset:0x2400
	ds_read_b64_tr_b16 v[96:97], v242 offset:0x2c00
	v_mfma_f32_32x32x16_bf16 v[34:49], v[82:85], v[98:101], v[34:49]
	ds_read_b64_tr_b16 v[98:99], v242 offset:0x3400
	ds_read_b64_tr_b16 v[100:101], v242 offset:0x3c00
	s_waitcnt lgkmcnt(0)
	v_mfma_f32_32x32x16_bf16 v[16:31], v[70:73], v[86:89], v[16:31]
	ds_read_b64_tr_b16 v[86:87], v242 offset:0x600
	ds_read_b64_tr_b16 v[88:89], v242 offset:0xe00
	v_mfma_f32_32x32x16_bf16 v[16:31], v[74:77], v[90:93], v[16:31]
	ds_read_b64_tr_b16 v[90:91], v242 offset:0x1600
	ds_read_b64_tr_b16 v[92:93], v242 offset:0x1e00
	v_mfma_f32_32x32x16_bf16 v[16:31], v[78:81], v[94:97], v[16:31]
	ds_read_b64_tr_b16 v[94:95], v242 offset:0x2600
	ds_read_b64_tr_b16 v[96:97], v242 offset:0x2e00
	v_mfma_f32_32x32x16_bf16 v[16:31], v[82:85], v[98:101], v[16:31]
	ds_read_b64_tr_b16 v[98:99], v242 offset:0x3600
	ds_read_b64_tr_b16 v[100:101], v242 offset:0x3e00
	s_waitcnt lgkmcnt(0)
	v_mfma_f32_32x32x16_bf16 v[0:15], v[70:73], v[86:89], v[0:15]
	v_mfma_f32_32x32x16_bf16 v[0:15], v[74:77], v[90:93], v[0:15]
	v_mfma_f32_32x32x16_bf16 v[0:15], v[78:81], v[94:97], v[0:15]
	v_mfma_f32_32x32x16_bf16 v[0:15], v[82:85], v[98:101], v[0:15]
	s_setprio 0
	v_cmp_gt_u32_e32 vcc, 32, v241
	s_and_saveexec_b64 s[4:5], vcc
	v_pk_add_f32 v[66:67], v[66:67], v[68:69]
	v_lshl_add_u32 v32, v240, 2, s48
	v_add_f32_e32 v66, v243, v66
	v_add_f32_e32 v66, v66, v67
	ds_write_b32 v32, v66
	s_or_b64 exec, exec, s[4:5]
	s_waitcnt lgkmcnt(0)
	v_lshl_add_u32 v32, v233, 4, s48
	ds_read_b128 v[78:81], v32
	ds_read_b128 v[74:77], v32 offset:32
	v_and_b32_e32 v82, 1, v232
	ds_read_b128 v[70:73], v32 offset:64
	ds_read_b128 v[66:69], v32 offset:96
	v_cmp_eq_u32_e64 s[6:7], 0, v82
	s_waitcnt lgkmcnt(3)
	v_rcp_f32_e32 v78, v78
	v_rcp_f32_e32 v79, v79
	v_cmp_eq_u32_e64 s[4:5], 1, v82
	v_mul_f32_e32 v32, v50, v78
	v_mul_f32_e32 v51, v51, v79
	v_cndmask_b32_e64 v50, v32, v51, s[6:7]
	ds_swizzle_b32 v50, v50 offset:swizzle(SWAP,1)
	s_mov_b64 s[14:15], exec
	s_and_b64 s[20:21], s[14:15], s[4:5]
	s_xor_b64 s[14:15], s[20:21], s[14:15]
	v_mov_b64_e32 v[244:245], 0x210
	v_mov_b64_e32 v[246:247], 0x20f
	s_mov_b64 exec, s[20:21]
	s_cbranch_execz .LBB0_2017
	s_waitcnt lgkmcnt(0)
	v_cvt_pk_bf16_f32 v83, v50, v51

; __device__ __forceinline__ int v_rd_base(int lane) { return ((lane & 3) << 3) | (((lane >> 2) & 3) << 6) | (((lane >> 4) & 1) << 5) | (((lane >> 5) & 1) << 8); }
; #define SLOAD(i, k0) do { sv0[i] = *reinterpret_cast<const bf16x8*>(&Vh[(size_t)((k0) + sr) * ldv + sc]); sv1[i] = *reinterpret_cast<const bf16x8*>(&Vh[(size_t)((k0) + 32 + sr) * ldv + sc]); \
;     _Pragma("unroll") for (int _q = 0; _q < NKP; ++_q) sk[i][_q] = *reinterpret_cast<const bf16x8*>(&Kh[(size_t)(k0) * ldk + koff[_q]]); } while (0)
; #define SWRITE(b, i) do { *(bf16x8*)(V_lds + (b) * SHM_V + vst0) = sv0[i]; *(bf16x8*)(V_lds + (b) * SHM_V + vst1) = sv1[i]; \
;     _Pragma("unroll") for (int _q = 0; _q < NKP; ++_q) *(bf16x8*)(K_lds + (b) * SHM_K + klds[_q]) = sk[i][_q]; } while (0)
; #define SLOAD(k0) do { sv0 = *reinterpret_cast<const bf16x8*>(&Vh[(size_t)((k0) + sr) * ldv + sc]); sv1 = *reinterpret_cast<const bf16x8*>(&Vh[(size_t)((k0) + 32 + sr) * ldv + sc]); \
;     _Pragma("unroll") for (int _q = 0; _q < NKP; ++_q) sk[_q] = *reinterpret_cast<const bf16x8*>(&Kh[(size_t)(k0) * ldk + koff[_q]]); } while (0)
; #define SWRITE(b) do { *(bf16x8*)(V_lds + (b) * SHM_V + vst0) = sv0; *(bf16x8*)(V_lds + (b) * SHM_V + vst1) = sv1; \
;     _Pragma("unroll") for (int _q = 0; _q < NKP; ++_q) *(bf16x8*)(K_lds + (b) * SHM_K + klds[_q]) = sk[_q]; } while (0)
; __device__ __forceinline__ int v_st(int k, int c) { const int kk = (k & ~0xC) | ((k & 4) << 1) | ((k & 8) >> 1); return ((kk >> 3) * 4 + (c >> 5)) * 512 + ((kk & 7) * 32 + (c & 31)) * 2; }
; template <int DQK, int SDEPTH, int QL, bool NOMAX, int ldq, int ldk, int ldv, int ldo> ...
;     ...
;     const int sr = tid >> 4, sc = (tid & 15) * 8, vst0 = v_st(sr, sc), vst1 = v_st(32 + sr, sc);
;     int koff[NKP], klds[NKP];
; #pragma unroll
;     for (int i = 0; i < NKP; ++i) { const int row = tid >> 3, c8 = (tid & 7) + 8 * i; koff[i] = row * ldk + c8 * 8; klds[i] = row * RS + c8 * 16; }
;     const int vb0 = (int)(uintptr_t)V_lds + v_rd_base(lane);
;     bf16x8 sv0[SDEPTH], sv1[SDEPTH], sk[SDEPTH][NKP];
;     ...
;     f32x16 pA0, pA1, pB0, pB1; float mnA, mnB, alA, alB; bf16x8 pa0, pa1, pa2, pa3; const int NT = seq / KVBLK;
;     if (ATT_PRIO && wid >= 4) __builtin_amdgcn_s_setprio(1);
;     constexpr int SE = 0, SO = SDEPTH - 1;
;     SLOAD(SE, 0); asm volatile("s_waitcnt vmcnt(0)" ::: "memory"); SWRITE(0, SE); __syncthreads();
.LBB0_2297:
	v_add_u32_e32 v0, s39, v162
	v_ashrrev_i32_e32 v14, 4, v0
	v_lshlrev_b32_e32 v18, 3, v162
	v_ashrrev_i32_e32 v15, 31, v14
	v_and_b32_e32 v1, 0x78, v18
	v_add_u32_e32 v16, 32, v14
	v_lshlrev_b64 v[82:83], 11, v[14:15]
	v_and_b32_e32 v20, 7, v162
	v_lshl_add_u64 v[2:3], s[26:27], 0, v[82:83]
	v_lshlrev_b32_e32 v4, 1, v1
	v_mov_b32_e32 v5, v33
	v_ashrrev_i32_e32 v17, 31, v16
	v_ashrrev_i32_e32 v19, 3, v0
	v_lshlrev_b32_e32 v0, 3, v20
	v_lshl_add_u64 v[54:55], v[2:3], 0, v[4:5]
	v_lshlrev_b64 v[2:3], 11, v[16:17]
	v_lshl_or_b32 v0, v19, 10, v0
	v_lshl_add_u64 v[2:3], s[26:27], 0, v[2:3]
	v_lshl_add_u64 v[6:7], v[2:3], 0, v[4:5]
	v_ashrrev_i32_e32 v1, 31, v0
	global_load_dwordx4 v[2:5], v[54:55], off
	s_nop 0
	global_load_dwordx4 v[6:9], v[6:7], off
	v_lshlrev_b64 v[30:31], 1, v[0:1]
	v_lshl_add_u64 v[56:57], s[24:25], 0, v[30:31]
	global_load_dwordx4 v[10:13], v[56:57], off
	s_movk_i32 s4, 0x90
	v_mad_u32_u24 v15, v164, s4, 0
	v_bfe_u32 v17, v18, 5, 2
	v_add_u32_e32 v168, v15, v32
	v_and_b32_e32 v15, 0xfffff0, v14
	v_mov_b32_e32 v18, v14
	v_mov_b32_e32 v21, v14
	v_and_b32_e32 v14, 3, v14
	v_mul_lo_u32 v19, v19, s4
	v_and_or_b32 v15, v18, 8, v15
	v_and_or_b32 v14, v21, 4, v14
	v_and_b32_e32 v18, 0xfffff0, v16
	v_lshl_add_u32 v19, v20, 4, v19
	v_lshrrev_b32_e32 v15, 1, v15
	v_lshlrev_b32_e32 v20, 6, v14
	v_and_or_b32 v14, v16, 8, v18
	v_lshlrev_b32_e32 v1, 4, v162
	v_or_b32_e32 v15, v15, v17
	v_lshrrev_b32_e32 v14, 1, v14
	v_and_b32_e32 v1, 48, v1
	v_add_u32_e32 v170, 0, v19
	v_lshlrev_b32_e32 v18, 9, v15
	v_or_b32_e32 v19, v14, v17
	v_or3_b32 v18, v18, v20, v1
	v_lshlrev_b32_e32 v19, 9, v19
	v_or3_b32 v1, v19, v20, v1
	v_add_u32_e32 v171, 0, v18
	s_waitcnt vmcnt(0)
	v_add_u32_e32 v172, 0, v1
	v_add_co_u32_e32 v14, vcc, s66, v54
	s_mov_b32 s4, 0x30000
	s_nop 0
	v_addc_co_u32_e32 v15, vcc, 0, v55, vcc
	v_add_co_u32_e32 v16, vcc, s4, v54
	v_and_b32_e32 v46, 15, v162
	s_nop 0
	v_addc_co_u32_e32 v17, vcc, 0, v55, vcc
	s_cmp_lg_u32 0, -1
	v_lshlrev_b32_e32 v32, 4, v46
	s_cselect_b32 s14, 0, 0
	s_add_i32 s7, s53, -3
	s_add_i32 s15, s14, 0x4000
	s_add_u32 s4, s0, s20
	s_addc_u32 s5, s1, s21
	s_mov_b32 s21, 0x40000
	v_and_b32_e32 v165, 63, v162
	s_mov_b32 s20, 0x50000
	v_lshlrev_b32_e32 v51, 4, v165
	v_lshlrev_b32_e32 v50, 3, v165
	v_lshlrev_b32_e32 v52, 1, v165
	v_and_b32_e32 v51, 0xc0, v51
	v_and_b32_e32 v52, 32, v52
	v_mov_b32_e32 v166, 0
	s_mov_b32 s6, 1
	v_mov_b32_e32 v0, 0
	v_mov_b32_e32 v1, v166
	v_lshl_add_u64 v[154:155], s[4:5], 0, v[30:31]
	v_mov_b32_e32 v30, v166
	v_mov_b32_e32 v31, v166
	s_waitcnt vmcnt(2)
	ds_write_b128 v171, v[2:5]
	s_waitcnt vmcnt(1)
	ds_write_b128 v172, v[6:9]
	s_waitcnt vmcnt(0)
	ds_write_b128 v170, v[10:13] offset:32768
	s_waitcnt lgkmcnt(0)
	s_barrier
; __device__ __forceinline__ int v_rd_base(int lane) { return ((lane & 3) << 3) | (((lane >> 2) & 3) << 6) | (((lane >> 4) & 1) << 5) | (((lane >> 5) & 1) << 8); }
; #define SLOAD(i, k0) do { sv0[i] = *reinterpret_cast<const bf16x8*>(&Vh[(size_t)((k0) + sr) * ldv + sc]); sv1[i] = *reinterpret_cast<const bf16x8*>(&Vh[(size_t)((k0) + 32 + sr) * ldv + sc]); \
;     _Pragma("unroll") for (int _q = 0; _q < NKP; ++_q) sk[i][_q] = *reinterpret_cast<const bf16x8*>(&Kh[(size_t)(k0) * ldk + koff[_q]]); } while (0)
; #define SWRITE(b, i) do { *(bf16x8*)(V_lds + (b) * SHM_V + vst0) = sv0[i]; *(bf16x8*)(V_lds + (b) * SHM_V + vst1) = sv1[i]; \
;     _Pragma("unroll") for (int _q = 0; _q < NKP; ++_q) *(bf16x8*)(K_lds + (b) * SHM_K + klds[_q]) = sk[i][_q]; } while (0)
; #define SWAIT() do { if constexpr (SDEPTH == 2) { if constexpr (NKP == 1) asm volatile("s_waitcnt vmcnt(3)" ::: "memory"); else if constexpr (NKP == 2) asm volatile("s_waitcnt vmcnt(4)" ::: "memory"); else asm volatile("s_waitcnt vmcnt(5)" ::: "memory"); } \
;     else asm volatile("s_waitcnt vmcnt(0)" ::: "memory"); } while (0)
; #define SLOAD(k0) do { sv0 = *reinterpret_cast<const bf16x8*>(&Vh[(size_t)((k0) + sr) * ldv + sc]); sv1 = *reinterpret_cast<const bf16x8*>(&Vh[(size_t)((k0) + 32 + sr) * ldv + sc]); \
;     _Pragma("unroll") for (int _q = 0; _q < NKP; ++_q) sk[_q] = *reinterpret_cast<const bf16x8*>(&Kh[(size_t)(k0) * ldk + koff[_q]]); } while (0)
; template <int DQK, int SDEPTH, int QL, bool NOMAX, int ldq, int ldk, int ldv, int ldo> ...
;     ...
;     const int vb0 = (int)(uintptr_t)V_lds + v_rd_base(lane);
;     bf16x8 sv0[SDEPTH], sv1[SDEPTH], sk[SDEPTH][NKP];
;     ...
;     f32x16 pA0, pA1, pB0, pB1; float mnA, mnB, alA, alB; bf16x8 pa0, pa1, pa2, pa3; const int NT = seq / KVBLK;
;     if (ATT_PRIO && wid >= 4) __builtin_amdgcn_s_setprio(1);
;     constexpr int SE = 0, SO = SDEPTH - 1;
;     SLOAD(SE, 0); asm volatile("s_waitcnt vmcnt(0)" ::: "memory"); SWRITE(0, SE); __syncthreads();
;     qkt<DQK, QL>(pA0, pA1, K_lds, qr, qpark, r32, hi); if constexpr (NOMAX) { partialSM_nm(pA0); alA = 1.f; } else partialSM(pA0, pA1, m_reg, mnA, alA, C, thr_raw);
;     SLOAD(SO, KVBLK); if constexpr (SDEPTH == 2) { if (2 < NT) SLOAD(SE, 2 * KVBLK); }
;     SWAIT(); SWRITE(1, SO); __syncthreads();
	ds_read_b128 v[2:5], v168 offset:32768
	ds_read_b128 v[6:9], v168 offset:37376
	v_add_co_u32_e32 v10, vcc, s66, v56
	s_waitcnt lgkmcnt(0)
	v_mfma_f32_32x32x16_bf16 v[66:81], v[6:9], v[126:129], 0
	v_addc_co_u32_e32 v11, vcc, 0, v57, vcc
	global_load_dwordx4 v[34:37], v[14:15], off
	global_load_dwordx4 v[38:41], v[16:17], off
	global_load_dwordx4 v[42:45], v[10:11], off
	ds_read_b128 v[10:13], v168 offset:32800
	ds_read_b128 v[58:61], v168 offset:32832
	ds_read_b128 v[46:49], v168 offset:37408
	v_mov_b32_e32 v6, v166
	v_mfma_f32_32x32x16_bf16 v[14:29], v[2:5], v[126:129], 0
	v_mov_b32_e32 v2, v166
	v_mov_b32_e32 v3, v166
	v_mov_b32_e32 v4, v166
	v_mov_b32_e32 v5, v166
	v_mov_b32_e32 v7, v166
	v_mov_b32_e32 v8, v166
	v_mov_b32_e32 v9, v166
	s_waitcnt lgkmcnt(2)
	v_mfma_f32_32x32x16_bf16 v[14:29], v[10:13], v[122:125], v[14:29]
	v_mov_b32_e32 v10, v166
	v_mov_b32_e32 v11, v166
	v_mov_b32_e32 v12, v166
	v_mov_b32_e32 v13, v166
	s_waitcnt lgkmcnt(1)
	v_mfma_f32_32x32x16_bf16 v[14:29], v[58:61], v[118:121], v[14:29]
	v_add_co_u32_e32 v60, vcc, s21, v54
	v_lshl_add_u64 v[58:59], v[82:83], 0, s[22:23]
	s_nop 0
	v_addc_co_u32_e32 v61, vcc, 0, v55, vcc
	v_add_co_u32_e32 v54, vcc, s20, v54
	s_waitcnt lgkmcnt(0)
	v_mfma_f32_32x32x16_bf16 v[66:81], v[46:49], v[122:125], v[66:81]
	v_addc_co_u32_e32 v55, vcc, 0, v55, vcc
	v_and_b32_e32 v46, 0x100, v50
	v_and_or_b32 v47, v50, 24, v51
	v_add_co_u32_e32 v56, vcc, s21, v56
	v_or3_b32 v84, v47, v52, v46
	ds_read_b128 v[62:65], v168 offset:37440
	ds_read_b128 v[50:53], v168 offset:32864
	ds_read_b128 v[46:49], v168 offset:37472
	v_addc_co_u32_e32 v57, vcc, 0, v57, vcc
	global_load_dwordx4 v[130:133], v[60:61], off
	global_load_dwordx4 v[134:137], v[54:55], off
	global_load_dwordx4 v[138:141], v[56:57], off
	s_waitcnt lgkmcnt(2)
	v_mfma_f32_32x32x16_bf16 v[66:81], v[62:65], v[118:121], v[66:81]
	s_waitcnt vmcnt(3)
	v_add_u32_e32 v169, s14, v84
	v_add_u32_e32 v167, s15, v84
	v_mov_b32_e32 v54, v166
	v_mov_b32_e32 v55, v166
	v_mov_b32_e32 v56, v166
	v_mov_b32_e32 v57, v166
	s_waitcnt lgkmcnt(1)
	v_mfma_f32_32x32x16_bf16 v[14:29], v[50:53], v[114:117], v[14:29]
	v_lshl_add_u64 v[50:51], v[58:59], 0, v[32:33]
	v_lshl_add_u64 v[156:157], s[0:1], 0, v[50:51]
	s_waitcnt vmcnt(5)
	ds_write_b128 v171, v[34:37] offset:16384
	s_waitcnt vmcnt(4)
	ds_write_b128 v172, v[38:41] offset:16384
	s_waitcnt vmcnt(3)
	ds_write_b128 v170, v[42:45] offset:41984
	s_waitcnt lgkmcnt(3)
	v_mfma_f32_32x32x16_bf16 v[66:81], v[46:49], v[114:117], v[66:81]
	s_nop 1
	v_exp_f32_e32 v180, v14
	v_exp_f32_e32 v183, v15
	v_exp_f32_e32 v177, v16
	v_exp_f32_e32 v181, v17
	v_exp_f32_e32 v176, v18
	v_exp_f32_e32 v178, v19
	v_exp_f32_e32 v179, v20
	v_exp_f32_e32 v182, v21
	v_exp_f32_e32 v160, v22
	v_exp_f32_e32 v174, v23
	v_exp_f32_e32 v158, v24
	v_exp_f32_e32 v161, v25
	v_exp_f32_e32 v32, v26
	v_exp_f32_e32 v175, v27
	v_exp_f32_e32 v159, v28
	v_exp_f32_e32 v173, v29
	v_mov_b32_e32 v14, v166
	v_mov_b32_e32 v15, v166
	v_mov_b32_e32 v50, 0
	v_mov_b32_e32 v51, v166
	v_mov_b32_e32 v52, v166
	v_mov_b32_e32 v53, v166
	v_mov_b32_e32 v58, v166
	v_mov_b32_e32 v59, v166
	v_mov_b32_e32 v60, v166
	v_mov_b32_e32 v61, v166
	v_mov_b32_e32 v62, v166
	v_mov_b32_e32 v63, v166
	v_mov_b32_e32 v64, v166
	v_mov_b32_e32 v65, v166
	v_mov_b32_e32 v34, 0
	v_mov_b32_e32 v35, v166
	v_mov_b32_e32 v36, v166
	v_mov_b32_e32 v37, v166
	v_mov_b32_e32 v38, v166
	v_mov_b32_e32 v39, v166
	v_mov_b32_e32 v40, v166
	v_mov_b32_e32 v41, v166
	v_mov_b32_e32 v42, v166
	v_mov_b32_e32 v43, v166
	v_mov_b32_e32 v44, v166
	v_mov_b32_e32 v45, v166
	v_mov_b32_e32 v46, v166
	v_mov_b32_e32 v47, v166
	v_mov_b32_e32 v48, v166
	v_mov_b32_e32 v49, v166
	v_mov_b32_e32 v16, 0
	v_mov_b32_e32 v17, v166
	v_mov_b32_e32 v18, v166
	v_mov_b32_e32 v19, v166
	v_mov_b32_e32 v20, v166
	v_mov_b32_e32 v21, v166
	v_mov_b32_e32 v22, v166
	v_mov_b32_e32 v23, v166
	v_mov_b32_e32 v24, v166
	v_mov_b32_e32 v25, v166
	v_mov_b32_e32 v26, v166
	v_mov_b32_e32 v27, v166
	v_mov_b32_e32 v28, v166
	v_mov_b32_e32 v29, v166
	s_mov_b64 s[14:15], 0x40000
	v_readfirstlane_b32 s98, v156
	v_readfirstlane_b32 s99, v157
	v_readfirstlane_b32 s100, v154
	v_readfirstlane_b32 s101, v155
	s_nop 1
	v_subrev_u32_e32 v224, s98, v156
	v_subrev_u32_e32 v226, s100, v154
	v_add_u32_e32 v225, 0x10000, v224
	s_add_u32 s98, s98, s18
	s_addc_u32 s99, s99, s19
	s_add_u32 s100, s100, s18
	s_addc_u32 s101, s101, s19
	s_add_u32 s98, s98, 0x42d7c000
	s_addc_u32 s99, s99, 0
	s_add_u32 s100, s100, 0x40c7c000
	s_addc_u32 s101, s101, 0
	s_waitcnt lgkmcnt(0)
	s_barrier
	s_branch .LBB0_2299

; #define SBAR() __builtin_amdgcn_sched_barrier(0)
; #define SLOAD(i, k0) do { sv0[i] = *reinterpret_cast<const bf16x8*>(&Vh[(size_t)((k0) + sr) * ldv + sc]); sv1[i] = *reinterpret_cast<const bf16x8*>(&Vh[(size_t)((k0) + 32 + sr) * ldv + sc]); \
;     _Pragma("unroll") for (int _q = 0; _q < NKP; ++_q) sk[i][_q] = *reinterpret_cast<const bf16x8*>(&Kh[(size_t)(k0) * ldk + koff[_q]]); } while (0)
; #define PVD0(...) do { if constexpr (PV_PIPE != 0) pv_d0_pipe(__VA_ARGS__); else pv_d0(__VA_ARGS__); } while (0)
; #define SLOAD(k0) do { sv0 = *reinterpret_cast<const bf16x8*>(&Vh[(size_t)((k0) + sr) * ldv + sc]); sv1 = *reinterpret_cast<const bf16x8*>(&Vh[(size_t)((k0) + 32 + sr) * ldv + sc]); \
;     _Pragma("unroll") for (int _q = 0; _q < NKP; ++_q) sk[_q] = *reinterpret_cast<const bf16x8*>(&Kh[(size_t)(k0) * ldk + koff[_q]]); } while (0)
; __device__ __forceinline__ void finishSM(f32x16& p0, f32x16& p1, float alpha, float& l_reg, bf16x8& pa0, bf16x8& pa1, bf16x8& pa2, bf16x8& pa3) {
; #pragma unroll
;     for (int r = 0; r < 16; ++r) p1[r] = __builtin_amdgcn_exp2f(p1[r]);
;     float ps = 0;
; #pragma unroll
;     for (int r = 0; r < 16; ++r) ps += p0[r];
; #pragma unroll
;     for (int r = 0; r < 16; ++r) ps += p1[r];
;     { auto rr = __builtin_amdgcn_permlane32_swap(__float_as_uint(ps), __float_as_uint(ps), false, false);
;       ps = __uint_as_float(rr[0]) + __uint_as_float(rr[1]); }
;     l_reg = l_reg * alpha + ps;
;     ...
;     PK4(p0, 0, pa0); PK4(p0, 8, pa1); PK4(p1, 0, pa2); PK4(p1, 8, pa3);
;     ...
; }
; template <int DQK, int SDEPTH, int QL, bool NOMAX, int ldq, int ldk, int ldv, int ldo> ...
;     ...
;         SBAR(); qkt<DQK, QL>(pB0, pB1, K_lds + SHM_K, qr, qpark, r32, hi);
;         finishSM(pA0, pA1, alA, l_reg, pa0, pa1, pa2, pa3); SBAR();
;         SLOAD(SO, (j + SDEPTH) * KVBLK); SBAR();
;         PVD0(o, vb0, pa0, pa1, pa2, pa3); if constexpr (NOMAX) { partialSM_nm(pB0); alB = 1.f; } else partialSM(pB0, pB1, m_reg, mnB, alB, C, thr_raw);
.LBB0_2299:
	ds_read_b128 v[82:85], v168 offset:46592
	ds_read_b128 v[86:89], v168 offset:41984
	ds_read_b128 v[142:145], v168 offset:42016
	ds_read_b128 v[146:149], v168 offset:46624
	v_exp_f32_e32 v150, v74
	v_exp_f32_e32 v151, v75
	s_waitcnt lgkmcnt(2)
	v_mfma_f32_32x32x16_bf16 v[98:113], v[86:89], v[126:129], 0
	v_exp_f32_e32 v152, v76
	v_exp_f32_e32 v153, v77
	v_exp_f32_e32 v186, v78
	v_exp_f32_e32 v187, v79
	v_exp_f32_e32 v188, v80
	v_exp_f32_e32 v81, v81
	v_mfma_f32_32x32x16_bf16 v[82:97], v[82:85], v[126:129], 0
	s_waitcnt lgkmcnt(1)
	v_mfma_f32_32x32x16_bf16 v[98:113], v[142:145], v[122:125], v[98:113]
	s_waitcnt lgkmcnt(0)
	v_mfma_f32_32x32x16_bf16 v[82:97], v[146:149], v[122:125], v[82:97]
	ds_read_b128 v[142:145], v168 offset:42048
	ds_read_b128 v[146:149], v168 offset:46656
	s_waitcnt lgkmcnt(1)
	v_mfma_f32_32x32x16_bf16 v[98:113], v[142:145], v[118:121], v[98:113]
	s_waitcnt lgkmcnt(0)
	v_mfma_f32_32x32x16_bf16 v[82:97], v[146:149], v[118:121], v[82:97]
	ds_read_b128 v[142:145], v168 offset:42080
	ds_read_b128 v[146:149], v168 offset:46688
	s_waitcnt lgkmcnt(1)
	v_mfma_f32_32x32x16_bf16 v[98:113], v[142:145], v[114:117], v[98:113]
	v_exp_f32_e32 v142, v66
	v_add_f32_e32 v66, 0, v180
	v_add_f32_e32 v66, v183, v66
	v_add_f32_e32 v66, v177, v66
	v_add_f32_e32 v66, v181, v66
	v_add_f32_e32 v66, v176, v66
	v_add_f32_e32 v66, v178, v66
	v_add_f32_e32 v66, v179, v66
	v_add_f32_e32 v66, v182, v66
	v_add_f32_e32 v66, v160, v66
	v_add_f32_e32 v66, v174, v66
	v_add_f32_e32 v66, v158, v66
	v_add_f32_e32 v66, v161, v66
	v_add_f32_e32 v66, v32, v66
	v_exp_f32_e32 v143, v67
	v_add_f32_e32 v66, v175, v66
	v_exp_f32_e32 v144, v68
	v_add_f32_e32 v66, v159, v66
	v_exp_f32_e32 v145, v69
	v_add_f32_e32 v66, v173, v66
	s_waitcnt lgkmcnt(0)
	v_mfma_f32_32x32x16_bf16 v[82:97], v[146:149], v[114:117], v[82:97]
	v_exp_f32_e32 v146, v70
	v_add_f32_e32 v66, v142, v66
	v_exp_f32_e32 v147, v71
	v_add_f32_e32 v66, v143, v66
	v_exp_f32_e32 v148, v72
	v_add_f32_e32 v66, v144, v66
	v_exp_f32_e32 v149, v73
	v_add_f32_e32 v66, v145, v66
	v_add_f32_e32 v66, v146, v66
	v_add_f32_e32 v66, v147, v66
	v_add_f32_e32 v66, v148, v66
	v_add_f32_e32 v66, v149, v66
	v_add_f32_e32 v66, v150, v66
	v_add_f32_e32 v66, v151, v66
	v_add_f32_e32 v66, v152, v66
	v_add_f32_e32 v66, v153, v66
	v_add_f32_e32 v66, v186, v66
	v_add_f32_e32 v66, v187, v66
	v_add_f32_e32 v66, v188, v66
	v_add_f32_e32 v184, v81, v66
	v_cvt_pk_bf16_f32 v66, v180, v183
	v_cvt_pk_bf16_f32 v67, v177, v181
	v_cvt_pk_bf16_f32 v68, v176, v178
	v_cvt_pk_bf16_f32 v69, v179, v182
	v_cvt_pk_bf16_f32 v70, v160, v174
	v_cvt_pk_bf16_f32 v71, v158, v161
	v_cvt_pk_bf16_f32 v72, v32, v175
	v_cvt_pk_bf16_f32 v73, v159, v173
	v_cvt_pk_bf16_f32 v74, v142, v143
	v_cvt_pk_bf16_f32 v75, v144, v145
	v_cvt_pk_bf16_f32 v76, v146, v147
	v_cvt_pk_bf16_f32 v77, v148, v149
	v_cvt_pk_bf16_f32 v78, v150, v151
	v_cvt_pk_bf16_f32 v79, v152, v153
	v_cvt_pk_bf16_f32 v80, v186, v187
	v_cvt_pk_bf16_f32 v81, v188, v81
	global_load_dwordx4 v[142:145], v224, s[98:99] offset:256
	global_load_dwordx4 v[146:149], v225, s[98:99] offset:256
	global_load_dwordx4 v[150:153], v226, s[100:101] offset:256
	s_add_u32 s98, s98, 0x20000
	s_addc_u32 s99, s99, 0
	s_add_u32 s100, s100, 0x20000
	s_addc_u32 s101, s101, 0
	ds_read_b64_tr_b16 v[174:175], v169 offset:0
	ds_read_b64_tr_b16 v[176:177], v169 offset:0x800
	ds_read_b64_tr_b16 v[178:179], v169 offset:0x1000
	ds_read_b64_tr_b16 v[180:181], v169 offset:0x1800
	ds_read_b64_tr_b16 v[186:187], v169 offset:0x2000
	ds_read_b64_tr_b16 v[188:189], v169 offset:0x2800
	ds_read_b64_tr_b16 v[190:191], v169 offset:0x3000
	ds_read_b64_tr_b16 v[192:193], v169 offset:0x3800
	s_waitcnt lgkmcnt(6)
	s_nop 0
	v_mfma_f32_32x32x16_bf16 v[0:15], v[66:69], v[174:177], v[0:15]
	ds_read_b64_tr_b16 v[174:175], v169 offset:0x200
	ds_read_b64_tr_b16 v[176:177], v169 offset:0xa00
	s_waitcnt lgkmcnt(6)
	v_mfma_f32_32x32x16_bf16 v[0:15], v[70:73], v[178:181], v[0:15]
	ds_read_b64_tr_b16 v[178:179], v169 offset:0x1200
	ds_read_b64_tr_b16 v[180:181], v169 offset:0x1a00
	s_waitcnt lgkmcnt(6)
	v_mfma_f32_32x32x16_bf16 v[0:15], v[74:77], v[186:189], v[0:15]
	ds_read_b64_tr_b16 v[186:187], v169 offset:0x2200
	ds_read_b64_tr_b16 v[188:189], v169 offset:0x2a00
	s_waitcnt lgkmcnt(6)
	v_mfma_f32_32x32x16_bf16 v[0:15], v[78:81], v[190:193], v[0:15]
	ds_read_b64_tr_b16 v[190:191], v169 offset:0x3200
	ds_read_b64_tr_b16 v[192:193], v169 offset:0x3a00
	s_waitcnt lgkmcnt(6)
	v_mfma_f32_32x32x16_bf16 v[50:65], v[66:69], v[174:177], v[50:65]
	ds_read_b64_tr_b16 v[174:175], v169 offset:0x400
	ds_read_b64_tr_b16 v[176:177], v169 offset:0xc00
	s_waitcnt lgkmcnt(6)
	v_mfma_f32_32x32x16_bf16 v[50:65], v[70:73], v[178:181], v[50:65]
	ds_read_b64_tr_b16 v[178:179], v169 offset:0x1400
	ds_read_b64_tr_b16 v[180:181], v169 offset:0x1c00
	s_waitcnt lgkmcnt(6)
	v_mfma_f32_32x32x16_bf16 v[50:65], v[74:77], v[186:189], v[50:65]
	ds_read_b64_tr_b16 v[186:187], v169 offset:0x2400
	ds_read_b64_tr_b16 v[188:189], v169 offset:0x2c00
	s_waitcnt lgkmcnt(6)
	v_mfma_f32_32x32x16_bf16 v[50:65], v[78:81], v[190:193], v[50:65]
	ds_read_b64_tr_b16 v[190:191], v169 offset:0x3400
	ds_read_b64_tr_b16 v[192:193], v169 offset:0x3c00
	s_waitcnt lgkmcnt(6)
	v_mfma_f32_32x32x16_bf16 v[34:49], v[66:69], v[174:177], v[34:49]
	ds_read_b64_tr_b16 v[174:175], v169 offset:0x600
	ds_read_b64_tr_b16 v[176:177], v169 offset:0xe00
	s_waitcnt lgkmcnt(6)
	v_mfma_f32_32x32x16_bf16 v[34:49], v[70:73], v[178:181], v[34:49]
	ds_read_b64_tr_b16 v[178:179], v169 offset:0x1600
	ds_read_b64_tr_b16 v[180:181], v169 offset:0x1e00
	s_waitcnt lgkmcnt(6)
	v_mfma_f32_32x32x16_bf16 v[34:49], v[74:77], v[186:189], v[34:49]
	ds_read_b64_tr_b16 v[186:187], v169 offset:0x2600
	ds_read_b64_tr_b16 v[188:189], v169 offset:0x2e00
	s_waitcnt lgkmcnt(6)
	v_mfma_f32_32x32x16_bf16 v[34:49], v[78:81], v[190:193], v[34:49]
	ds_read_b64_tr_b16 v[190:191], v169 offset:0x3600
	ds_read_b64_tr_b16 v[192:193], v169 offset:0x3e00
	s_waitcnt lgkmcnt(0)
	v_mfma_f32_32x32x16_bf16 v[16:31], v[66:69], v[174:177], v[16:31]
	s_barrier
; #define SBAR() __builtin_amdgcn_sched_barrier(0)
; #define SLOAD(i, k0) do { sv0[i] = *reinterpret_cast<const bf16x8*>(&Vh[(size_t)((k0) + sr) * ldv + sc]); sv1[i] = *reinterpret_cast<const bf16x8*>(&Vh[(size_t)((k0) + 32 + sr) * ldv + sc]); \
;     _Pragma("unroll") for (int _q = 0; _q < NKP; ++_q) sk[i][_q] = *reinterpret_cast<const bf16x8*>(&Kh[(size_t)(k0) * ldk + koff[_q]]); } while (0)
; #define SWRITE(b, i) do { *(bf16x8*)(V_lds + (b) * SHM_V + vst0) = sv0[i]; *(bf16x8*)(V_lds + (b) * SHM_V + vst1) = sv1[i]; \
;     _Pragma("unroll") for (int _q = 0; _q < NKP; ++_q) *(bf16x8*)(K_lds + (b) * SHM_K + klds[_q]) = sk[i][_q]; } while (0)
; #define SWAIT() do { if constexpr (SDEPTH == 2) { if constexpr (NKP == 1) asm volatile("s_waitcnt vmcnt(3)" ::: "memory"); else if constexpr (NKP == 2) asm volatile("s_waitcnt vmcnt(4)" ::: "memory"); else asm volatile("s_waitcnt vmcnt(5)" ::: "memory"); } \
;     else asm volatile("s_waitcnt vmcnt(0)" ::: "memory"); } while (0)
; #define PVD0(...) do { if constexpr (PV_PIPE != 0) pv_d0_pipe(__VA_ARGS__); else pv_d0(__VA_ARGS__); } while (0)
; #define RESC(a) do { if constexpr (!NOMAX) if (__any((a) < 1.f)) { if (hi == 0) al_l[r32] = (a); asm volatile("s_waitcnt lgkmcnt(0)" ::: "memory"); \
;     _Pragma("unroll") for (int d = 0; d < 4; ++d) _Pragma("unroll") for (int r = 0; r < 16; ++r) o[d][r] *= al_l[crow(r, hi)]; } } while (0)
; template <int DQK, int SDEPTH, int QL, bool NOMAX, int ldq, int ldk, int ldv, int ldo> ...
;     ...
;         __syncthreads(); SWAIT(); SWRITE(0, SE);
;         RESC(alB); __syncthreads();
;         SBAR(); qkt<DQK, QL>(pA0, pA1, K_lds, qr, qpark, r32, hi);
;         finishSM(pB0, pB1, alB, l_reg, pa0, pa1, pa2, pa3); SBAR();
;         if (SDEPTH == 1 || j + 3 < NT) SLOAD(SE, (j + 1 + SDEPTH) * KVBLK); SBAR();
;         PVD0(o, vb0 + SHM_V, pa0, pa1, pa2, pa3); if constexpr (NOMAX) { partialSM_nm(pA0); alA = 1.f; } else partialSM(pA0, pA1, m_reg, mnA, alA, C, thr_raw);
;         __syncthreads(); SWAIT(); SWRITE(1, SO);
;         RESC(alA); __syncthreads();
;     }
;     SBAR(); qkt<DQK, QL>(pB0, pB1, K_lds + SHM_K, qr, qpark, r32, hi);
;     finishSM(pA0, pA1, alA, l_reg, pa0, pa1, pa2, pa3); SBAR();
	s_waitcnt vmcnt(3)
	v_exp_f32_e32 v182, v98
	v_exp_f32_e32 v183, v99
	v_exp_f32_e32 v194, v108
	v_mfma_f32_32x32x16_bf16 v[16:31], v[70:73], v[178:181], v[16:31]
	v_exp_f32_e32 v195, v109
	v_exp_f32_e32 v196, v110
	v_exp_f32_e32 v197, v111
	v_exp_f32_e32 v198, v112
	v_exp_f32_e32 v199, v113
	s_waitcnt vmcnt(5)
	ds_write_b128 v171, v[130:133]
	s_waitcnt vmcnt(4)
	ds_write_b128 v172, v[134:137]
	s_waitcnt vmcnt(3)
	ds_write_b128 v170, v[138:141] offset:32768
	s_waitcnt lgkmcnt(0)
	v_mfma_f32_32x32x16_bf16 v[16:31], v[74:77], v[186:189], v[16:31]
	v_exp_f32_e32 v186, v100
	v_exp_f32_e32 v187, v101
	v_exp_f32_e32 v188, v102
	v_exp_f32_e32 v189, v103
	s_barrier
	v_mfma_f32_32x32x16_bf16 v[16:31], v[78:81], v[190:193], v[16:31]
	v_exp_f32_e32 v190, v104
	v_exp_f32_e32 v191, v105
	v_exp_f32_e32 v192, v106
	v_exp_f32_e32 v193, v107
	ds_read_b128 v[66:69], v168 offset:37376
	ds_read_b128 v[70:73], v168 offset:32768
	ds_read_b128 v[174:177], v168 offset:32800
	ds_read_b128 v[178:181], v168 offset:37408
	v_add_f32_e32 v32, 0, v182
	v_add_f32_e32 v32, v183, v32
	s_waitcnt lgkmcnt(2)
	v_mfma_f32_32x32x16_bf16 v[98:113], v[70:73], v[126:129], 0
	v_add_f32_e32 v32, v186, v32
	v_add_f32_e32 v32, v187, v32
	v_add_f32_e32 v32, v188, v32
	v_add_f32_e32 v32, v189, v32
	v_add_f32_e32 v32, v190, v32
	v_add_f32_e32 v32, v191, v32
	v_add_f32_e32 v32, v192, v32
	v_mfma_f32_32x32x16_bf16 v[66:81], v[66:69], v[126:129], 0
	v_add_f32_e32 v32, v193, v32
	v_add_f32_e32 v32, v194, v32
	v_add_f32_e32 v32, v195, v32
	v_add_f32_e32 v32, v196, v32
	v_add_f32_e32 v32, v197, v32
	v_add_f32_e32 v32, v198, v32
	v_add_f32_e32 v32, v199, v32
	s_waitcnt lgkmcnt(1)
	v_mfma_f32_32x32x16_bf16 v[98:113], v[174:177], v[122:125], v[98:113]
	v_exp_f32_e32 v200, v90
	v_exp_f32_e32 v201, v91
	v_exp_f32_e32 v202, v92
	v_exp_f32_e32 v203, v93
	v_exp_f32_e32 v204, v94
	v_exp_f32_e32 v205, v95
	v_exp_f32_e32 v206, v96
	s_waitcnt lgkmcnt(0)
	v_mfma_f32_32x32x16_bf16 v[66:81], v[178:181], v[122:125], v[66:81]
	ds_read_b128 v[174:177], v168 offset:32832
	ds_read_b128 v[178:181], v168 offset:37440
	v_exp_f32_e32 v97, v97
	s_waitcnt lgkmcnt(1)
	v_mfma_f32_32x32x16_bf16 v[98:113], v[174:177], v[118:121], v[98:113]
	s_waitcnt lgkmcnt(0)
	v_mfma_f32_32x32x16_bf16 v[66:81], v[178:181], v[118:121], v[66:81]
	ds_read_b128 v[174:177], v168 offset:32864
	ds_read_b128 v[178:181], v168 offset:37472
	s_waitcnt lgkmcnt(1)
	v_mfma_f32_32x32x16_bf16 v[98:113], v[174:177], v[114:117], v[98:113]
	v_exp_f32_e32 v174, v82
	v_exp_f32_e32 v175, v83
	v_exp_f32_e32 v176, v84
	v_exp_f32_e32 v177, v85
	v_add_f32_e32 v32, v174, v32
	v_add_f32_e32 v32, v175, v32
	v_add_f32_e32 v32, v176, v32
	s_waitcnt lgkmcnt(0)
	v_mfma_f32_32x32x16_bf16 v[66:81], v[178:181], v[114:117], v[66:81]
	v_exp_f32_e32 v178, v86
	v_exp_f32_e32 v179, v87
	v_exp_f32_e32 v180, v88
	v_exp_f32_e32 v181, v89
	v_add_f32_e32 v32, v177, v32
	v_add_f32_e32 v32, v178, v32
	v_add_f32_e32 v32, v179, v32
	v_add_f32_e32 v32, v180, v32
	v_add_f32_e32 v32, v181, v32
	v_add_f32_e32 v32, v200, v32
	v_add_f32_e32 v32, v201, v32
	v_add_f32_e32 v32, v202, v32
	v_add_f32_e32 v32, v203, v32
	v_add_f32_e32 v32, v204, v32
	v_add_f32_e32 v32, v205, v32
	v_add_f32_e32 v32, v206, v32
	v_add_f32_e32 v32, v97, v32
	v_cvt_pk_bf16_f32 v82, v182, v183
	v_cvt_pk_bf16_f32 v83, v186, v187
	v_cvt_pk_bf16_f32 v84, v188, v189
	v_cvt_pk_bf16_f32 v85, v190, v191
	v_cvt_pk_bf16_f32 v86, v192, v193
	v_cvt_pk_bf16_f32 v87, v194, v195
	v_cvt_pk_bf16_f32 v88, v196, v197
	v_cvt_pk_bf16_f32 v89, v198, v199
	v_cvt_pk_bf16_f32 v90, v174, v175
	v_cvt_pk_bf16_f32 v91, v176, v177
	v_cvt_pk_bf16_f32 v92, v178, v179
	v_cvt_pk_bf16_f32 v93, v180, v181
	v_cvt_pk_bf16_f32 v94, v200, v201
	v_cvt_pk_bf16_f32 v95, v202, v203
	v_cvt_pk_bf16_f32 v96, v204, v205
	v_cvt_pk_bf16_f32 v97, v206, v97
	s_cmp_ge_u32 s6, s7
	s_cselect_b64 s[4:5], -1, 0
	s_and_b64 vcc, exec, s[4:5]
	s_cbranch_vccnz .LBB0_2298
	global_load_dwordx4 v[130:133], v224, s[98:99] offset:256
	global_load_dwordx4 v[134:137], v225, s[98:99] offset:256
	global_load_dwordx4 v[138:141], v226, s[100:101] offset:256
	s_add_u32 s98, s98, 0x20000
	s_addc_u32 s99, s99, 0
	s_add_u32 s100, s100, 0x20000
	s_addc_u32 s101, s101, 0
	s_branch .LBB0_2298
.LBB0_2301:
	v_mov_b32_e32 v227, v166
	s_nop 1
	v_permlane32_swap_b32_e32 v166, v227
	v_add_f32_e32 v166, v166, v227
	ds_read_b128 v[82:85], v168 offset:46592
	ds_read_b128 v[86:89], v168 offset:41984
	ds_read_b128 v[130:133], v168 offset:42016
	v_exp_f32_e32 v67, v67
	v_exp_f32_e32 v69, v69
	s_waitcnt lgkmcnt(1)
	v_mfma_f32_32x32x16_bf16 v[98:113], v[86:89], v[126:129], 0
	v_mfma_f32_32x32x16_bf16 v[82:97], v[82:85], v[126:129], 0
	ds_read_b128 v[126:129], v168 offset:46624
	s_waitcnt lgkmcnt(1)
	v_mfma_f32_32x32x16_bf16 v[98:113], v[130:133], v[122:125], v[98:113]
	s_waitcnt lgkmcnt(0)
	v_mfma_f32_32x32x16_bf16 v[82:97], v[126:129], v[122:125], v[82:97]
	ds_read_b128 v[122:125], v168 offset:42048
	ds_read_b128 v[126:129], v168 offset:46656
	s_waitcnt lgkmcnt(1)
	v_mfma_f32_32x32x16_bf16 v[98:113], v[122:125], v[118:121], v[98:113]
	s_waitcnt lgkmcnt(0)
	v_mfma_f32_32x32x16_bf16 v[82:97], v[126:129], v[118:121], v[82:97]
	ds_read_b128 v[118:121], v168 offset:42080
	ds_read_b128 v[122:125], v168 offset:46688
	v_exp_f32_e32 v126, v80
	v_exp_f32_e32 v127, v81
	s_waitcnt lgkmcnt(1)
	v_mfma_f32_32x32x16_bf16 v[98:113], v[118:121], v[114:117], v[98:113]
	v_exp_f32_e32 v118, v72
	v_exp_f32_e32 v119, v73
	v_exp_f32_e32 v120, v74
	v_exp_f32_e32 v121, v75
	s_waitcnt lgkmcnt(0)
; #define SBAR() __builtin_amdgcn_sched_barrier(0)
; #define PVD0(...) do { if constexpr (PV_PIPE != 0) pv_d0_pipe(__VA_ARGS__); else pv_d0(__VA_ARGS__); } while (0)
; #define RESC(a) do { if constexpr (!NOMAX) if (__any((a) < 1.f)) { if (hi == 0) al_l[r32] = (a); asm volatile("s_waitcnt lgkmcnt(0)" ::: "memory"); \
;     _Pragma("unroll") for (int d = 0; d < 4; ++d) _Pragma("unroll") for (int r = 0; r < 16; ++r) o[d][r] *= al_l[crow(r, hi)]; } } while (0)
; #define RESC(a) do { if (__any((a) < 1.f)) { if (hi == 0) al_l[r32] = (a); asm volatile("s_waitcnt lgkmcnt(0)" ::: "memory"); \
;     _Pragma("unroll") for (int d = 0; d < 4; ++d) _Pragma("unroll") for (int r = 0; r < 16; ++r) o[d][r] *= al_l[crow(r, hi)]; } } while (0)
; template <int DQK, int SDEPTH, int QL, bool NOMAX, int ldq, int ldk, int ldv, int ldo> ...
;     ...
;     SBAR(); qkt<DQK, QL>(pB0, pB1, K_lds + SHM_K, qr, qpark, r32, hi);
;     finishSM(pA0, pA1, alA, l_reg, pa0, pa1, pa2, pa3); SBAR();
;     PVD0(o, vb0, pa0, pa1, pa2, pa3); if constexpr (NOMAX) { partialSM_nm(pB0); alB = 1.f; } else partialSM(pB0, pB1, m_reg, mnB, alB, C, thr_raw);
;     __syncthreads(); RESC(alB);
;     finishSM(pB0, pB1, alB, l_reg, pa0, pa1, pa2, pa3); SBAR();
	v_mfma_f32_32x32x16_bf16 v[82:97], v[122:125], v[114:117], v[82:97]
	v_exp_f32_e32 v114, v66
	v_add_f32_e32 v66, 0, v180
	v_add_f32_e32 v66, v183, v66
	v_add_f32_e32 v66, v177, v66
	v_add_f32_e32 v66, v181, v66
	v_add_f32_e32 v66, v176, v66
	v_add_f32_e32 v66, v178, v66
	v_add_f32_e32 v66, v179, v66
	v_add_f32_e32 v66, v182, v66
	v_add_f32_e32 v66, v160, v66
	v_add_f32_e32 v66, v174, v66
	v_add_f32_e32 v66, v158, v66
	v_add_f32_e32 v66, v161, v66
	v_add_f32_e32 v66, v32, v66
	v_add_f32_e32 v66, v175, v66
	v_exp_f32_e32 v115, v68
	v_add_f32_e32 v66, v159, v66
	v_add_f32_e32 v66, v173, v66
	v_exp_f32_e32 v116, v70
	v_add_f32_e32 v66, v114, v66
	v_exp_f32_e32 v117, v71
	v_add_f32_e32 v66, v67, v66
	v_add_f32_e32 v66, v115, v66
	v_add_f32_e32 v66, v69, v66
	v_add_f32_e32 v66, v116, v66
	v_add_f32_e32 v66, v117, v66
	v_exp_f32_e32 v122, v76
	v_add_f32_e32 v66, v118, v66
	v_exp_f32_e32 v123, v77
	v_add_f32_e32 v66, v119, v66
	v_exp_f32_e32 v124, v78
	v_add_f32_e32 v66, v120, v66
	v_exp_f32_e32 v125, v79
	v_add_f32_e32 v66, v121, v66
	v_add_f32_e32 v66, v122, v66
	v_add_f32_e32 v66, v123, v66
	v_add_f32_e32 v66, v124, v66
	v_add_f32_e32 v66, v125, v66
	v_add_f32_e32 v66, v126, v66
	v_add_f32_e32 v66, v127, v66
	v_mov_b32_e32 v68, v66
	s_nop 1
	v_permlane32_swap_b32_e32 v66, v68
	v_cvt_pk_bf16_f32 v70, v180, v183
	v_cvt_pk_bf16_f32 v71, v177, v181
	v_cvt_pk_bf16_f32 v72, v176, v178
	v_cvt_pk_bf16_f32 v73, v179, v182
	v_cvt_pk_bf16_f32 v74, v160, v174
	v_cvt_pk_bf16_f32 v75, v158, v161
	v_cvt_pk_bf16_f32 v76, v32, v175
	v_cvt_pk_bf16_f32 v77, v159, v173
	v_cvt_pk_bf16_f32 v78, v114, v67
	v_cvt_pk_bf16_f32 v79, v115, v69
	v_cvt_pk_bf16_f32 v80, v116, v117
	v_cvt_pk_bf16_f32 v81, v118, v119
	v_cvt_pk_bf16_f32 v114, v120, v121
	v_cvt_pk_bf16_f32 v115, v122, v123
	v_cvt_pk_bf16_f32 v116, v124, v125
	v_cvt_pk_bf16_f32 v117, v126, v127
	ds_read_b64_tr_b16 v[118:119], v169 offset:0
	ds_read_b64_tr_b16 v[120:121], v169 offset:0x800
	ds_read_b64_tr_b16 v[122:123], v169 offset:0x1000
	ds_read_b64_tr_b16 v[124:125], v169 offset:0x1800
	ds_read_b64_tr_b16 v[126:127], v169 offset:0x2000
	ds_read_b64_tr_b16 v[128:129], v169 offset:0x2800
	ds_read_b64_tr_b16 v[130:131], v169 offset:0x3000
	ds_read_b64_tr_b16 v[132:133], v169 offset:0x3800
	s_waitcnt lgkmcnt(0)
	s_nop 0
	v_mfma_f32_32x32x16_bf16 v[0:15], v[70:73], v[118:121], v[0:15]
	ds_read_b64_tr_b16 v[118:119], v169 offset:0x200
	ds_read_b64_tr_b16 v[120:121], v169 offset:0xa00
	v_mfma_f32_32x32x16_bf16 v[0:15], v[74:77], v[122:125], v[0:15]
	ds_read_b64_tr_b16 v[122:123], v169 offset:0x1200
	ds_read_b64_tr_b16 v[124:125], v169 offset:0x1a00
	v_mfma_f32_32x32x16_bf16 v[0:15], v[78:81], v[126:129], v[0:15]
	ds_read_b64_tr_b16 v[126:127], v169 offset:0x2200
	ds_read_b64_tr_b16 v[128:129], v169 offset:0x2a00
	v_mfma_f32_32x32x16_bf16 v[0:15], v[114:117], v[130:133], v[0:15]
	ds_read_b64_tr_b16 v[130:131], v169 offset:0x3200
	ds_read_b64_tr_b16 v[132:133], v169 offset:0x3a00
	s_waitcnt lgkmcnt(0)
	v_mfma_f32_32x32x16_bf16 v[50:65], v[70:73], v[118:121], v[50:65]
	ds_read_b64_tr_b16 v[118:119], v169 offset:0x400
	ds_read_b64_tr_b16 v[120:121], v169 offset:0xc00
	v_mfma_f32_32x32x16_bf16 v[50:65], v[74:77], v[122:125], v[50:65]
	ds_read_b64_tr_b16 v[122:123], v169 offset:0x1400
	ds_read_b64_tr_b16 v[124:125], v169 offset:0x1c00
	v_mfma_f32_32x32x16_bf16 v[50:65], v[78:81], v[126:129], v[50:65]
	ds_read_b64_tr_b16 v[126:127], v169 offset:0x2400
	ds_read_b64_tr_b16 v[128:129], v169 offset:0x2c00
	v_mfma_f32_32x32x16_bf16 v[50:65], v[114:117], v[130:133], v[50:65]
	ds_read_b64_tr_b16 v[130:131], v169 offset:0x3400
	ds_read_b64_tr_b16 v[132:133], v169 offset:0x3c00
	s_waitcnt lgkmcnt(0)
	v_mfma_f32_32x32x16_bf16 v[34:49], v[70:73], v[118:121], v[34:49]
	ds_read_b64_tr_b16 v[118:119], v169 offset:0x600
	ds_read_b64_tr_b16 v[120:121], v169 offset:0xe00
	v_mfma_f32_32x32x16_bf16 v[34:49], v[74:77], v[122:125], v[34:49]
	ds_read_b64_tr_b16 v[122:123], v169 offset:0x1600
	ds_read_b64_tr_b16 v[124:125], v169 offset:0x1e00
	v_mfma_f32_32x32x16_bf16 v[34:49], v[78:81], v[126:129], v[34:49]
	ds_read_b64_tr_b16 v[126:127], v169 offset:0x2600
	ds_read_b64_tr_b16 v[128:129], v169 offset:0x2e00
	v_mfma_f32_32x32x16_bf16 v[34:49], v[114:117], v[130:133], v[34:49]
	ds_read_b64_tr_b16 v[130:131], v169 offset:0x3600
	ds_read_b64_tr_b16 v[132:133], v169 offset:0x3e00
	s_waitcnt lgkmcnt(0)
	v_mfma_f32_32x32x16_bf16 v[16:31], v[70:73], v[118:121], v[16:31]
	v_exp_f32_e32 v32, v98
	v_exp_f32_e32 v70, v99
	v_exp_f32_e32 v71, v100
	v_exp_f32_e32 v72, v101
	v_exp_f32_e32 v73, v102
	v_add_f32_e32 v67, 0, v32
	v_add_f32_e32 v67, v70, v67
	v_mfma_f32_32x32x16_bf16 v[16:31], v[74:77], v[122:125], v[16:31]
	v_exp_f32_e32 v74, v103
	v_exp_f32_e32 v75, v104
	v_add_f32_e32 v67, v71, v67
	v_exp_f32_e32 v76, v105
	v_add_f32_e32 v67, v72, v67
	v_exp_f32_e32 v77, v106
	v_add_f32_e32 v67, v73, v67
	v_mfma_f32_32x32x16_bf16 v[16:31], v[78:81], v[126:129], v[16:31]
	v_exp_f32_e32 v78, v107
	v_add_f32_e32 v67, v74, v67
	v_exp_f32_e32 v79, v108
	v_add_f32_e32 v67, v75, v67
	v_exp_f32_e32 v80, v109
	v_add_f32_e32 v67, v76, v67
	v_exp_f32_e32 v81, v110
	v_add_f32_e32 v67, v77, v67
	v_exp_f32_e32 v98, v111
	v_add_f32_e32 v67, v78, v67
	v_exp_f32_e32 v99, v112
	v_add_f32_e32 v67, v79, v67
	v_exp_f32_e32 v100, v113
	v_add_f32_e32 v67, v80, v67
	v_exp_f32_e32 v82, v82
	v_add_f32_e32 v67, v81, v67
	v_exp_f32_e32 v83, v83
	v_add_f32_e32 v67, v98, v67
	v_exp_f32_e32 v84, v84
	v_add_f32_e32 v67, v99, v67
	v_exp_f32_e32 v85, v85
	v_add_f32_e32 v67, v100, v67
	v_exp_f32_e32 v86, v86
	v_add_f32_e32 v67, v82, v67
	v_exp_f32_e32 v87, v87
	v_add_f32_e32 v67, v83, v67
	v_exp_f32_e32 v88, v88
	v_add_f32_e32 v67, v84, v67
	v_exp_f32_e32 v89, v89
	v_add_f32_e32 v67, v85, v67
	v_exp_f32_e32 v90, v90
	v_add_f32_e32 v67, v86, v67
	v_exp_f32_e32 v91, v91
	v_add_f32_e32 v67, v87, v67
	v_exp_f32_e32 v92, v92
	v_add_f32_e32 v67, v88, v67
	v_exp_f32_e32 v93, v93
	v_add_f32_e32 v67, v89, v67
	v_exp_f32_e32 v94, v94
	v_add_f32_e32 v67, v90, v67
	v_exp_f32_e32 v95, v95
	v_add_f32_e32 v67, v91, v67
	v_mfma_f32_32x32x16_bf16 v[16:31], v[114:117], v[130:133], v[16:31]
	v_exp_f32_e32 v96, v96
	v_add_f32_e32 v67, v92, v67
	v_exp_f32_e32 v97, v97
	v_add_f32_e32 v67, v93, v67
	v_add_f32_e32 v67, v94, v67
	v_add_f32_e32 v67, v95, v67
	v_add_f32_e32 v67, v96, v67
	v_add_f32_e32 v67, v97, v67
	v_mov_b32_e32 v69, v67
	s_barrier
; template <int M> __device__ __forceinline__ float swz_xor(float v) { return __int_as_float(__builtin_amdgcn_ds_swizzle(__float_as_int(v), (M << 10) | 0x1f)); }
; #define SBAR() __builtin_amdgcn_sched_barrier(0)
; __device__ __forceinline__ int crow(int r, int hi) { return (r & 3) + 8 * (r >> 2) + 4 * hi; }
; __device__ __forceinline__ unsigned cvtpk(float lo, float hi) { unsigned r; asm volatile("v_cvt_pk_bf16_f32 %0, %1, %2" : "=v"(r) : "v"(lo), "v"(hi)); return r; }
; #define PVD0(...) do { if constexpr (PV_PIPE != 0) pv_d0_pipe(__VA_ARGS__); else pv_d0(__VA_ARGS__); } while (0)
; template <int DQK, int SDEPTH, int QL, bool NOMAX, int ldq, int ldk, int ldv, int ldo> ...
;     ...
;     finishSM(pB0, pB1, alB, l_reg, pa0, pa1, pa2, pa3); SBAR();
;     PVD0(o, vb0 + SHM_V, pa0, pa1, pa2, pa3);
;     if (ATT_PRIO) __builtin_amdgcn_s_setprio(0);
;     if (hi == 0) li_l[r32] = l_reg; asm volatile("s_waitcnt lgkmcnt(0)" ::: "memory");
;     float rli[16];
; #pragma unroll
;     for (int r = 0; r < 16; ++r) rli[r] = __builtin_amdgcn_rcpf(li_l[crow(r, hi)]);
;     bf16_t* Ow = Ob + (size_t)(wid * QBLK) * ldo + (r32 & ~1);
;     const bool odd = (r32 & 1) != 0;
; #pragma unroll
;     for (int r = 0; r < 16; r += 2) { const int orow = crow(r, hi) + (odd ? 1 : 0);
; #pragma unroll
;         for (int d0 = 0; d0 < 4; ++d0) { const float a = o[d0][r] * rli[r], b = o[d0][r + 1] * rli[r + 1];
;             const float recv = swz_xor<1>(odd ? a : b);
;             const unsigned w = odd ? cvtpk(recv, b) : cvtpk(a, recv);
;             *(unsigned*)(Ow + (size_t)orow * ldo + d0 * 32) = w; } }
	s_nop 0
	v_permlane32_swap_b32_e32 v67, v69
	v_cvt_pk_bf16_f32 v70, v32, v70
	v_cvt_pk_bf16_f32 v71, v71, v72
	v_cvt_pk_bf16_f32 v72, v73, v74
	v_cvt_pk_bf16_f32 v73, v75, v76
	v_cvt_pk_bf16_f32 v74, v77, v78
	v_cvt_pk_bf16_f32 v75, v79, v80
	v_cvt_pk_bf16_f32 v76, v81, v98
	v_cvt_pk_bf16_f32 v77, v99, v100
	v_cvt_pk_bf16_f32 v78, v82, v83
	v_cvt_pk_bf16_f32 v79, v84, v85
	v_cvt_pk_bf16_f32 v80, v86, v87
	v_cvt_pk_bf16_f32 v81, v88, v89
	v_cvt_pk_bf16_f32 v82, v90, v91
	v_cvt_pk_bf16_f32 v83, v92, v93
	v_cvt_pk_bf16_f32 v84, v94, v95
	v_cvt_pk_bf16_f32 v85, v96, v97
	ds_read_b64_tr_b16 v[86:87], v167 offset:0
	ds_read_b64_tr_b16 v[88:89], v167 offset:0x800
	ds_read_b64_tr_b16 v[90:91], v167 offset:0x1000
	ds_read_b64_tr_b16 v[92:93], v167 offset:0x1800
	ds_read_b64_tr_b16 v[94:95], v167 offset:0x2000
	ds_read_b64_tr_b16 v[96:97], v167 offset:0x2800
	ds_read_b64_tr_b16 v[98:99], v167 offset:0x3000
	ds_read_b64_tr_b16 v[100:101], v167 offset:0x3800
	s_waitcnt lgkmcnt(0)
	s_nop 0
	v_mfma_f32_32x32x16_bf16 v[0:15], v[70:73], v[86:89], v[0:15]
	ds_read_b64_tr_b16 v[86:87], v167 offset:0x200
	ds_read_b64_tr_b16 v[88:89], v167 offset:0xa00
	v_mfma_f32_32x32x16_bf16 v[0:15], v[74:77], v[90:93], v[0:15]
	ds_read_b64_tr_b16 v[90:91], v167 offset:0x1200
	ds_read_b64_tr_b16 v[92:93], v167 offset:0x1a00
	v_mfma_f32_32x32x16_bf16 v[0:15], v[78:81], v[94:97], v[0:15]
	ds_read_b64_tr_b16 v[94:95], v167 offset:0x2200
	ds_read_b64_tr_b16 v[96:97], v167 offset:0x2a00
	v_mfma_f32_32x32x16_bf16 v[0:15], v[82:85], v[98:101], v[0:15]
	ds_read_b64_tr_b16 v[98:99], v167 offset:0x3200
	ds_read_b64_tr_b16 v[100:101], v167 offset:0x3a00
	s_waitcnt lgkmcnt(0)
	v_mfma_f32_32x32x16_bf16 v[50:65], v[70:73], v[86:89], v[50:65]
	ds_read_b64_tr_b16 v[86:87], v167 offset:0x400
	ds_read_b64_tr_b16 v[88:89], v167 offset:0xc00
	v_mfma_f32_32x32x16_bf16 v[50:65], v[74:77], v[90:93], v[50:65]
	ds_read_b64_tr_b16 v[90:91], v167 offset:0x1400
	ds_read_b64_tr_b16 v[92:93], v167 offset:0x1c00
	v_mfma_f32_32x32x16_bf16 v[50:65], v[78:81], v[94:97], v[50:65]
	ds_read_b64_tr_b16 v[94:95], v167 offset:0x2400
	ds_read_b64_tr_b16 v[96:97], v167 offset:0x2c00
	v_mfma_f32_32x32x16_bf16 v[50:65], v[82:85], v[98:101], v[50:65]
	ds_read_b64_tr_b16 v[98:99], v167 offset:0x3400
	ds_read_b64_tr_b16 v[100:101], v167 offset:0x3c00
	s_waitcnt lgkmcnt(0)
	v_mfma_f32_32x32x16_bf16 v[34:49], v[70:73], v[86:89], v[34:49]
	ds_read_b64_tr_b16 v[86:87], v167 offset:0x600
	ds_read_b64_tr_b16 v[88:89], v167 offset:0xe00
	v_mfma_f32_32x32x16_bf16 v[34:49], v[74:77], v[90:93], v[34:49]
	ds_read_b64_tr_b16 v[90:91], v167 offset:0x1600
	ds_read_b64_tr_b16 v[92:93], v167 offset:0x1e00
	v_mfma_f32_32x32x16_bf16 v[34:49], v[78:81], v[94:97], v[34:49]
	ds_read_b64_tr_b16 v[94:95], v167 offset:0x2600
	ds_read_b64_tr_b16 v[96:97], v167 offset:0x2e00
	v_mfma_f32_32x32x16_bf16 v[34:49], v[82:85], v[98:101], v[34:49]
	ds_read_b64_tr_b16 v[98:99], v167 offset:0x3600
	ds_read_b64_tr_b16 v[100:101], v167 offset:0x3e00
	s_waitcnt lgkmcnt(0)
	v_mfma_f32_32x32x16_bf16 v[16:31], v[70:73], v[86:89], v[16:31]
	v_mfma_f32_32x32x16_bf16 v[16:31], v[74:77], v[90:93], v[16:31]
	v_mfma_f32_32x32x16_bf16 v[16:31], v[78:81], v[94:97], v[16:31]
	v_mfma_f32_32x32x16_bf16 v[16:31], v[82:85], v[98:101], v[16:31]
	s_setprio 0
	v_cmp_gt_u32_e32 vcc, 32, v165
	s_and_saveexec_b64 s[4:5], vcc
	v_pk_add_f32 v[66:67], v[66:67], v[68:69]
	v_lshl_add_u32 v32, v164, 2, s49
	v_add_f32_e32 v66, v166, v66
	v_add_f32_e32 v66, v66, v67
	ds_write_b32 v32, v66 offset:51200
	s_or_b64 exec, exec, s[4:5]
	s_waitcnt lgkmcnt(0)
	v_lshl_add_u32 v32, v163, 4, s49
	ds_read_b128 v[78:81], v32 offset:51200
	ds_read_b128 v[74:77], v32 offset:51232
	v_and_b32_e32 v82, 1, v162
	ds_read_b128 v[70:73], v32 offset:51264
	ds_read_b128 v[66:69], v32 offset:51296
	v_cmp_eq_u32_e64 s[6:7], 0, v82
	s_waitcnt lgkmcnt(3)
	v_rcp_f32_e32 v78, v78
	v_rcp_f32_e32 v79, v79
	v_cmp_eq_u32_e64 s[4:5], 1, v82
	v_mul_f32_e32 v0, v0, v78
	v_mul_f32_e32 v32, v1, v79
	v_cndmask_b32_e64 v1, v0, v32, s[6:7]
	ds_swizzle_b32 v1, v1 offset:swizzle(SWAP,1)
	s_and_saveexec_b64 s[14:15], s[4:5]
	s_xor_b64 s[14:15], exec, s[14:15]
	s_cbranch_execz .LBB0_2305
	s_waitcnt lgkmcnt(0)
	v_cvt_pk_bf16_f32 v83, v1, v32
